# pool_rows<16>/<8> fast paths: the rows the compiler reloaded one per round trip are prefetched up front into spare VGPRs (reloads become v_mov), counted waits re-derived
# baseline (speedup 1.0000x reference)
.LBB0_258:
	s_and_b64 vcc, exec, s[0:1]
	s_cbranch_vccz .LBB0_232
	s_sub_i32 s26, s21, s23
	s_lshl_b32 s34, s28, 7
	s_cmp_eq_u32 s23, 0
	s_cselect_b64 s[0:1], -1, 0
	v_or_b32_e32 v32, s34, v205
	s_and_b64 s[0:1], s[6:7], s[0:1]
	v_add_u32_e32 v36, s23, v148
	s_mov_b64 s[8:9], -1
	s_andn2_b64 vcc, exec, s[0:1]
	v_ashrrev_i32_e32 v33, 31, v32
	s_cbranch_vccz .LBB0_275
	v_lshl_add_u64 v[34:35], v[32:33], 1, s[52:53]
	s_mov_b64 s[10:11], -1
	s_mov_b64 s[0:1], 0
	s_cmp_lt_i32 s28, 1
	s_mov_b64 s[8:9], 0
	s_cbranch_scc1 .LBB0_268
	s_cmp_gt_i32 s28, 1
	s_cbranch_scc0 .LBB0_265
	s_cmp_eq_u32 s28, 2
	s_mov_b64 s[8:9], -1
	s_cbranch_scc0 .LBB0_264
	v_max_i32_e32 v112, 6, v36
	v_add3_u32 v112, s26, -6, v112
	v_mad_i64_i32 v[112:113], s[8:9], v112, s19, v[34:35]
	global_load_dwordx4 v[112:115], v[112:113], off
	v_max_i32_e32 v116, 5, v36
	v_add3_u32 v116, s26, -5, v116
	v_mad_i64_i32 v[116:117], s[8:9], v116, s19, v[34:35]
	global_load_dwordx4 v[116:119], v[116:117], off
	v_max_i32_e32 v120, 4, v36
	v_add3_u32 v120, s26, -4, v120
	v_mad_i64_i32 v[120:121], s[8:9], v120, s19, v[34:35]
	global_load_dwordx4 v[120:123], v[120:121], off
	v_max_i32_e32 v124, 3, v36
	v_add3_u32 v124, s26, -3, v124
	v_mad_i64_i32 v[124:125], s[8:9], v124, s19, v[34:35]
	global_load_dwordx4 v[124:127], v[124:125], off
	v_max_i32_e32 v128, 2, v36
	v_add3_u32 v128, s26, -2, v128
	v_mad_i64_i32 v[128:129], s[8:9], v128, s19, v[34:35]
	global_load_dwordx4 v[128:131], v[128:129], off
	v_max_i32_e32 v132, 1, v36
	v_add3_u32 v132, s26, -1, v132
	v_mad_i64_i32 v[132:133], s[8:9], v132, s19, v[34:35]
	global_load_dwordx4 v[132:135], v[132:133], off
	v_max_i32_e32 v136, 0, v36
	v_add_u32_e32 v136, s26, v136
	v_mad_i64_i32 v[136:137], s[8:9], v136, s19, v[34:35]
	global_load_dwordx4 v[136:139], v[136:137], off
	v_max_i32_e32 v0, 7, v36
	v_add3_u32 v0, s26, -7, v0
	v_mad_i64_i32 v[0:1], s[8:9], v0, s19, v[34:35]
	global_load_dwordx4 v[0:3], v[0:1], off
	v_or_b32_e32 v52, 1, v36
	v_max_i32_e32 v4, 0, v52
	v_add_u32_e32 v4, s26, v4
	v_cmp_lt_i32_e32 vcc, 6, v36
	v_mad_i64_i32 v[4:5], s[8:9], v4, s19, v[34:35]
	global_load_dwordx4 v[4:7], v[4:5], off
	v_or_b32_e32 v20, 2, v36
	v_max_i32_e32 v8, 0, v20
	v_add_u32_e32 v8, s26, v8
	v_mad_i64_i32 v[8:9], s[8:9], v8, s19, v[34:35]
	v_or_b32_e32 v53, 3, v36
	v_max_i32_e32 v12, 0, v53
	v_add_u32_e32 v12, s26, v12
	v_mad_i64_i32 v[12:13], s[8:9], v12, s19, v[34:35]
	v_min_i32_e32 v20, 7, v20
	v_add_u32_e32 v20, 1, v20
	v_cvt_f32_i32_e32 v20, v20
	global_load_dwordx4 v[8:11], v[8:9], off
	s_waitcnt vmcnt(2)
	v_cndmask_b32_e32 v17, 0, v0, vcc
	v_max_i32_e32 v0, 6, v36
	v_add3_u32 v0, s26, -6, v0
	v_cndmask_b32_e32 v16, 0, v1, vcc
	v_mad_i64_i32 v[0:1], s[8:9], v0, s19, v[34:35]
	v_cndmask_b32_e32 v14, 0, v3, vcc
	v_cndmask_b32_e32 v15, 0, v2, vcc
	v_mov_b32_e32 v0, v112
	v_mov_b32_e32 v1, v113
	v_mov_b32_e32 v2, v114
	v_mov_b32_e32 v3, v115
	v_cmp_lt_i32_e32 vcc, 5, v36
	v_lshlrev_b32_e32 v54, 16, v17
	v_and_b32_e32 v17, 0xffff0000, v17
	v_lshlrev_b32_e32 v55, 16, v16
	v_and_b32_e32 v16, 0xffff0000, v16
	v_add_f32_e32 v56, 0, v55
	v_add_f32_e32 v57, 0, v16
	v_and_b32_e32 v60, 0xffff0000, v15
	v_lshlrev_b32_e32 v61, 16, v14
	v_lshlrev_b32_e32 v58, 16, v15
	v_add_f32_e32 v15, 0, v60
	v_add_f32_e32 v62, 0, v61
	v_and_b32_e32 v63, 0xffff0000, v14
	v_add_f32_e32 v14, 0, v63
	v_add_f32_e32 v59, 0, v58
	global_load_dwordx4 v[24:27], v[12:13], off
	v_add_f32_e32 v12, 0, v54
	v_add_f32_e32 v13, 0, v17
	s_waitcnt vmcnt(1)
	v_cndmask_b32_e32 v22, 0, v0, vcc
	v_max_i32_e32 v0, 5, v36
	v_add3_u32 v0, s26, -5, v0
	v_cndmask_b32_e32 v21, 0, v1, vcc
	v_mad_i64_i32 v[0:1], s[8:9], v0, s19, v[34:35]
	v_cndmask_b32_e32 v18, 0, v3, vcc
	v_cndmask_b32_e32 v19, 0, v2, vcc
	v_mov_b32_e32 v0, v116
	v_mov_b32_e32 v1, v117
	v_mov_b32_e32 v2, v118
	v_mov_b32_e32 v3, v119
	v_cmp_lt_i32_e32 vcc, 4, v36
	v_lshlrev_b32_e32 v64, 16, v22
	v_add_f32_e32 v12, v12, v64
	v_and_b32_e32 v22, 0xffff0000, v22
	v_add_f32_e32 v13, v13, v22
	v_lshlrev_b32_e32 v65, 16, v21
	v_and_b32_e32 v21, 0xffff0000, v21
	v_add_f32_e32 v56, v56, v65
	v_add_f32_e32 v57, v57, v21
	v_and_b32_e32 v67, 0xffff0000, v19
	v_lshlrev_b32_e32 v68, 16, v18
	v_lshlrev_b32_e32 v66, 16, v19
	v_add_f32_e32 v15, v15, v67
	v_add_f32_e32 v19, v62, v68
	v_and_b32_e32 v62, 0xffff0000, v18
	v_add_f32_e32 v14, v14, v62
	v_add_f32_e32 v59, v59, v66
	s_waitcnt vmcnt(0)
	v_cndmask_b32_e32 v30, 0, v0, vcc
	v_max_i32_e32 v0, 4, v36
	v_add3_u32 v0, s26, -4, v0
	v_cndmask_b32_e32 v29, 0, v1, vcc
	v_mad_i64_i32 v[0:1], s[8:9], v0, s19, v[34:35]
	v_cndmask_b32_e32 v23, 0, v3, vcc
	v_cndmask_b32_e32 v28, 0, v2, vcc
	v_mov_b32_e32 v0, v120
	v_mov_b32_e32 v1, v121
	v_mov_b32_e32 v2, v122
	v_mov_b32_e32 v3, v123
	v_cmp_lt_i32_e32 vcc, 3, v36
	v_lshlrev_b32_e32 v69, 16, v30
	v_add_f32_e32 v12, v12, v69
	v_and_b32_e32 v30, 0xffff0000, v30
	v_lshlrev_b32_e32 v71, 16, v23
	v_and_b32_e32 v72, 0xffff0000, v23
	v_add_f32_e32 v13, v13, v30
	v_lshlrev_b32_e32 v70, 16, v29
	v_and_b32_e32 v29, 0xffff0000, v29
	v_add_f32_e32 v18, v56, v70
	v_add_f32_e32 v56, v57, v29
	v_lshlrev_b32_e32 v57, 16, v28
	v_and_b32_e32 v28, 0xffff0000, v28
	v_add_f32_e32 v15, v15, v28
	v_add_f32_e32 v19, v19, v71
	v_add_f32_e32 v14, v14, v72
	v_add_f32_e32 v59, v59, v57
	s_waitcnt vmcnt(0)
	v_cndmask_b32_e32 v39, 0, v0, vcc
	v_max_i32_e32 v0, 3, v36
	v_add3_u32 v0, s26, -3, v0
	v_cndmask_b32_e32 v38, 0, v1, vcc
	v_mad_i64_i32 v[0:1], s[8:9], v0, s19, v[34:35]
	v_cndmask_b32_e32 v31, 0, v3, vcc
	v_cndmask_b32_e32 v37, 0, v2, vcc
	v_mov_b32_e32 v0, v124
	v_mov_b32_e32 v1, v125
	v_mov_b32_e32 v2, v126
	v_mov_b32_e32 v3, v127
	v_cmp_lt_i32_e32 vcc, 2, v36
	v_lshlrev_b32_e32 v23, 16, v39
	v_add_f32_e32 v12, v12, v23
	v_and_b32_e32 v23, 0xffff0000, v39
	v_add_f32_e32 v13, v13, v23
	v_lshlrev_b32_e32 v23, 16, v38
	v_add_f32_e32 v18, v18, v23
	v_and_b32_e32 v23, 0xffff0000, v38
	v_lshlrev_b32_e32 v38, 16, v37
	v_and_b32_e32 v37, 0xffff0000, v37
	v_add_f32_e32 v15, v15, v37
	v_lshlrev_b32_e32 v37, 16, v31
	v_add_f32_e32 v19, v19, v37
	v_and_b32_e32 v31, 0xffff0000, v31
	v_add_f32_e32 v14, v14, v31
	v_add_f32_e32 v23, v56, v23
	v_add_f32_e32 v38, v59, v38
	s_waitcnt vmcnt(0)
	v_cndmask_b32_e32 v43, 0, v0, vcc
	v_max_i32_e32 v0, 2, v36
	v_add3_u32 v0, s26, -2, v0
	v_cndmask_b32_e32 v42, 0, v1, vcc
	v_mad_i64_i32 v[0:1], s[8:9], v0, s19, v[34:35]
	v_cndmask_b32_e32 v40, 0, v3, vcc
	v_cndmask_b32_e32 v41, 0, v2, vcc
	v_mov_b32_e32 v0, v128
	v_mov_b32_e32 v1, v129
	v_mov_b32_e32 v2, v130
	v_mov_b32_e32 v3, v131
	v_cmp_lt_i32_e32 vcc, 1, v36
	v_and_b32_e32 v37, 0xffff0000, v41
	v_add_f32_e32 v15, v15, v37
	v_lshlrev_b32_e32 v37, 16, v40
	v_lshlrev_b32_e32 v31, 16, v43
	v_add_f32_e32 v19, v19, v37
	v_and_b32_e32 v37, 0xffff0000, v40
	v_add_f32_e32 v12, v12, v31
	v_and_b32_e32 v31, 0xffff0000, v43
	v_add_f32_e32 v14, v14, v37
	v_add_f32_e32 v13, v13, v31
	v_lshlrev_b32_e32 v31, 16, v42
	v_add_f32_e32 v18, v18, v31
	v_and_b32_e32 v31, 0xffff0000, v42
	v_add_f32_e32 v23, v23, v31
	v_lshlrev_b32_e32 v31, 16, v41
	v_add_f32_e32 v31, v38, v31
	s_waitcnt vmcnt(0)
	v_cndmask_b32_e32 v47, 0, v0, vcc
	v_max_i32_e32 v0, 1, v36
	v_add3_u32 v0, s26, -1, v0
	v_cndmask_b32_e32 v46, 0, v1, vcc
	v_mad_i64_i32 v[0:1], s[8:9], v0, s19, v[34:35]
	v_cndmask_b32_e32 v44, 0, v3, vcc
	v_cndmask_b32_e32 v45, 0, v2, vcc
	v_mov_b32_e32 v0, v132
	v_mov_b32_e32 v1, v133
	v_mov_b32_e32 v2, v134
	v_mov_b32_e32 v3, v135
	v_cmp_lt_i32_e32 vcc, 0, v36
	v_lshlrev_b32_e32 v37, 16, v47
	v_add_f32_e32 v12, v12, v37
	v_and_b32_e32 v37, 0xffff0000, v47
	v_add_f32_e32 v13, v13, v37
	v_lshlrev_b32_e32 v37, 16, v46
	v_add_f32_e32 v18, v18, v37
	v_and_b32_e32 v37, 0xffff0000, v46
	v_add_f32_e32 v23, v23, v37
	v_lshlrev_b32_e32 v37, 16, v45
	v_add_f32_e32 v31, v31, v37
	v_and_b32_e32 v37, 0xffff0000, v45
	v_add_f32_e32 v15, v15, v37
	v_lshlrev_b32_e32 v37, 16, v44
	v_add_f32_e32 v19, v19, v37
	v_and_b32_e32 v37, 0xffff0000, v44
	v_add_f32_e32 v14, v14, v37
	s_waitcnt vmcnt(0)
	v_cndmask_b32_e32 v51, 0, v0, vcc
	v_max_i32_e32 v0, 0, v36
	v_add_u32_e32 v0, s26, v0
	v_cndmask_b32_e32 v50, 0, v1, vcc
	v_mad_i64_i32 v[0:1], s[8:9], v0, s19, v[34:35]
	v_cndmask_b32_e32 v48, 0, v3, vcc
	v_cndmask_b32_e32 v49, 0, v2, vcc
	v_mov_b32_e32 v0, v136
	v_mov_b32_e32 v1, v137
	v_mov_b32_e32 v2, v138
	v_mov_b32_e32 v3, v139
	v_lshlrev_b32_e32 v37, 16, v51
	v_add_f32_e32 v12, v12, v37
	v_and_b32_e32 v37, 0xffff0000, v51
	v_add_f32_e32 v13, v13, v37
	v_lshlrev_b32_e32 v37, 16, v50
	v_add_f32_e32 v18, v18, v37
	v_and_b32_e32 v37, 0xffff0000, v50
	v_add_f32_e32 v23, v23, v37
	v_lshlrev_b32_e32 v37, 16, v49
	v_add_f32_e32 v31, v31, v37
	v_and_b32_e32 v37, 0xffff0000, v49
	v_cmp_lt_i32_e32 vcc, -1, v36
	v_add_f32_e32 v15, v15, v37
	v_lshlrev_b32_e32 v37, 16, v48
	v_add_f32_e32 v19, v19, v37
	v_and_b32_e32 v37, 0xffff0000, v48
	v_add_f32_e32 v14, v14, v37
	s_waitcnt vmcnt(0)
	v_cndmask_b32_e32 v3, 0, v3, vcc
	v_and_b32_e32 v44, 0xffff0000, v3
	v_add_f32_e32 v45, v14, v44
	v_min_i32_e32 v14, 7, v36
	v_add_u32_e32 v14, 1, v14
	v_cvt_f32_i32_e32 v14, v14
	v_cndmask_b32_e32 v2, 0, v2, vcc
	v_cndmask_b32_e32 v1, 0, v1, vcc
	v_cndmask_b32_e32 v0, 0, v0, vcc
	v_div_scale_f32 v46, s[8:9], v14, v14, 1.0
	v_rcp_f32_e32 v47, v46
	v_cmp_lt_i32_e32 vcc, -2, v36
	v_lshlrev_b32_e32 v37, 16, v0
	v_add_f32_e32 v38, v12, v37
	v_cndmask_b32_e32 v7, 0, v7, vcc
	v_cndmask_b32_e32 v6, 0, v6, vcc
	v_cndmask_b32_e32 v5, 0, v5, vcc
	v_cndmask_b32_e32 v4, 0, v4, vcc
	v_cmp_lt_i32_e32 vcc, -3, v36
	v_fma_f32 v48, -v46, v47, 1.0
	v_fmac_f32_e32 v47, v48, v47
	v_cndmask_b32_e32 v11, 0, v11, vcc
	v_cndmask_b32_e32 v10, 0, v10, vcc
	v_cndmask_b32_e32 v9, 0, v9, vcc
	v_cndmask_b32_e32 v8, 0, v8, vcc
	v_div_scale_f32 v48, vcc, 1.0, v14, 1.0
	v_mul_f32_e32 v49, v48, v47
	v_fma_f32 v50, -v46, v49, v48
	v_fmac_f32_e32 v49, v50, v47
	v_fma_f32 v46, -v46, v49, v48
	v_div_fmas_f32 v46, v46, v47, v49
	v_and_b32_e32 v12, 0xffff0000, v0
	v_div_fixup_f32 v14, v46, v14, 1.0
	v_add_f32_e32 v39, v13, v12
	v_and_b32_e32 v40, 0xffff0000, v1
	v_cndmask_b32_e64 v46, v14, v209, s[6:7]
	v_add_f32_e32 v23, v23, v40
	v_fma_f32 v14, v46, v38, -v37
	v_fma_f32 v12, v46, v39, -v12
	v_cvt_pk_bf16_f32 v12, v14, v12
	v_fma_f32 v14, v46, v23, -v40
	v_and_b32_e32 v40, 0xffff0000, v4
	v_lshlrev_b32_e32 v13, 16, v1
	v_add_f32_e32 v39, v39, v40
	v_add_f32_e32 v18, v18, v13
	v_lshlrev_b32_e32 v41, 16, v2
	v_sub_f32_e32 v39, v39, v17
	v_lshlrev_b32_e32 v17, 16, v5
	v_add_f32_e32 v31, v31, v41
	v_and_b32_e32 v42, 0xffff0000, v2
	v_fma_f32 v13, v46, v18, -v13
	v_add_f32_e32 v18, v18, v17
	v_add_f32_e32 v43, v15, v42
	v_cvt_pk_bf16_f32 v13, v13, v14
	v_fma_f32 v14, v46, v31, -v41
	v_sub_f32_e32 v41, v18, v55
	v_and_b32_e32 v18, 0xffff0000, v5
	v_lshlrev_b32_e32 v15, 16, v3
	v_fma_f32 v37, v46, v43, -v42
	v_add_f32_e32 v23, v23, v18
	v_lshlrev_b32_e32 v42, 16, v6
	v_add_f32_e32 v19, v19, v15
	v_cvt_pk_bf16_f32 v14, v14, v37
	v_fma_f32 v37, v46, v45, -v44
	v_sub_f32_e32 v23, v23, v16
	v_add_f32_e32 v16, v31, v42
	v_and_b32_e32 v44, 0xffff0000, v6
	v_fma_f32 v15, v46, v19, -v15
	v_sub_f32_e32 v31, v16, v58
	v_add_f32_e32 v16, v43, v44
	v_lshlrev_b32_e32 v46, 16, v7
	v_sub_f32_e32 v43, v16, v60
	v_add_f32_e32 v16, v19, v46
	v_and_b32_e32 v19, 0xffff0000, v7
	v_sub_f32_e32 v47, v16, v61
	v_add_f32_e32 v16, v45, v19
	v_sub_f32_e32 v45, v16, v63
	v_min_i32_e32 v16, 7, v52
	v_add_u32_e32 v16, 1, v16
	v_cvt_f32_i32_e32 v16, v16
	v_cvt_pk_bf16_f32 v15, v15, v37
	v_lshlrev_b32_e32 v37, 16, v4
	v_add_f32_e32 v38, v38, v37
	v_div_scale_f32 v48, s[8:9], v16, v16, 1.0
	v_rcp_f32_e32 v49, v48
	v_sub_f32_e32 v38, v38, v54
	v_fma_f32 v50, -v48, v49, 1.0
	v_fmac_f32_e32 v49, v50, v49
	v_div_scale_f32 v50, vcc, 1.0, v16, 1.0
	v_mul_f32_e32 v51, v50, v49
	v_fma_f32 v52, -v48, v51, v50
	v_fmac_f32_e32 v51, v52, v49
	v_fma_f32 v48, -v48, v51, v50
	v_div_fmas_f32 v48, v48, v49, v51
	v_div_fixup_f32 v16, v48, v16, 1.0
	v_cndmask_b32_e64 v48, v16, v209, s[6:7]
	v_fma_f32 v17, v48, v41, -v17
	v_fma_f32 v18, v48, v23, -v18
	v_cvt_pk_bf16_f32 v17, v17, v18
	v_fma_f32 v18, v48, v31, -v42
	v_and_b32_e32 v42, 0xffff0000, v9
	v_fma_f32 v16, v48, v38, -v37
	v_fma_f32 v37, v48, v39, -v40
	v_add_f32_e32 v23, v23, v42
	v_cvt_pk_bf16_f32 v16, v16, v37
	v_fma_f32 v37, v48, v43, -v44
	v_sub_f32_e32 v44, v23, v21
	v_lshlrev_b32_e32 v23, 16, v10
	v_cvt_pk_bf16_f32 v18, v18, v37
	v_fma_f32 v37, v48, v47, -v46
	v_add_f32_e32 v21, v31, v23
	v_and_b32_e32 v46, 0xffff0000, v10
	v_fma_f32 v19, v48, v45, -v19
	v_sub_f32_e32 v31, v21, v66
	v_add_f32_e32 v21, v43, v46
	v_lshlrev_b32_e32 v48, 16, v11
	v_sub_f32_e32 v43, v21, v67
	v_add_f32_e32 v21, v47, v48
	v_and_b32_e32 v49, 0xffff0000, v11
	v_sub_f32_e32 v47, v21, v68
	v_add_f32_e32 v21, v45, v49
	v_sub_f32_e32 v45, v21, v62
	v_div_scale_f32 v21, s[8:9], v20, v20, 1.0
	v_rcp_f32_e32 v50, v21
	v_and_b32_e32 v40, 0xffff0000, v8
	v_cvt_pk_bf16_f32 v19, v37, v19
	v_lshlrev_b32_e32 v37, 16, v8
	v_fma_f32 v51, -v21, v50, 1.0
	v_fmac_f32_e32 v50, v51, v50
	v_div_scale_f32 v51, vcc, 1.0, v20, 1.0
	v_mul_f32_e32 v52, v51, v50
	v_fma_f32 v54, -v21, v52, v51
	v_fmac_f32_e32 v52, v54, v50
	v_fma_f32 v21, -v21, v52, v51
	v_add_f32_e32 v39, v39, v40
	v_div_fmas_f32 v21, v21, v50, v52
	v_add_f32_e32 v38, v38, v37
	v_sub_f32_e32 v39, v39, v22
	v_lshlrev_b32_e32 v22, 16, v9
	v_div_fixup_f32 v20, v21, v20, 1.0
	v_sub_f32_e32 v38, v38, v64
	v_add_f32_e32 v41, v41, v22
	v_cndmask_b32_e64 v50, v20, v209, s[6:7]
	v_sub_f32_e32 v41, v41, v65
	v_fma_f32 v20, v50, v38, -v37
	v_fma_f32 v21, v50, v39, -v40
	v_cmp_lt_i32_e32 vcc, -4, v36
	v_cvt_pk_bf16_f32 v20, v20, v21
	v_fma_f32 v21, v50, v41, -v22
	v_fma_f32 v22, v50, v44, -v42
	v_cndmask_b32_e32 v26, 0, v26, vcc
	v_cvt_pk_bf16_f32 v21, v21, v22
	v_fma_f32 v22, v50, v31, -v23
	v_fma_f32 v23, v50, v43, -v46
	v_cndmask_b32_e32 v27, 0, v27, vcc
	v_and_b32_e32 v46, 0xffff0000, v26
	v_cvt_pk_bf16_f32 v22, v22, v23
	v_fma_f32 v23, v50, v47, -v48
	v_add_f32_e32 v43, v43, v46
	v_lshlrev_b32_e32 v48, 16, v27
	v_fma_f32 v37, v50, v45, -v49
	v_sub_f32_e32 v43, v43, v28
	v_add_f32_e32 v28, v47, v48
	v_and_b32_e32 v49, 0xffff0000, v27
	v_sub_f32_e32 v47, v28, v71
	v_add_f32_e32 v28, v45, v49
	v_sub_f32_e32 v45, v28, v72
	v_min_i32_e32 v28, 7, v53
	v_add_u32_e32 v28, 1, v28
	v_cvt_f32_i32_e32 v28, v28
	v_cndmask_b32_e32 v25, 0, v25, vcc
	v_cndmask_b32_e32 v24, 0, v24, vcc
	v_and_b32_e32 v40, 0xffff0000, v24
	v_div_scale_f32 v50, s[8:9], v28, v28, 1.0
	v_rcp_f32_e32 v51, v50
	v_cvt_pk_bf16_f32 v23, v23, v37
	v_lshlrev_b32_e32 v37, 16, v24
	v_add_f32_e32 v39, v39, v40
	v_fma_f32 v52, -v50, v51, 1.0
	v_fmac_f32_e32 v51, v52, v51
	v_div_scale_f32 v52, vcc, 1.0, v28, 1.0
	v_mul_f32_e32 v53, v52, v51
	v_fma_f32 v54, -v50, v53, v52
	v_fmac_f32_e32 v53, v54, v51
	v_fma_f32 v50, -v50, v53, v52
	v_and_b32_e32 v42, 0xffff0000, v25
	v_div_fmas_f32 v50, v50, v51, v53
	v_add_f32_e32 v38, v38, v37
	v_sub_f32_e32 v30, v39, v30
	v_lshlrev_b32_e32 v39, 16, v25
	v_add_f32_e32 v44, v44, v42
	v_div_fixup_f32 v28, v50, v28, 1.0
	v_sub_f32_e32 v38, v38, v69
	v_add_f32_e32 v41, v41, v39
	v_sub_f32_e32 v29, v44, v29
	v_lshlrev_b32_e32 v44, 16, v26
	v_cndmask_b32_e64 v50, v28, v209, s[6:7]
	v_sub_f32_e32 v41, v41, v70
	v_add_f32_e32 v31, v31, v44
	v_fma_f32 v28, v50, v38, -v37
	v_fma_f32 v30, v50, v30, -v40
	v_sub_f32_e32 v31, v31, v57
	v_cvt_pk_bf16_f32 v28, v28, v30
	v_fma_f32 v30, v50, v41, -v39
	v_fma_f32 v29, v50, v29, -v42
	v_cvt_pk_bf16_f32 v29, v30, v29
	v_fma_f32 v30, v50, v31, -v44
	v_fma_f32 v31, v50, v43, -v46
	v_cvt_pk_bf16_f32 v30, v30, v31
	v_fma_f32 v31, v50, v47, -v48
	v_fma_f32 v37, v50, v45, -v49
	v_cvt_pk_bf16_f32 v31, v31, v37
	s_mov_b64 s[8:9], 0

.LBB0_270:
	v_max_i32_e32 v40, 1, v36
	v_max_i32_e32 v41, 0, v36
	v_or_b32_e32 v39, 1, v36
	v_or_b32_e32 v38, 2, v36
	v_or_b32_e32 v37, 3, v36
	s_andn2_b64 vcc, exec, s[8:9]
	v_cmp_lt_i32_e64 s[14:15], 0, v36
	v_cmp_lt_i32_e64 s[12:13], -1, v36
	v_cmp_lt_i32_e64 s[10:11], -2, v36
	v_cmp_lt_i32_e64 s[8:9], -3, v36
	v_add3_u32 v44, s26, -1, v40
	v_add_u32_e32 v43, s26, v41
	v_max_i32_e32 v42, 0, v39
	v_max_i32_e32 v41, 0, v38
	v_max_i32_e32 v40, 0, v37
	s_cbranch_vccnz .LBB0_272
	v_max_i32_e32 v112, 14, v36
	v_add3_u32 v112, s26, -14, v112
	v_mad_i64_i32 v[112:113], s[0:1], v112, s19, v[34:35]
	global_load_dwordx4 v[112:115], v[112:113], off
	v_max_i32_e32 v116, 13, v36
	v_add3_u32 v116, s26, -13, v116
	v_mad_i64_i32 v[116:117], s[0:1], v116, s19, v[34:35]
	global_load_dwordx4 v[116:119], v[116:117], off
	v_max_i32_e32 v120, 12, v36
	v_add3_u32 v120, s26, -12, v120
	v_mad_i64_i32 v[120:121], s[0:1], v120, s19, v[34:35]
	global_load_dwordx4 v[120:123], v[120:121], off
	v_max_i32_e32 v124, 11, v36
	v_add3_u32 v124, s26, -11, v124
	v_mad_i64_i32 v[124:125], s[0:1], v124, s19, v[34:35]
	global_load_dwordx4 v[124:127], v[124:125], off
	v_max_i32_e32 v128, 10, v36
	v_add3_u32 v128, s26, -10, v128
	v_mad_i64_i32 v[128:129], s[0:1], v128, s19, v[34:35]
	global_load_dwordx4 v[128:131], v[128:129], off
	v_max_i32_e32 v132, 9, v36
	v_add3_u32 v132, s26, -9, v132
	v_mad_i64_i32 v[132:133], s[0:1], v132, s19, v[34:35]
	global_load_dwordx4 v[132:135], v[132:133], off
	v_max_i32_e32 v136, 8, v36
	v_add3_u32 v136, s26, -8, v136
	v_mad_i64_i32 v[136:137], s[0:1], v136, s19, v[34:35]
	global_load_dwordx4 v[136:139], v[136:137], off
	v_max_i32_e32 v176, 7, v36
	v_add3_u32 v176, s26, -7, v176
	v_mad_i64_i32 v[176:177], s[0:1], v176, s19, v[34:35]
	global_load_dwordx4 v[176:179], v[176:177], off
	v_max_i32_e32 v180, 6, v36
	v_add3_u32 v180, s26, -6, v180
	v_mad_i64_i32 v[180:181], s[0:1], v180, s19, v[34:35]
	global_load_dwordx4 v[180:183], v[180:181], off
	v_max_i32_e32 v184, 5, v36
	v_add3_u32 v184, s26, -5, v184
	v_mad_i64_i32 v[184:185], s[0:1], v184, s19, v[34:35]
	global_load_dwordx4 v[184:187], v[184:185], off
	v_max_i32_e32 v188, 4, v36
	v_add3_u32 v188, s26, -4, v188
	v_mad_i64_i32 v[188:189], s[0:1], v188, s19, v[34:35]
	global_load_dwordx4 v[188:191], v[188:189], off
	v_max_i32_e32 v192, 3, v36
	v_add3_u32 v192, s26, -3, v192
	v_mad_i64_i32 v[192:193], s[0:1], v192, s19, v[34:35]
	global_load_dwordx4 v[192:195], v[192:193], off
	v_max_i32_e32 v196, 2, v36
	v_add3_u32 v196, s26, -2, v196
	v_mad_i64_i32 v[196:197], s[0:1], v196, s19, v[34:35]
	global_load_dwordx4 v[196:199], v[196:197], off
	v_mad_i64_i32 v[200:201], s[0:1], v44, s19, v[34:35]
	global_load_dwordx4 v[200:203], v[200:201], off
	v_mad_i64_i32 v[218:219], s[0:1], v43, s19, v[34:35]
	global_load_dwordx4 v[218:221], v[218:219], off
	v_max_i32_e32 v0, 15, v36
	v_add3_u32 v0, s26, -15, v0
	v_mad_i64_i32 v[0:1], s[0:1], v0, s19, v[34:35]
	global_load_dwordx4 v[0:3], v[0:1], off
	v_add_u32_e32 v4, s26, v42
	v_cmp_lt_i32_e32 vcc, 14, v36
	v_mad_i64_i32 v[4:5], s[0:1], v4, s19, v[34:35]
	global_load_dwordx4 v[4:7], v[4:5], off
	v_add_u32_e32 v8, s26, v41
	v_mad_i64_i32 v[8:9], s[0:1], v8, s19, v[34:35]
	v_add_u32_e32 v24, s26, v40
	v_mad_i64_i32 v[24:25], s[0:1], v24, s19, v[34:35]
	global_load_dwordx4 v[8:11], v[8:9], off
	s_waitcnt vmcnt(2)
	v_cndmask_b32_e32 v16, 0, v0, vcc
	v_max_i32_e32 v0, 14, v36
	v_add3_u32 v0, s26, -14, v0
	v_cndmask_b32_e32 v14, 0, v1, vcc
	v_mad_i64_i32 v[0:1], s[0:1], v0, s19, v[34:35]
	v_cndmask_b32_e32 v12, 0, v3, vcc
	v_cndmask_b32_e32 v13, 0, v2, vcc
	v_mov_b32_e32 v0, v112
	v_mov_b32_e32 v1, v113
	v_mov_b32_e32 v2, v114
	v_mov_b32_e32 v3, v115
	v_cmp_lt_i32_e32 vcc, 13, v36
	v_and_b32_e32 v94, 0xffff0000, v14
	v_lshlrev_b32_e32 v92, 16, v16
	v_and_b32_e32 v16, 0xffff0000, v16
	v_lshlrev_b32_e32 v93, 16, v14
	v_add_f32_e32 v14, 0, v94
	v_lshlrev_b32_e32 v95, 16, v13
	v_add_f32_e32 v90, 0, v16
	v_add_f32_e32 v91, 0, v93
	v_add_f32_e32 v96, 0, v95
	v_and_b32_e32 v97, 0xffff0000, v13
	v_add_f32_e32 v13, 0, v97
	v_lshlrev_b32_e32 v98, 16, v12
	v_add_f32_e32 v89, 0, v92
	v_add_f32_e32 v99, 0, v98
	v_and_b32_e32 v100, 0xffff0000, v12
	v_add_f32_e32 v12, 0, v100
	s_waitcnt vmcnt(1)
	v_cndmask_b32_e64 v4, 0, v4, s[10:11]
	v_cndmask_b32_e64 v5, 0, v5, s[10:11]
	v_cndmask_b32_e64 v6, 0, v6, s[10:11]
	v_cndmask_b32_e64 v7, 0, v7, s[10:11]
	s_waitcnt vmcnt(0)
	v_cndmask_b32_e64 v8, 0, v8, s[8:9]
	v_cndmask_b32_e64 v9, 0, v9, s[8:9]
	v_cndmask_b32_e64 v10, 0, v10, s[8:9]
	v_cndmask_b32_e64 v11, 0, v11, s[8:9]
	global_load_dwordx4 v[24:27], v[24:25], off
	s_waitcnt vmcnt(1)
	v_cndmask_b32_e32 v19, 0, v0, vcc
	v_max_i32_e32 v0, 13, v36
	v_add3_u32 v0, s26, -13, v0
	v_cndmask_b32_e32 v18, 0, v1, vcc
	v_mad_i64_i32 v[0:1], s[0:1], v0, s19, v[34:35]
	v_cndmask_b32_e32 v15, 0, v3, vcc
	v_cndmask_b32_e32 v17, 0, v2, vcc
	v_mov_b32_e32 v0, v116
	v_mov_b32_e32 v1, v117
	v_mov_b32_e32 v2, v118
	v_mov_b32_e32 v3, v119
	v_cmp_lt_i32_e32 vcc, 12, v36
	v_and_b32_e32 v104, 0xffff0000, v18
	v_and_b32_e32 v102, 0xffff0000, v19
	v_lshlrev_b32_e32 v103, 16, v18
	v_add_f32_e32 v14, v14, v104
	v_lshlrev_b32_e32 v105, 16, v17
	v_lshlrev_b32_e32 v101, 16, v19
	v_add_f32_e32 v19, v90, v102
	v_add_f32_e32 v90, v91, v103
	v_add_f32_e32 v18, v96, v105
	v_and_b32_e32 v96, 0xffff0000, v17
	v_add_f32_e32 v13, v13, v96
	v_lshlrev_b32_e32 v106, 16, v15
	v_add_f32_e32 v89, v89, v101
	v_add_f32_e32 v17, v99, v106
	v_and_b32_e32 v99, 0xffff0000, v15
	v_add_f32_e32 v12, v12, v99
	s_waitcnt vmcnt(0)
	v_cndmask_b32_e32 v23, 0, v0, vcc
	v_max_i32_e32 v0, 12, v36
	v_add3_u32 v0, s26, -12, v0
	v_cndmask_b32_e32 v22, 0, v1, vcc
	v_mad_i64_i32 v[0:1], s[0:1], v0, s19, v[34:35]
	v_cndmask_b32_e32 v20, 0, v3, vcc
	v_cndmask_b32_e32 v21, 0, v2, vcc
	v_mov_b32_e32 v0, v120
	v_mov_b32_e32 v1, v121
	v_mov_b32_e32 v2, v122
	v_mov_b32_e32 v3, v123
	v_cmp_lt_i32_e32 vcc, 11, v36
	v_and_b32_e32 v110, 0xffff0000, v22
	v_add_f32_e32 v14, v14, v110
	v_lshlrev_b32_e32 v111, 16, v21
	v_and_b32_e32 v91, 0xffff0000, v21
	v_lshlrev_b32_e32 v109, 16, v22
	v_add_f32_e32 v18, v18, v111
	v_lshlrev_b32_e32 v107, 16, v23
	v_and_b32_e32 v108, 0xffff0000, v23
	v_add_f32_e32 v23, v90, v109
	v_add_f32_e32 v13, v13, v91
	v_lshlrev_b32_e32 v90, 16, v20
	v_add_f32_e32 v15, v89, v107
	v_add_f32_e32 v17, v17, v90
	v_and_b32_e32 v89, 0xffff0000, v20
	v_add_f32_e32 v12, v12, v89
	v_add_f32_e32 v19, v19, v108
	s_waitcnt vmcnt(0)
	v_cndmask_b32_e32 v31, 0, v0, vcc
	v_max_i32_e32 v0, 11, v36
	v_add3_u32 v0, s26, -11, v0
	v_cndmask_b32_e32 v30, 0, v1, vcc
	v_mad_i64_i32 v[0:1], s[0:1], v0, s19, v[34:35]
	v_cndmask_b32_e32 v28, 0, v3, vcc
	v_cndmask_b32_e32 v29, 0, v2, vcc
	v_mov_b32_e32 v0, v124
	v_mov_b32_e32 v1, v125
	v_mov_b32_e32 v2, v126
	v_mov_b32_e32 v3, v127
	v_cmp_lt_i32_e32 vcc, 10, v36
	v_and_b32_e32 v21, 0xffff0000, v30
	v_add_f32_e32 v14, v14, v21
	v_lshlrev_b32_e32 v21, 16, v29
	v_add_f32_e32 v18, v18, v21
	v_and_b32_e32 v21, 0xffff0000, v29
	v_add_f32_e32 v13, v13, v21
	v_lshlrev_b32_e32 v21, 16, v28
	v_lshlrev_b32_e32 v20, 16, v31
	v_add_f32_e32 v17, v17, v21
	v_and_b32_e32 v21, 0xffff0000, v28
	v_add_f32_e32 v15, v15, v20
	v_and_b32_e32 v20, 0xffff0000, v31
	v_add_f32_e32 v12, v12, v21
	v_add_f32_e32 v19, v19, v20
	v_lshlrev_b32_e32 v20, 16, v30
	v_add_f32_e32 v20, v23, v20
	s_waitcnt vmcnt(0)
	v_cndmask_b32_e32 v48, 0, v0, vcc
	v_max_i32_e32 v0, 10, v36
	v_add3_u32 v0, s26, -10, v0
	v_cndmask_b32_e32 v47, 0, v1, vcc
	v_mad_i64_i32 v[0:1], s[0:1], v0, s19, v[34:35]
	v_cndmask_b32_e32 v45, 0, v3, vcc
	v_cndmask_b32_e32 v46, 0, v2, vcc
	v_mov_b32_e32 v0, v128
	v_mov_b32_e32 v1, v129
	v_mov_b32_e32 v2, v130
	v_mov_b32_e32 v3, v131
	v_cmp_lt_i32_e32 vcc, 9, v36
	v_lshlrev_b32_e32 v21, 16, v48
	v_add_f32_e32 v15, v15, v21
	v_and_b32_e32 v21, 0xffff0000, v48
	v_add_f32_e32 v19, v19, v21
	v_lshlrev_b32_e32 v21, 16, v47
	v_add_f32_e32 v20, v20, v21
	v_and_b32_e32 v21, 0xffff0000, v47
	v_add_f32_e32 v14, v14, v21
	v_lshlrev_b32_e32 v21, 16, v46
	v_add_f32_e32 v18, v18, v21
	v_and_b32_e32 v21, 0xffff0000, v46
	v_add_f32_e32 v13, v13, v21
	v_lshlrev_b32_e32 v21, 16, v45
	v_add_f32_e32 v17, v17, v21
	v_and_b32_e32 v21, 0xffff0000, v45
	v_add_f32_e32 v12, v12, v21
	s_waitcnt vmcnt(0)
	v_cndmask_b32_e32 v52, 0, v0, vcc
	v_max_i32_e32 v0, 9, v36
	v_add3_u32 v0, s26, -9, v0
	v_cndmask_b32_e32 v51, 0, v1, vcc
	v_mad_i64_i32 v[0:1], s[0:1], v0, s19, v[34:35]
	v_cndmask_b32_e32 v49, 0, v3, vcc
	v_cndmask_b32_e32 v50, 0, v2, vcc
	v_mov_b32_e32 v0, v132
	v_mov_b32_e32 v1, v133
	v_mov_b32_e32 v2, v134
	v_mov_b32_e32 v3, v135
	v_cmp_lt_i32_e32 vcc, 8, v36
	v_lshlrev_b32_e32 v21, 16, v52
	v_add_f32_e32 v15, v15, v21
	v_and_b32_e32 v21, 0xffff0000, v52
	v_add_f32_e32 v19, v19, v21
	v_lshlrev_b32_e32 v21, 16, v51
	v_add_f32_e32 v20, v20, v21
	v_and_b32_e32 v21, 0xffff0000, v51
	v_add_f32_e32 v14, v14, v21
	v_lshlrev_b32_e32 v21, 16, v50
	v_add_f32_e32 v18, v18, v21
	v_and_b32_e32 v21, 0xffff0000, v50
	v_add_f32_e32 v13, v13, v21
	v_lshlrev_b32_e32 v21, 16, v49
	v_add_f32_e32 v17, v17, v21
	v_and_b32_e32 v21, 0xffff0000, v49
	v_add_f32_e32 v12, v12, v21
	s_waitcnt vmcnt(0)
	v_cndmask_b32_e32 v56, 0, v0, vcc
	v_max_i32_e32 v0, 8, v36
	v_add3_u32 v0, s26, -8, v0
	v_cndmask_b32_e32 v55, 0, v1, vcc
	v_mad_i64_i32 v[0:1], s[0:1], v0, s19, v[34:35]
	v_cndmask_b32_e32 v53, 0, v3, vcc
	v_cndmask_b32_e32 v54, 0, v2, vcc
	v_mov_b32_e32 v0, v136
	v_mov_b32_e32 v1, v137
	v_mov_b32_e32 v2, v138
	v_mov_b32_e32 v3, v139
	v_cmp_lt_i32_e32 vcc, 7, v36
	v_lshlrev_b32_e32 v21, 16, v56
	v_add_f32_e32 v15, v15, v21
	v_and_b32_e32 v21, 0xffff0000, v56
	v_add_f32_e32 v19, v19, v21
	v_lshlrev_b32_e32 v21, 16, v55
	v_add_f32_e32 v20, v20, v21
	v_and_b32_e32 v21, 0xffff0000, v55
	v_add_f32_e32 v14, v14, v21
	v_lshlrev_b32_e32 v21, 16, v54
	v_add_f32_e32 v18, v18, v21
	v_and_b32_e32 v21, 0xffff0000, v54
	v_add_f32_e32 v13, v13, v21
	v_lshlrev_b32_e32 v21, 16, v53
	v_add_f32_e32 v17, v17, v21
	v_and_b32_e32 v21, 0xffff0000, v53
	v_add_f32_e32 v12, v12, v21
	s_waitcnt vmcnt(0)
	v_cndmask_b32_e32 v60, 0, v0, vcc
	v_max_i32_e32 v0, 7, v36
	v_add3_u32 v0, s26, -7, v0
	v_cndmask_b32_e32 v59, 0, v1, vcc
	v_mad_i64_i32 v[0:1], s[0:1], v0, s19, v[34:35]
	v_cndmask_b32_e32 v57, 0, v3, vcc
	v_cndmask_b32_e32 v58, 0, v2, vcc
	v_mov_b32_e32 v0, v176
	v_mov_b32_e32 v1, v177
	v_mov_b32_e32 v2, v178
	v_mov_b32_e32 v3, v179
	v_cmp_lt_i32_e32 vcc, 6, v36
	v_lshlrev_b32_e32 v21, 16, v60
	v_add_f32_e32 v15, v15, v21
	v_and_b32_e32 v21, 0xffff0000, v60
	v_add_f32_e32 v19, v19, v21
	v_lshlrev_b32_e32 v21, 16, v59
	v_add_f32_e32 v20, v20, v21
	v_and_b32_e32 v21, 0xffff0000, v59
	v_add_f32_e32 v14, v14, v21
	v_lshlrev_b32_e32 v21, 16, v58
	v_add_f32_e32 v18, v18, v21
	v_and_b32_e32 v21, 0xffff0000, v58
	v_add_f32_e32 v13, v13, v21
	v_lshlrev_b32_e32 v21, 16, v57
	v_add_f32_e32 v17, v17, v21
	v_and_b32_e32 v21, 0xffff0000, v57
	v_add_f32_e32 v12, v12, v21
	s_waitcnt vmcnt(0)
	v_cndmask_b32_e32 v64, 0, v0, vcc
	v_max_i32_e32 v0, 6, v36
	v_add3_u32 v0, s26, -6, v0
	v_cndmask_b32_e32 v63, 0, v1, vcc
	v_mad_i64_i32 v[0:1], s[0:1], v0, s19, v[34:35]
	v_cndmask_b32_e32 v61, 0, v3, vcc
	v_cndmask_b32_e32 v62, 0, v2, vcc
	v_mov_b32_e32 v0, v180
	v_mov_b32_e32 v1, v181
	v_mov_b32_e32 v2, v182
	v_mov_b32_e32 v3, v183
	v_cmp_lt_i32_e32 vcc, 5, v36
	v_lshlrev_b32_e32 v21, 16, v64
	v_add_f32_e32 v15, v15, v21
	v_and_b32_e32 v21, 0xffff0000, v64
	v_add_f32_e32 v19, v19, v21
	v_lshlrev_b32_e32 v21, 16, v63
	v_add_f32_e32 v20, v20, v21
	v_and_b32_e32 v21, 0xffff0000, v63
	v_add_f32_e32 v14, v14, v21
	v_lshlrev_b32_e32 v21, 16, v62
	v_add_f32_e32 v18, v18, v21
	v_and_b32_e32 v21, 0xffff0000, v62
	v_add_f32_e32 v13, v13, v21
	v_lshlrev_b32_e32 v21, 16, v61
	v_add_f32_e32 v17, v17, v21
	v_and_b32_e32 v21, 0xffff0000, v61
	v_add_f32_e32 v12, v12, v21
	s_waitcnt vmcnt(0)
	v_cndmask_b32_e32 v68, 0, v0, vcc
	v_max_i32_e32 v0, 5, v36
	v_add3_u32 v0, s26, -5, v0
	v_cndmask_b32_e32 v67, 0, v1, vcc
	v_mad_i64_i32 v[0:1], s[0:1], v0, s19, v[34:35]
	v_cndmask_b32_e32 v65, 0, v3, vcc
	v_cndmask_b32_e32 v66, 0, v2, vcc
	v_mov_b32_e32 v0, v184
	v_mov_b32_e32 v1, v185
	v_mov_b32_e32 v2, v186
	v_mov_b32_e32 v3, v187
	v_cmp_lt_i32_e32 vcc, 4, v36
	v_lshlrev_b32_e32 v21, 16, v68
	v_add_f32_e32 v15, v15, v21
	v_and_b32_e32 v21, 0xffff0000, v68
	v_add_f32_e32 v19, v19, v21
	v_lshlrev_b32_e32 v21, 16, v67
	v_add_f32_e32 v20, v20, v21
	v_and_b32_e32 v21, 0xffff0000, v67
	v_add_f32_e32 v14, v14, v21
	v_lshlrev_b32_e32 v21, 16, v66
	v_add_f32_e32 v18, v18, v21
	v_and_b32_e32 v21, 0xffff0000, v66
	v_add_f32_e32 v13, v13, v21
	v_lshlrev_b32_e32 v21, 16, v65
	v_add_f32_e32 v17, v17, v21
	v_and_b32_e32 v21, 0xffff0000, v65
	v_add_f32_e32 v12, v12, v21
	s_waitcnt vmcnt(0)
	v_cndmask_b32_e32 v72, 0, v0, vcc
	v_max_i32_e32 v0, 4, v36
	v_add3_u32 v0, s26, -4, v0
	v_cndmask_b32_e32 v71, 0, v1, vcc
	v_mad_i64_i32 v[0:1], s[0:1], v0, s19, v[34:35]
	v_cndmask_b32_e32 v69, 0, v3, vcc
	v_cndmask_b32_e32 v70, 0, v2, vcc
	v_mov_b32_e32 v0, v188
	v_mov_b32_e32 v1, v189
	v_mov_b32_e32 v2, v190
	v_mov_b32_e32 v3, v191
	v_cmp_lt_i32_e32 vcc, 3, v36
	v_lshlrev_b32_e32 v21, 16, v72
	v_add_f32_e32 v15, v15, v21
	v_and_b32_e32 v21, 0xffff0000, v72
	v_add_f32_e32 v19, v19, v21
	v_lshlrev_b32_e32 v21, 16, v71
	v_add_f32_e32 v20, v20, v21
	v_and_b32_e32 v21, 0xffff0000, v71
	v_add_f32_e32 v14, v14, v21
	v_lshlrev_b32_e32 v21, 16, v70
	v_add_f32_e32 v18, v18, v21
	v_and_b32_e32 v21, 0xffff0000, v70
	v_add_f32_e32 v13, v13, v21
	v_lshlrev_b32_e32 v21, 16, v69
	v_add_f32_e32 v17, v17, v21
	v_and_b32_e32 v21, 0xffff0000, v69
	v_add_f32_e32 v12, v12, v21
	s_waitcnt vmcnt(0)
	v_cndmask_b32_e32 v76, 0, v0, vcc
	v_max_i32_e32 v0, 3, v36
	v_add3_u32 v0, s26, -3, v0
	v_cndmask_b32_e32 v75, 0, v1, vcc
	v_mad_i64_i32 v[0:1], s[0:1], v0, s19, v[34:35]
	v_cndmask_b32_e32 v73, 0, v3, vcc
	v_cndmask_b32_e32 v74, 0, v2, vcc
	v_mov_b32_e32 v0, v192
	v_mov_b32_e32 v1, v193
	v_mov_b32_e32 v2, v194
	v_mov_b32_e32 v3, v195
	v_cmp_lt_i32_e32 vcc, 2, v36
	v_lshlrev_b32_e32 v21, 16, v76
	v_add_f32_e32 v15, v15, v21
	v_and_b32_e32 v21, 0xffff0000, v76
	v_add_f32_e32 v19, v19, v21
	v_lshlrev_b32_e32 v21, 16, v75
	v_add_f32_e32 v20, v20, v21
	v_and_b32_e32 v21, 0xffff0000, v75
	v_add_f32_e32 v14, v14, v21
	v_lshlrev_b32_e32 v21, 16, v74
	v_add_f32_e32 v18, v18, v21
	v_and_b32_e32 v21, 0xffff0000, v74
	v_add_f32_e32 v13, v13, v21
	v_lshlrev_b32_e32 v21, 16, v73
	v_add_f32_e32 v17, v17, v21
	v_and_b32_e32 v21, 0xffff0000, v73
	v_add_f32_e32 v12, v12, v21
	s_waitcnt vmcnt(0)
	v_cndmask_b32_e32 v80, 0, v0, vcc
	v_max_i32_e32 v0, 2, v36
	v_add3_u32 v0, s26, -2, v0
	v_cndmask_b32_e32 v79, 0, v1, vcc
	v_mad_i64_i32 v[0:1], s[0:1], v0, s19, v[34:35]
	v_cndmask_b32_e32 v77, 0, v3, vcc
	v_cndmask_b32_e32 v78, 0, v2, vcc
	v_mov_b32_e32 v0, v196
	v_mov_b32_e32 v1, v197
	v_mov_b32_e32 v2, v198
	v_mov_b32_e32 v3, v199
	v_cmp_lt_i32_e32 vcc, 1, v36
	v_lshlrev_b32_e32 v21, 16, v80
	v_add_f32_e32 v15, v15, v21
	v_and_b32_e32 v21, 0xffff0000, v80
	v_add_f32_e32 v19, v19, v21
	v_lshlrev_b32_e32 v21, 16, v79
	v_add_f32_e32 v20, v20, v21
	v_and_b32_e32 v21, 0xffff0000, v79
	v_add_f32_e32 v14, v14, v21
	v_lshlrev_b32_e32 v21, 16, v78
	v_add_f32_e32 v18, v18, v21
	v_and_b32_e32 v21, 0xffff0000, v78
	v_add_f32_e32 v13, v13, v21
	v_lshlrev_b32_e32 v21, 16, v77
	v_add_f32_e32 v17, v17, v21
	v_and_b32_e32 v21, 0xffff0000, v77
	v_add_f32_e32 v12, v12, v21
	s_waitcnt vmcnt(0)
	v_cndmask_b32_e32 v83, 0, v1, vcc
	v_cndmask_b32_e32 v85, 0, v0, vcc
	v_mad_i64_i32 v[0:1], s[0:1], v44, s19, v[34:35]
	v_cndmask_b32_e32 v81, 0, v3, vcc
	v_cndmask_b32_e32 v82, 0, v2, vcc
	v_mov_b32_e32 v0, v200
	v_mov_b32_e32 v1, v201
	v_mov_b32_e32 v2, v202
	v_mov_b32_e32 v3, v203
	v_lshlrev_b32_e32 v21, 16, v85
	v_add_f32_e32 v15, v15, v21
	v_and_b32_e32 v21, 0xffff0000, v85
	v_add_f32_e32 v19, v19, v21
	v_lshlrev_b32_e32 v21, 16, v83
	v_add_f32_e32 v20, v20, v21
	v_and_b32_e32 v21, 0xffff0000, v83
	v_add_f32_e32 v14, v14, v21
	v_lshlrev_b32_e32 v21, 16, v82
	v_add_f32_e32 v18, v18, v21
	v_and_b32_e32 v21, 0xffff0000, v82
	v_add_f32_e32 v13, v13, v21
	v_lshlrev_b32_e32 v21, 16, v81
	v_add_f32_e32 v17, v17, v21
	v_and_b32_e32 v21, 0xffff0000, v81
	v_add_f32_e32 v12, v12, v21
	s_waitcnt vmcnt(0)
	v_cndmask_b32_e64 v87, 0, v1, s[14:15]
	v_cndmask_b32_e64 v88, 0, v0, s[14:15]
	v_mad_i64_i32 v[0:1], s[0:1], v43, s19, v[34:35]
	v_cndmask_b32_e64 v84, 0, v3, s[14:15]
	v_cndmask_b32_e64 v86, 0, v2, s[14:15]
	v_mov_b32_e32 v0, v218
	v_mov_b32_e32 v1, v219
	v_mov_b32_e32 v2, v220
	v_mov_b32_e32 v3, v221
	v_lshlrev_b32_e32 v21, 16, v88
	v_add_f32_e32 v15, v15, v21
	v_and_b32_e32 v21, 0xffff0000, v88
	v_add_f32_e32 v19, v19, v21
	v_lshlrev_b32_e32 v21, 16, v87
	v_add_f32_e32 v20, v20, v21
	v_and_b32_e32 v21, 0xffff0000, v87
	v_add_f32_e32 v14, v14, v21
	v_lshlrev_b32_e32 v21, 16, v86
	v_add_f32_e32 v18, v18, v21
	v_and_b32_e32 v21, 0xffff0000, v86
	v_add_f32_e32 v13, v13, v21
	v_lshlrev_b32_e32 v21, 16, v84
	v_add_f32_e32 v17, v17, v21
	v_and_b32_e32 v21, 0xffff0000, v84
	v_add_f32_e32 v12, v12, v21
	s_waitcnt vmcnt(0)
	v_cndmask_b32_e64 v3, 0, v3, s[12:13]
	v_and_b32_e32 v46, 0xffff0000, v3
	v_add_f32_e32 v47, v12, v46
	v_min_i32_e32 v12, 15, v36
	v_add_u32_e32 v12, 1, v12
	v_cvt_f32_i32_e32 v12, v12
	v_cndmask_b32_e64 v2, 0, v2, s[12:13]
	v_and_b32_e32 v30, 0xffff0000, v2
	v_add_f32_e32 v31, v13, v30
	v_div_scale_f32 v13, s[0:1], v12, v12, 1.0
	v_rcp_f32_e32 v48, v13
	v_cndmask_b32_e64 v0, 0, v0, s[12:13]
	v_lshlrev_b32_e32 v21, 16, v0
	v_cndmask_b32_e64 v1, 0, v1, s[12:13]
	v_fma_f32 v49, -v13, v48, 1.0
	v_fmac_f32_e32 v48, v49, v48
	v_div_scale_f32 v49, vcc, 1.0, v12, 1.0
	v_mul_f32_e32 v50, v49, v48
	v_fma_f32 v51, -v13, v50, v49
	v_fmac_f32_e32 v50, v51, v48
	v_fma_f32 v13, -v13, v50, v49
	v_div_fmas_f32 v13, v13, v48, v50
	v_add_f32_e32 v22, v15, v21
	v_and_b32_e32 v15, 0xffff0000, v0
	v_div_fixup_f32 v12, v13, v12, 1.0
	v_add_f32_e32 v19, v19, v15
	v_lshlrev_b32_e32 v23, 16, v1
	v_cndmask_b32_e64 v48, v12, v211, s[6:7]
	v_add_f32_e32 v20, v20, v23
	v_fma_f32 v12, v48, v22, -v21
	v_fma_f32 v13, v48, v19, -v15
	v_and_b32_e32 v28, 0xffff0000, v1
	v_cvt_pk_bf16_f32 v12, v12, v13
	v_fma_f32 v13, v48, v20, -v23
	v_and_b32_e32 v23, 0xffff0000, v4
	v_add_f32_e32 v29, v14, v28
	v_lshlrev_b32_e32 v14, 16, v2
	v_add_f32_e32 v19, v19, v23
	v_add_f32_e32 v18, v18, v14
	v_lshlrev_b32_e32 v45, 16, v3
	v_fma_f32 v15, v48, v29, -v28
	v_sub_f32_e32 v28, v19, v16
	v_lshlrev_b32_e32 v19, 16, v5
	v_add_f32_e32 v17, v17, v45
	v_cvt_pk_bf16_f32 v13, v13, v15
	v_fma_f32 v14, v48, v18, -v14
	v_fma_f32 v15, v48, v31, -v30
	v_add_f32_e32 v16, v20, v19
	v_and_b32_e32 v30, 0xffff0000, v5
	v_cvt_pk_bf16_f32 v14, v14, v15
	v_fma_f32 v15, v48, v17, -v45
	v_sub_f32_e32 v20, v16, v93
	v_add_f32_e32 v16, v29, v30
	v_lshlrev_b32_e32 v45, 16, v6
	v_sub_f32_e32 v29, v16, v94
	v_add_f32_e32 v16, v18, v45
	v_and_b32_e32 v18, 0xffff0000, v6
	v_fma_f32 v21, v48, v47, -v46
	v_sub_f32_e32 v46, v16, v95
	v_add_f32_e32 v16, v31, v18
	v_lshlrev_b32_e32 v48, 16, v7
	v_sub_f32_e32 v31, v16, v97
	v_add_f32_e32 v16, v17, v48
	v_and_b32_e32 v50, 0xffff0000, v7
	v_sub_f32_e32 v49, v16, v98
	v_add_f32_e32 v16, v47, v50
	v_sub_f32_e32 v47, v16, v100
	v_min_i32_e32 v16, 15, v39
	v_add_u32_e32 v16, 1, v16
	v_cvt_f32_i32_e32 v16, v16
	v_cvt_pk_bf16_f32 v15, v15, v21
	v_lshlrev_b32_e32 v21, 16, v4
	v_add_f32_e32 v22, v22, v21
	v_div_scale_f32 v17, s[0:1], v16, v16, 1.0
	v_rcp_f32_e32 v51, v17
	v_sub_f32_e32 v22, v22, v92
	v_fma_f32 v52, -v17, v51, 1.0
	v_fmac_f32_e32 v51, v52, v51
	v_div_scale_f32 v52, vcc, 1.0, v16, 1.0
	v_mul_f32_e32 v53, v52, v51
	v_fma_f32 v54, -v17, v53, v52
	v_fmac_f32_e32 v53, v54, v51
	v_fma_f32 v17, -v17, v53, v52
	v_div_fmas_f32 v17, v17, v51, v53
	v_div_fixup_f32 v16, v17, v16, 1.0
	v_cndmask_b32_e64 v51, v16, v211, s[6:7]
	v_fma_f32 v16, v51, v22, -v21
	v_fma_f32 v17, v51, v28, -v23
	v_cvt_pk_bf16_f32 v16, v16, v17
	v_fma_f32 v17, v51, v20, -v19
	v_fma_f32 v19, v51, v29, -v30
	v_cvt_pk_bf16_f32 v17, v17, v19
	v_fma_f32 v19, v51, v46, -v45
	v_fma_f32 v18, v51, v31, -v18
	v_cvt_pk_bf16_f32 v18, v19, v18
	v_fma_f32 v19, v51, v49, -v48
	v_fma_f32 v21, v51, v47, -v50
	v_cvt_pk_bf16_f32 v19, v19, v21
	v_lshlrev_b32_e32 v21, 16, v8
	v_add_f32_e32 v22, v22, v21
	v_sub_f32_e32 v30, v22, v101
	v_and_b32_e32 v22, 0xffff0000, v8
	v_add_f32_e32 v23, v28, v22
	v_sub_f32_e32 v28, v23, v102
	v_lshlrev_b32_e32 v23, 16, v9
	v_add_f32_e32 v20, v20, v23
	v_and_b32_e32 v48, 0xffff0000, v9
	v_sub_f32_e32 v45, v20, v103
	v_add_f32_e32 v20, v29, v48
	v_lshlrev_b32_e32 v50, 16, v10
	v_sub_f32_e32 v29, v20, v104
	v_add_f32_e32 v20, v46, v50
	v_and_b32_e32 v51, 0xffff0000, v10
	v_sub_f32_e32 v46, v20, v105
	v_add_f32_e32 v20, v31, v51
	v_lshlrev_b32_e32 v52, 16, v11
	v_sub_f32_e32 v31, v20, v96
	v_add_f32_e32 v20, v49, v52
	v_and_b32_e32 v53, 0xffff0000, v11
	v_sub_f32_e32 v49, v20, v106
	v_add_f32_e32 v20, v47, v53
	v_sub_f32_e32 v47, v20, v99
	v_min_i32_e32 v20, 15, v38
	v_add_u32_e32 v20, 1, v20
	v_cvt_f32_i32_e32 v20, v20
	v_div_scale_f32 v54, s[0:1], v20, v20, 1.0
	v_rcp_f32_e32 v55, v54
	s_nop 0
	v_fma_f32 v56, -v54, v55, 1.0
	v_fmac_f32_e32 v55, v56, v55
	v_div_scale_f32 v56, vcc, 1.0, v20, 1.0
	v_mul_f32_e32 v57, v56, v55
	v_fma_f32 v58, -v54, v57, v56
	v_fmac_f32_e32 v57, v58, v55
	v_fma_f32 v54, -v54, v57, v56
	v_div_fmas_f32 v54, v54, v55, v57
	v_min_i32_e32 v57, 15, v37
	v_add_u32_e32 v57, 1, v57
	v_cvt_f32_i32_e32 v57, v57
	v_div_fixup_f32 v20, v54, v20, 1.0
	v_cmp_lt_i32_e32 vcc, -4, v36
	v_cndmask_b32_e64 v54, v20, v211, s[6:7]
	v_div_scale_f32 v58, s[0:1], v57, v57, 1.0
	v_rcp_f32_e32 v59, v58
	v_cndmask_b32_e32 v27, 0, v27, vcc
	v_cndmask_b32_e32 v26, 0, v26, vcc
	v_cndmask_b32_e32 v25, 0, v25, vcc
	v_fma_f32 v60, -v58, v59, 1.0
	v_cndmask_b32_e32 v24, 0, v24, vcc
	v_fmac_f32_e32 v59, v60, v59
	v_div_scale_f32 v60, vcc, 1.0, v57, 1.0
	v_fma_f32 v20, v54, v30, -v21
	v_fma_f32 v21, v54, v28, -v22
	v_mul_f32_e32 v61, v60, v59
	v_cvt_pk_bf16_f32 v20, v20, v21
	v_fma_f32 v21, v54, v45, -v23
	v_fma_f32 v22, v54, v29, -v48
	v_fma_f32 v62, -v58, v61, v60
	v_cvt_pk_bf16_f32 v21, v21, v22
	v_fma_f32 v22, v54, v46, -v50
	v_fma_f32 v23, v54, v31, -v51
	v_fmac_f32_e32 v61, v62, v59
	v_cvt_pk_bf16_f32 v22, v22, v23
	v_fma_f32 v23, v54, v49, -v52
	v_fma_f32 v48, v54, v47, -v53
	v_fma_f32 v58, -v58, v61, v60
	v_cvt_pk_bf16_f32 v23, v23, v48
	v_lshlrev_b32_e32 v48, 16, v24
	v_and_b32_e32 v50, 0xffff0000, v24
	v_div_fmas_f32 v58, v58, v59, v61
	v_add_f32_e32 v30, v30, v48
	v_add_f32_e32 v28, v28, v50
	v_lshlrev_b32_e32 v51, 16, v25
	v_and_b32_e32 v52, 0xffff0000, v25
	v_div_fixup_f32 v57, v58, v57, 1.0
	v_sub_f32_e32 v30, v30, v107
	v_sub_f32_e32 v28, v28, v108
	v_add_f32_e32 v45, v45, v51
	v_add_f32_e32 v29, v29, v52
	v_lshlrev_b32_e32 v53, 16, v26
	v_and_b32_e32 v54, 0xffff0000, v26
	v_cndmask_b32_e64 v57, v57, v211, s[6:7]
	v_sub_f32_e32 v45, v45, v109
	v_sub_f32_e32 v29, v29, v110
	v_add_f32_e32 v46, v46, v53
	v_add_f32_e32 v31, v31, v54
	v_lshlrev_b32_e32 v55, 16, v27
	v_fma_f32 v30, v57, v30, -v48
	v_fma_f32 v28, v57, v28, -v50
	v_sub_f32_e32 v46, v46, v111
	v_sub_f32_e32 v31, v31, v91
	v_add_f32_e32 v49, v49, v55
	v_and_b32_e32 v56, 0xffff0000, v27
	v_cvt_pk_bf16_f32 v28, v30, v28
	v_fma_f32 v30, v57, v45, -v51
	v_fma_f32 v29, v57, v29, -v52
	v_sub_f32_e32 v49, v49, v90
	v_add_f32_e32 v47, v47, v56
	v_cvt_pk_bf16_f32 v29, v30, v29
	v_fma_f32 v30, v57, v46, -v53
	v_fma_f32 v31, v57, v31, -v54
	v_sub_f32_e32 v47, v47, v89
	v_cvt_pk_bf16_f32 v30, v30, v31
	v_fma_f32 v31, v57, v49, -v55
	v_fma_f32 v45, v57, v47, -v56
	v_cvt_pk_bf16_f32 v31, v31, v45
	s_mov_b64 s[0:1], 0

.LBB0_966:
	s_and_b64 vcc, exec, s[8:9]
	s_cbranch_vccz .LBB0_940
	s_mul_i32 s0, s0, 15
	s_ashr_i32 s1, s0, 31
	s_sub_i32 s4, s29, s30
	s_lshl_b64 s[0:1], s[0:1], 9
	s_add_u32 s24, s0, 0xf000
	s_addc_u32 s25, s1, 0
	s_lshl_b32 s8, s6, 7
	s_cmp_eq_u32 s30, 0
	s_cselect_b64 s[0:1], -1, 0
	v_or_b32_e32 v32, s8, v207
	s_and_b64 s[16:17], s[14:15], s[0:1]
	v_add_u32_e32 v36, s30, v150
	s_mov_b64 s[0:1], -1
	s_andn2_b64 vcc, exec, s[16:17]
	v_ashrrev_i32_e32 v33, 31, v32
	s_cbranch_vccz .LBB0_983
	v_lshl_add_u64 v[34:35], v[32:33], 1, s[52:53]
	s_mov_b64 s[18:19], -1
	s_mov_b64 s[0:1], 0
	s_cmp_lt_i32 s6, 1
	s_mov_b64 s[16:17], 0
	s_cbranch_scc1 .LBB0_976
	s_cmp_gt_i32 s6, 1
	s_cbranch_scc0 .LBB0_973
	s_cmp_eq_u32 s6, 2
	s_mov_b64 s[16:17], -1
	s_cbranch_scc0 .LBB0_972
	v_max_i32_e32 v112, 6, v36
	v_add3_u32 v112, s4, -6, v112
	v_mad_i64_i32 v[112:113], s[16:17], v112, s27, v[34:35]
	global_load_dwordx4 v[112:115], v[112:113], off
	v_max_i32_e32 v116, 5, v36
	v_add3_u32 v116, s4, -5, v116
	v_mad_i64_i32 v[116:117], s[16:17], v116, s27, v[34:35]
	global_load_dwordx4 v[116:119], v[116:117], off
	v_max_i32_e32 v120, 4, v36
	v_add3_u32 v120, s4, -4, v120
	v_mad_i64_i32 v[120:121], s[16:17], v120, s27, v[34:35]
	global_load_dwordx4 v[120:123], v[120:121], off
	v_max_i32_e32 v124, 3, v36
	v_add3_u32 v124, s4, -3, v124
	v_mad_i64_i32 v[124:125], s[16:17], v124, s27, v[34:35]
	global_load_dwordx4 v[124:127], v[124:125], off
	v_max_i32_e32 v128, 2, v36
	v_add3_u32 v128, s4, -2, v128
	v_mad_i64_i32 v[128:129], s[16:17], v128, s27, v[34:35]
	global_load_dwordx4 v[128:131], v[128:129], off
	v_max_i32_e32 v132, 1, v36
	v_add3_u32 v132, s4, -1, v132
	v_mad_i64_i32 v[132:133], s[16:17], v132, s27, v[34:35]
	global_load_dwordx4 v[132:135], v[132:133], off
	v_max_i32_e32 v136, 0, v36
	v_add_u32_e32 v136, s4, v136
	v_mad_i64_i32 v[136:137], s[16:17], v136, s27, v[34:35]
	global_load_dwordx4 v[136:139], v[136:137], off
	v_max_i32_e32 v0, 7, v36
	v_add3_u32 v0, s4, -7, v0
	v_mad_i64_i32 v[0:1], s[16:17], v0, s27, v[34:35]
	global_load_dwordx4 v[0:3], v[0:1], off
	v_or_b32_e32 v52, 1, v36
	v_max_i32_e32 v4, 0, v52
	v_add_u32_e32 v4, s4, v4
	v_cmp_lt_i32_e32 vcc, 6, v36
	v_mad_i64_i32 v[4:5], s[16:17], v4, s27, v[34:35]
	global_load_dwordx4 v[4:7], v[4:5], off
	v_or_b32_e32 v20, 2, v36
	v_max_i32_e32 v8, 0, v20
	v_add_u32_e32 v8, s4, v8
	v_mad_i64_i32 v[8:9], s[16:17], v8, s27, v[34:35]
	v_or_b32_e32 v53, 3, v36
	v_max_i32_e32 v12, 0, v53
	v_add_u32_e32 v12, s4, v12
	v_mad_i64_i32 v[12:13], s[16:17], v12, s27, v[34:35]
	v_min_i32_e32 v20, 7, v20
	v_add_u32_e32 v20, 1, v20
	v_cvt_f32_i32_e32 v20, v20
	global_load_dwordx4 v[8:11], v[8:9], off
	s_waitcnt vmcnt(2)
	v_cndmask_b32_e32 v17, 0, v0, vcc
	v_max_i32_e32 v0, 6, v36
	v_add3_u32 v0, s4, -6, v0
	v_cndmask_b32_e32 v16, 0, v1, vcc
	v_mad_i64_i32 v[0:1], s[16:17], v0, s27, v[34:35]
	v_cndmask_b32_e32 v14, 0, v3, vcc
	v_cndmask_b32_e32 v15, 0, v2, vcc
	v_mov_b32_e32 v0, v112
	v_mov_b32_e32 v1, v113
	v_mov_b32_e32 v2, v114
	v_mov_b32_e32 v3, v115
	v_cmp_lt_i32_e32 vcc, 5, v36
	v_lshlrev_b32_e32 v54, 16, v17
	v_and_b32_e32 v17, 0xffff0000, v17
	v_lshlrev_b32_e32 v55, 16, v16
	v_and_b32_e32 v16, 0xffff0000, v16
	v_add_f32_e32 v56, 0, v55
	v_add_f32_e32 v57, 0, v16
	v_and_b32_e32 v60, 0xffff0000, v15
	v_lshlrev_b32_e32 v61, 16, v14
	v_lshlrev_b32_e32 v58, 16, v15
	v_add_f32_e32 v15, 0, v60
	v_add_f32_e32 v62, 0, v61
	v_and_b32_e32 v63, 0xffff0000, v14
	v_add_f32_e32 v14, 0, v63
	v_add_f32_e32 v59, 0, v58
	global_load_dwordx4 v[24:27], v[12:13], off
	v_add_f32_e32 v12, 0, v54
	v_add_f32_e32 v13, 0, v17
	s_waitcnt vmcnt(1)
	v_cndmask_b32_e32 v22, 0, v0, vcc
	v_max_i32_e32 v0, 5, v36
	v_add3_u32 v0, s4, -5, v0
	v_cndmask_b32_e32 v21, 0, v1, vcc
	v_mad_i64_i32 v[0:1], s[16:17], v0, s27, v[34:35]
	v_cndmask_b32_e32 v18, 0, v3, vcc
	v_cndmask_b32_e32 v19, 0, v2, vcc
	v_mov_b32_e32 v0, v116
	v_mov_b32_e32 v1, v117
	v_mov_b32_e32 v2, v118
	v_mov_b32_e32 v3, v119
	v_cmp_lt_i32_e32 vcc, 4, v36
	v_lshlrev_b32_e32 v64, 16, v22
	v_add_f32_e32 v12, v12, v64
	v_and_b32_e32 v22, 0xffff0000, v22
	v_add_f32_e32 v13, v13, v22
	v_lshlrev_b32_e32 v65, 16, v21
	v_and_b32_e32 v21, 0xffff0000, v21
	v_add_f32_e32 v56, v56, v65
	v_add_f32_e32 v57, v57, v21
	v_and_b32_e32 v67, 0xffff0000, v19
	v_lshlrev_b32_e32 v68, 16, v18
	v_lshlrev_b32_e32 v66, 16, v19
	v_add_f32_e32 v15, v15, v67
	v_add_f32_e32 v19, v62, v68
	v_and_b32_e32 v62, 0xffff0000, v18
	v_add_f32_e32 v14, v14, v62
	v_add_f32_e32 v59, v59, v66
	s_waitcnt vmcnt(0)
	v_cndmask_b32_e32 v30, 0, v0, vcc
	v_max_i32_e32 v0, 4, v36
	v_add3_u32 v0, s4, -4, v0
	v_cndmask_b32_e32 v29, 0, v1, vcc
	v_mad_i64_i32 v[0:1], s[16:17], v0, s27, v[34:35]
	v_cndmask_b32_e32 v23, 0, v3, vcc
	v_cndmask_b32_e32 v28, 0, v2, vcc
	v_mov_b32_e32 v0, v120
	v_mov_b32_e32 v1, v121
	v_mov_b32_e32 v2, v122
	v_mov_b32_e32 v3, v123
	v_cmp_lt_i32_e32 vcc, 3, v36
	v_lshlrev_b32_e32 v69, 16, v30
	v_add_f32_e32 v12, v12, v69
	v_and_b32_e32 v30, 0xffff0000, v30
	v_lshlrev_b32_e32 v71, 16, v23
	v_and_b32_e32 v72, 0xffff0000, v23
	v_add_f32_e32 v13, v13, v30
	v_lshlrev_b32_e32 v70, 16, v29
	v_and_b32_e32 v29, 0xffff0000, v29
	v_add_f32_e32 v18, v56, v70
	v_add_f32_e32 v56, v57, v29
	v_lshlrev_b32_e32 v57, 16, v28
	v_and_b32_e32 v28, 0xffff0000, v28
	v_add_f32_e32 v15, v15, v28
	v_add_f32_e32 v19, v19, v71
	v_add_f32_e32 v14, v14, v72
	v_add_f32_e32 v59, v59, v57
	s_waitcnt vmcnt(0)
	v_cndmask_b32_e32 v39, 0, v0, vcc
	v_max_i32_e32 v0, 3, v36
	v_add3_u32 v0, s4, -3, v0
	v_cndmask_b32_e32 v38, 0, v1, vcc
	v_mad_i64_i32 v[0:1], s[16:17], v0, s27, v[34:35]
	v_cndmask_b32_e32 v31, 0, v3, vcc
	v_cndmask_b32_e32 v37, 0, v2, vcc
	v_mov_b32_e32 v0, v124
	v_mov_b32_e32 v1, v125
	v_mov_b32_e32 v2, v126
	v_mov_b32_e32 v3, v127
	v_cmp_lt_i32_e32 vcc, 2, v36
	v_lshlrev_b32_e32 v23, 16, v39
	v_add_f32_e32 v12, v12, v23
	v_and_b32_e32 v23, 0xffff0000, v39
	v_add_f32_e32 v13, v13, v23
	v_lshlrev_b32_e32 v23, 16, v38
	v_add_f32_e32 v18, v18, v23
	v_and_b32_e32 v23, 0xffff0000, v38
	v_lshlrev_b32_e32 v38, 16, v37
	v_and_b32_e32 v37, 0xffff0000, v37
	v_add_f32_e32 v15, v15, v37
	v_lshlrev_b32_e32 v37, 16, v31
	v_add_f32_e32 v19, v19, v37
	v_and_b32_e32 v31, 0xffff0000, v31
	v_add_f32_e32 v14, v14, v31
	v_add_f32_e32 v23, v56, v23
	v_add_f32_e32 v38, v59, v38
	s_waitcnt vmcnt(0)
	v_cndmask_b32_e32 v43, 0, v0, vcc
	v_max_i32_e32 v0, 2, v36
	v_add3_u32 v0, s4, -2, v0
	v_cndmask_b32_e32 v42, 0, v1, vcc
	v_mad_i64_i32 v[0:1], s[16:17], v0, s27, v[34:35]
	v_cndmask_b32_e32 v40, 0, v3, vcc
	v_cndmask_b32_e32 v41, 0, v2, vcc
	v_mov_b32_e32 v0, v128
	v_mov_b32_e32 v1, v129
	v_mov_b32_e32 v2, v130
	v_mov_b32_e32 v3, v131
	v_cmp_lt_i32_e32 vcc, 1, v36
	v_and_b32_e32 v37, 0xffff0000, v41
	v_add_f32_e32 v15, v15, v37
	v_lshlrev_b32_e32 v37, 16, v40
	v_lshlrev_b32_e32 v31, 16, v43
	v_add_f32_e32 v19, v19, v37
	v_and_b32_e32 v37, 0xffff0000, v40
	v_add_f32_e32 v12, v12, v31
	v_and_b32_e32 v31, 0xffff0000, v43
	v_add_f32_e32 v14, v14, v37
	v_add_f32_e32 v13, v13, v31
	v_lshlrev_b32_e32 v31, 16, v42
	v_add_f32_e32 v18, v18, v31
	v_and_b32_e32 v31, 0xffff0000, v42
	v_add_f32_e32 v23, v23, v31
	v_lshlrev_b32_e32 v31, 16, v41
	v_add_f32_e32 v31, v38, v31
	s_waitcnt vmcnt(0)
	v_cndmask_b32_e32 v47, 0, v0, vcc
	v_max_i32_e32 v0, 1, v36
	v_add3_u32 v0, s4, -1, v0
	v_cndmask_b32_e32 v46, 0, v1, vcc
	v_mad_i64_i32 v[0:1], s[16:17], v0, s27, v[34:35]
	v_cndmask_b32_e32 v44, 0, v3, vcc
	v_cndmask_b32_e32 v45, 0, v2, vcc
	v_mov_b32_e32 v0, v132
	v_mov_b32_e32 v1, v133
	v_mov_b32_e32 v2, v134
	v_mov_b32_e32 v3, v135
	v_cmp_lt_i32_e32 vcc, 0, v36
	v_lshlrev_b32_e32 v37, 16, v47
	v_add_f32_e32 v12, v12, v37
	v_and_b32_e32 v37, 0xffff0000, v47
	v_add_f32_e32 v13, v13, v37
	v_lshlrev_b32_e32 v37, 16, v46
	v_add_f32_e32 v18, v18, v37
	v_and_b32_e32 v37, 0xffff0000, v46
	v_add_f32_e32 v23, v23, v37
	v_lshlrev_b32_e32 v37, 16, v45
	v_add_f32_e32 v31, v31, v37
	v_and_b32_e32 v37, 0xffff0000, v45
	v_add_f32_e32 v15, v15, v37
	v_lshlrev_b32_e32 v37, 16, v44
	v_add_f32_e32 v19, v19, v37
	v_and_b32_e32 v37, 0xffff0000, v44
	v_add_f32_e32 v14, v14, v37
	s_waitcnt vmcnt(0)
	v_cndmask_b32_e32 v51, 0, v0, vcc
	v_max_i32_e32 v0, 0, v36
	v_add_u32_e32 v0, s4, v0
	v_cndmask_b32_e32 v50, 0, v1, vcc
	v_mad_i64_i32 v[0:1], s[16:17], v0, s27, v[34:35]
	v_cndmask_b32_e32 v48, 0, v3, vcc
	v_cndmask_b32_e32 v49, 0, v2, vcc
	v_mov_b32_e32 v0, v136
	v_mov_b32_e32 v1, v137
	v_mov_b32_e32 v2, v138
	v_mov_b32_e32 v3, v139
	v_lshlrev_b32_e32 v37, 16, v51
	v_add_f32_e32 v12, v12, v37
	v_and_b32_e32 v37, 0xffff0000, v51
	v_add_f32_e32 v13, v13, v37
	v_lshlrev_b32_e32 v37, 16, v50
	v_add_f32_e32 v18, v18, v37
	v_and_b32_e32 v37, 0xffff0000, v50
	v_add_f32_e32 v23, v23, v37
	v_lshlrev_b32_e32 v37, 16, v49
	v_add_f32_e32 v31, v31, v37
	v_and_b32_e32 v37, 0xffff0000, v49
	v_cmp_lt_i32_e32 vcc, -1, v36
	v_add_f32_e32 v15, v15, v37
	v_lshlrev_b32_e32 v37, 16, v48
	v_add_f32_e32 v19, v19, v37
	v_and_b32_e32 v37, 0xffff0000, v48
	v_add_f32_e32 v14, v14, v37
	s_waitcnt vmcnt(0)
	v_cndmask_b32_e32 v3, 0, v3, vcc
	v_and_b32_e32 v44, 0xffff0000, v3
	v_add_f32_e32 v45, v14, v44
	v_min_i32_e32 v14, 7, v36
	v_add_u32_e32 v14, 1, v14
	v_cvt_f32_i32_e32 v14, v14
	v_cndmask_b32_e32 v2, 0, v2, vcc
	v_cndmask_b32_e32 v1, 0, v1, vcc
	v_cndmask_b32_e32 v0, 0, v0, vcc
	v_div_scale_f32 v46, s[16:17], v14, v14, 1.0
	v_rcp_f32_e32 v47, v46
	v_cmp_lt_i32_e32 vcc, -2, v36
	v_lshlrev_b32_e32 v37, 16, v0
	v_add_f32_e32 v38, v12, v37
	v_cndmask_b32_e32 v7, 0, v7, vcc
	v_cndmask_b32_e32 v6, 0, v6, vcc
	v_cndmask_b32_e32 v5, 0, v5, vcc
	v_cndmask_b32_e32 v4, 0, v4, vcc
	v_cmp_lt_i32_e32 vcc, -3, v36
	v_fma_f32 v48, -v46, v47, 1.0
	v_fmac_f32_e32 v47, v48, v47
	v_cndmask_b32_e32 v11, 0, v11, vcc
	v_cndmask_b32_e32 v10, 0, v10, vcc
	v_cndmask_b32_e32 v9, 0, v9, vcc
	v_cndmask_b32_e32 v8, 0, v8, vcc
	v_div_scale_f32 v48, vcc, 1.0, v14, 1.0
	v_mul_f32_e32 v49, v48, v47
	v_fma_f32 v50, -v46, v49, v48
	v_fmac_f32_e32 v49, v50, v47
	v_fma_f32 v46, -v46, v49, v48
	v_div_fmas_f32 v46, v46, v47, v49
	v_and_b32_e32 v12, 0xffff0000, v0
	v_div_fixup_f32 v14, v46, v14, 1.0
	v_add_f32_e32 v39, v13, v12
	v_and_b32_e32 v40, 0xffff0000, v1
	v_cndmask_b32_e64 v46, v14, v211, s[14:15]
	v_add_f32_e32 v23, v23, v40
	v_fma_f32 v14, v46, v38, -v37
	v_fma_f32 v12, v46, v39, -v12
	v_cvt_pk_bf16_f32 v12, v14, v12
	v_fma_f32 v14, v46, v23, -v40
	v_and_b32_e32 v40, 0xffff0000, v4
	v_lshlrev_b32_e32 v13, 16, v1
	v_add_f32_e32 v39, v39, v40
	v_add_f32_e32 v18, v18, v13
	v_lshlrev_b32_e32 v41, 16, v2
	v_sub_f32_e32 v39, v39, v17
	v_lshlrev_b32_e32 v17, 16, v5
	v_add_f32_e32 v31, v31, v41
	v_and_b32_e32 v42, 0xffff0000, v2
	v_fma_f32 v13, v46, v18, -v13
	v_add_f32_e32 v18, v18, v17
	v_add_f32_e32 v43, v15, v42
	v_cvt_pk_bf16_f32 v13, v13, v14
	v_fma_f32 v14, v46, v31, -v41
	v_sub_f32_e32 v41, v18, v55
	v_and_b32_e32 v18, 0xffff0000, v5
	v_lshlrev_b32_e32 v15, 16, v3
	v_fma_f32 v37, v46, v43, -v42
	v_add_f32_e32 v23, v23, v18
	v_lshlrev_b32_e32 v42, 16, v6
	v_add_f32_e32 v19, v19, v15
	v_cvt_pk_bf16_f32 v14, v14, v37
	v_fma_f32 v37, v46, v45, -v44
	v_sub_f32_e32 v23, v23, v16
	v_add_f32_e32 v16, v31, v42
	v_and_b32_e32 v44, 0xffff0000, v6
	v_fma_f32 v15, v46, v19, -v15
	v_sub_f32_e32 v31, v16, v58
	v_add_f32_e32 v16, v43, v44
	v_lshlrev_b32_e32 v46, 16, v7
	v_sub_f32_e32 v43, v16, v60
	v_add_f32_e32 v16, v19, v46
	v_and_b32_e32 v19, 0xffff0000, v7
	v_sub_f32_e32 v47, v16, v61
	v_add_f32_e32 v16, v45, v19
	v_sub_f32_e32 v45, v16, v63
	v_min_i32_e32 v16, 7, v52
	v_add_u32_e32 v16, 1, v16
	v_cvt_f32_i32_e32 v16, v16
	v_cvt_pk_bf16_f32 v15, v15, v37
	v_lshlrev_b32_e32 v37, 16, v4
	v_add_f32_e32 v38, v38, v37
	v_div_scale_f32 v48, s[16:17], v16, v16, 1.0
	v_rcp_f32_e32 v49, v48
	v_sub_f32_e32 v38, v38, v54
	v_fma_f32 v50, -v48, v49, 1.0
	v_fmac_f32_e32 v49, v50, v49
	v_div_scale_f32 v50, vcc, 1.0, v16, 1.0
	v_mul_f32_e32 v51, v50, v49
	v_fma_f32 v52, -v48, v51, v50
	v_fmac_f32_e32 v51, v52, v49
	v_fma_f32 v48, -v48, v51, v50
	v_div_fmas_f32 v48, v48, v49, v51
	v_div_fixup_f32 v16, v48, v16, 1.0
	v_cndmask_b32_e64 v48, v16, v211, s[14:15]
	v_fma_f32 v17, v48, v41, -v17
	v_fma_f32 v18, v48, v23, -v18
	v_cvt_pk_bf16_f32 v17, v17, v18
	v_fma_f32 v18, v48, v31, -v42
	v_and_b32_e32 v42, 0xffff0000, v9
	v_fma_f32 v16, v48, v38, -v37
	v_fma_f32 v37, v48, v39, -v40
	v_add_f32_e32 v23, v23, v42
	v_cvt_pk_bf16_f32 v16, v16, v37
	v_fma_f32 v37, v48, v43, -v44
	v_sub_f32_e32 v44, v23, v21
	v_lshlrev_b32_e32 v23, 16, v10
	v_cvt_pk_bf16_f32 v18, v18, v37
	v_fma_f32 v37, v48, v47, -v46
	v_add_f32_e32 v21, v31, v23
	v_and_b32_e32 v46, 0xffff0000, v10
	v_fma_f32 v19, v48, v45, -v19
	v_sub_f32_e32 v31, v21, v66
	v_add_f32_e32 v21, v43, v46
	v_lshlrev_b32_e32 v48, 16, v11
	v_sub_f32_e32 v43, v21, v67
	v_add_f32_e32 v21, v47, v48
	v_and_b32_e32 v49, 0xffff0000, v11
	v_sub_f32_e32 v47, v21, v68
	v_add_f32_e32 v21, v45, v49
	v_sub_f32_e32 v45, v21, v62
	v_div_scale_f32 v21, s[16:17], v20, v20, 1.0
	v_rcp_f32_e32 v50, v21
	v_and_b32_e32 v40, 0xffff0000, v8
	v_cvt_pk_bf16_f32 v19, v37, v19
	v_lshlrev_b32_e32 v37, 16, v8
	v_fma_f32 v51, -v21, v50, 1.0
	v_fmac_f32_e32 v50, v51, v50
	v_div_scale_f32 v51, vcc, 1.0, v20, 1.0
	v_mul_f32_e32 v52, v51, v50
	v_fma_f32 v54, -v21, v52, v51
	v_fmac_f32_e32 v52, v54, v50
	v_fma_f32 v21, -v21, v52, v51
	v_add_f32_e32 v39, v39, v40
	v_div_fmas_f32 v21, v21, v50, v52
	v_add_f32_e32 v38, v38, v37
	v_sub_f32_e32 v39, v39, v22
	v_lshlrev_b32_e32 v22, 16, v9
	v_div_fixup_f32 v20, v21, v20, 1.0
	v_sub_f32_e32 v38, v38, v64
	v_add_f32_e32 v41, v41, v22
	v_cndmask_b32_e64 v50, v20, v211, s[14:15]
	v_sub_f32_e32 v41, v41, v65
	v_fma_f32 v20, v50, v38, -v37
	v_fma_f32 v21, v50, v39, -v40
	v_cmp_lt_i32_e32 vcc, -4, v36
	v_cvt_pk_bf16_f32 v20, v20, v21
	v_fma_f32 v21, v50, v41, -v22
	v_fma_f32 v22, v50, v44, -v42
	v_cndmask_b32_e32 v26, 0, v26, vcc
	v_cvt_pk_bf16_f32 v21, v21, v22
	v_fma_f32 v22, v50, v31, -v23
	v_fma_f32 v23, v50, v43, -v46
	v_cndmask_b32_e32 v27, 0, v27, vcc
	v_and_b32_e32 v46, 0xffff0000, v26
	v_cvt_pk_bf16_f32 v22, v22, v23
	v_fma_f32 v23, v50, v47, -v48
	v_add_f32_e32 v43, v43, v46
	v_lshlrev_b32_e32 v48, 16, v27
	v_fma_f32 v37, v50, v45, -v49
	v_sub_f32_e32 v43, v43, v28
	v_add_f32_e32 v28, v47, v48
	v_and_b32_e32 v49, 0xffff0000, v27
	v_sub_f32_e32 v47, v28, v71
	v_add_f32_e32 v28, v45, v49
	v_sub_f32_e32 v45, v28, v72
	v_min_i32_e32 v28, 7, v53
	v_add_u32_e32 v28, 1, v28
	v_cvt_f32_i32_e32 v28, v28
	v_cndmask_b32_e32 v25, 0, v25, vcc
	v_cndmask_b32_e32 v24, 0, v24, vcc
	v_and_b32_e32 v40, 0xffff0000, v24
	v_div_scale_f32 v50, s[16:17], v28, v28, 1.0
	v_rcp_f32_e32 v51, v50
	v_cvt_pk_bf16_f32 v23, v23, v37
	v_lshlrev_b32_e32 v37, 16, v24
	v_add_f32_e32 v39, v39, v40
	v_fma_f32 v52, -v50, v51, 1.0
	v_fmac_f32_e32 v51, v52, v51
	v_div_scale_f32 v52, vcc, 1.0, v28, 1.0
	v_mul_f32_e32 v53, v52, v51
	v_fma_f32 v54, -v50, v53, v52
	v_fmac_f32_e32 v53, v54, v51
	v_fma_f32 v50, -v50, v53, v52
	v_and_b32_e32 v42, 0xffff0000, v25
	v_div_fmas_f32 v50, v50, v51, v53
	v_add_f32_e32 v38, v38, v37
	v_sub_f32_e32 v30, v39, v30
	v_lshlrev_b32_e32 v39, 16, v25
	v_add_f32_e32 v44, v44, v42
	v_div_fixup_f32 v28, v50, v28, 1.0
	v_sub_f32_e32 v38, v38, v69
	v_add_f32_e32 v41, v41, v39
	v_sub_f32_e32 v29, v44, v29
	v_lshlrev_b32_e32 v44, 16, v26
	v_cndmask_b32_e64 v50, v28, v211, s[14:15]
	v_sub_f32_e32 v41, v41, v70
	v_add_f32_e32 v31, v31, v44
	v_fma_f32 v28, v50, v38, -v37
	v_fma_f32 v30, v50, v30, -v40
	v_sub_f32_e32 v31, v31, v57
	v_cvt_pk_bf16_f32 v28, v28, v30
	v_fma_f32 v30, v50, v41, -v39
	v_fma_f32 v29, v50, v29, -v42
	v_cvt_pk_bf16_f32 v29, v30, v29
	v_fma_f32 v30, v50, v31, -v44
	v_fma_f32 v31, v50, v43, -v46
	v_cvt_pk_bf16_f32 v30, v30, v31
	v_fma_f32 v31, v50, v47, -v48
	v_fma_f32 v37, v50, v45, -v49
	v_cvt_pk_bf16_f32 v31, v31, v37
	s_mov_b64 s[16:17], 0

.LBB0_978:
	v_max_i32_e32 v40, 1, v36
	v_max_i32_e32 v41, 0, v36
	v_or_b32_e32 v39, 1, v36
	v_or_b32_e32 v38, 2, v36
	v_or_b32_e32 v37, 3, v36
	s_andn2_b64 vcc, exec, s[16:17]
	v_cmp_lt_i32_e64 s[22:23], 0, v36
	v_cmp_lt_i32_e64 s[20:21], -1, v36
	v_cmp_lt_i32_e64 s[18:19], -2, v36
	v_cmp_lt_i32_e64 s[16:17], -3, v36
	v_add3_u32 v44, s4, -1, v40
	v_add_u32_e32 v43, s4, v41
	v_max_i32_e32 v42, 0, v39
	v_max_i32_e32 v41, 0, v38
	v_max_i32_e32 v40, 0, v37
	s_cbranch_vccnz .LBB0_980
	v_max_i32_e32 v112, 14, v36
	v_add3_u32 v112, s4, -14, v112
	v_mad_i64_i32 v[112:113], s[0:1], v112, s27, v[34:35]
	global_load_dwordx4 v[112:115], v[112:113], off
	v_max_i32_e32 v116, 13, v36
	v_add3_u32 v116, s4, -13, v116
	v_mad_i64_i32 v[116:117], s[0:1], v116, s27, v[34:35]
	global_load_dwordx4 v[116:119], v[116:117], off
	v_max_i32_e32 v120, 12, v36
	v_add3_u32 v120, s4, -12, v120
	v_mad_i64_i32 v[120:121], s[0:1], v120, s27, v[34:35]
	global_load_dwordx4 v[120:123], v[120:121], off
	v_max_i32_e32 v124, 11, v36
	v_add3_u32 v124, s4, -11, v124
	v_mad_i64_i32 v[124:125], s[0:1], v124, s27, v[34:35]
	global_load_dwordx4 v[124:127], v[124:125], off
	v_max_i32_e32 v128, 10, v36
	v_add3_u32 v128, s4, -10, v128
	v_mad_i64_i32 v[128:129], s[0:1], v128, s27, v[34:35]
	global_load_dwordx4 v[128:131], v[128:129], off
	v_max_i32_e32 v132, 9, v36
	v_add3_u32 v132, s4, -9, v132
	v_mad_i64_i32 v[132:133], s[0:1], v132, s27, v[34:35]
	global_load_dwordx4 v[132:135], v[132:133], off
	v_max_i32_e32 v136, 8, v36
	v_add3_u32 v136, s4, -8, v136
	v_mad_i64_i32 v[136:137], s[0:1], v136, s27, v[34:35]
	global_load_dwordx4 v[136:139], v[136:137], off
	v_max_i32_e32 v176, 7, v36
	v_add3_u32 v176, s4, -7, v176
	v_mad_i64_i32 v[176:177], s[0:1], v176, s27, v[34:35]
	global_load_dwordx4 v[176:179], v[176:177], off
	v_max_i32_e32 v180, 6, v36
	v_add3_u32 v180, s4, -6, v180
	v_mad_i64_i32 v[180:181], s[0:1], v180, s27, v[34:35]
	global_load_dwordx4 v[180:183], v[180:181], off
	v_max_i32_e32 v184, 5, v36
	v_add3_u32 v184, s4, -5, v184
	v_mad_i64_i32 v[184:185], s[0:1], v184, s27, v[34:35]
	global_load_dwordx4 v[184:187], v[184:185], off
	v_max_i32_e32 v188, 4, v36
	v_add3_u32 v188, s4, -4, v188
	v_mad_i64_i32 v[188:189], s[0:1], v188, s27, v[34:35]
	global_load_dwordx4 v[188:191], v[188:189], off
	v_max_i32_e32 v192, 3, v36
	v_add3_u32 v192, s4, -3, v192
	v_mad_i64_i32 v[192:193], s[0:1], v192, s27, v[34:35]
	global_load_dwordx4 v[192:195], v[192:193], off
	v_max_i32_e32 v196, 2, v36
	v_add3_u32 v196, s4, -2, v196
	v_mad_i64_i32 v[196:197], s[0:1], v196, s27, v[34:35]
	global_load_dwordx4 v[196:199], v[196:197], off
	v_mad_i64_i32 v[200:201], s[0:1], v44, s27, v[34:35]
	global_load_dwordx4 v[200:203], v[200:201], off
	v_mad_i64_i32 v[218:219], s[0:1], v43, s27, v[34:35]
	global_load_dwordx4 v[218:221], v[218:219], off
	v_max_i32_e32 v0, 15, v36
	v_add3_u32 v0, s4, -15, v0
	v_mad_i64_i32 v[0:1], s[0:1], v0, s27, v[34:35]
	global_load_dwordx4 v[0:3], v[0:1], off
	v_add_u32_e32 v4, s4, v42
	v_cmp_lt_i32_e32 vcc, 14, v36
	v_mad_i64_i32 v[4:5], s[0:1], v4, s27, v[34:35]
	global_load_dwordx4 v[4:7], v[4:5], off
	v_add_u32_e32 v8, s4, v41
	v_mad_i64_i32 v[8:9], s[0:1], v8, s27, v[34:35]
	v_add_u32_e32 v24, s4, v40
	v_mad_i64_i32 v[24:25], s[0:1], v24, s27, v[34:35]
	global_load_dwordx4 v[8:11], v[8:9], off
	s_waitcnt vmcnt(2)
	v_cndmask_b32_e32 v16, 0, v0, vcc
	v_max_i32_e32 v0, 14, v36
	v_add3_u32 v0, s4, -14, v0
	v_cndmask_b32_e32 v14, 0, v1, vcc
	v_mad_i64_i32 v[0:1], s[0:1], v0, s27, v[34:35]
	v_cndmask_b32_e32 v12, 0, v3, vcc
	v_cndmask_b32_e32 v13, 0, v2, vcc
	v_mov_b32_e32 v0, v112
	v_mov_b32_e32 v1, v113
	v_mov_b32_e32 v2, v114
	v_mov_b32_e32 v3, v115
	v_cmp_lt_i32_e32 vcc, 13, v36
	v_and_b32_e32 v94, 0xffff0000, v14
	v_lshlrev_b32_e32 v92, 16, v16
	v_and_b32_e32 v16, 0xffff0000, v16
	v_lshlrev_b32_e32 v93, 16, v14
	v_add_f32_e32 v14, 0, v94
	v_lshlrev_b32_e32 v95, 16, v13
	v_add_f32_e32 v90, 0, v16
	v_add_f32_e32 v91, 0, v93
	v_add_f32_e32 v96, 0, v95
	v_and_b32_e32 v97, 0xffff0000, v13
	v_add_f32_e32 v13, 0, v97
	v_lshlrev_b32_e32 v98, 16, v12
	v_add_f32_e32 v89, 0, v92
	v_add_f32_e32 v99, 0, v98
	v_and_b32_e32 v100, 0xffff0000, v12
	v_add_f32_e32 v12, 0, v100
	s_waitcnt vmcnt(1)
	v_cndmask_b32_e64 v4, 0, v4, s[18:19]
	v_cndmask_b32_e64 v5, 0, v5, s[18:19]
	v_cndmask_b32_e64 v6, 0, v6, s[18:19]
	v_cndmask_b32_e64 v7, 0, v7, s[18:19]
	s_waitcnt vmcnt(0)
	v_cndmask_b32_e64 v8, 0, v8, s[16:17]
	v_cndmask_b32_e64 v9, 0, v9, s[16:17]
	v_cndmask_b32_e64 v10, 0, v10, s[16:17]
	v_cndmask_b32_e64 v11, 0, v11, s[16:17]
	global_load_dwordx4 v[24:27], v[24:25], off
	s_waitcnt vmcnt(1)
	v_cndmask_b32_e32 v19, 0, v0, vcc
	v_max_i32_e32 v0, 13, v36
	v_add3_u32 v0, s4, -13, v0
	v_cndmask_b32_e32 v18, 0, v1, vcc
	v_mad_i64_i32 v[0:1], s[0:1], v0, s27, v[34:35]
	v_cndmask_b32_e32 v15, 0, v3, vcc
	v_cndmask_b32_e32 v17, 0, v2, vcc
	v_mov_b32_e32 v0, v116
	v_mov_b32_e32 v1, v117
	v_mov_b32_e32 v2, v118
	v_mov_b32_e32 v3, v119
	v_cmp_lt_i32_e32 vcc, 12, v36
	v_and_b32_e32 v104, 0xffff0000, v18
	v_and_b32_e32 v102, 0xffff0000, v19
	v_lshlrev_b32_e32 v103, 16, v18
	v_add_f32_e32 v14, v14, v104
	v_lshlrev_b32_e32 v105, 16, v17
	v_lshlrev_b32_e32 v101, 16, v19
	v_add_f32_e32 v19, v90, v102
	v_add_f32_e32 v90, v91, v103
	v_add_f32_e32 v18, v96, v105
	v_and_b32_e32 v96, 0xffff0000, v17
	v_add_f32_e32 v13, v13, v96
	v_lshlrev_b32_e32 v106, 16, v15
	v_add_f32_e32 v89, v89, v101
	v_add_f32_e32 v17, v99, v106
	v_and_b32_e32 v99, 0xffff0000, v15
	v_add_f32_e32 v12, v12, v99
	s_waitcnt vmcnt(0)
	v_cndmask_b32_e32 v23, 0, v0, vcc
	v_max_i32_e32 v0, 12, v36
	v_add3_u32 v0, s4, -12, v0
	v_cndmask_b32_e32 v22, 0, v1, vcc
	v_mad_i64_i32 v[0:1], s[0:1], v0, s27, v[34:35]
	v_cndmask_b32_e32 v20, 0, v3, vcc
	v_cndmask_b32_e32 v21, 0, v2, vcc
	v_mov_b32_e32 v0, v120
	v_mov_b32_e32 v1, v121
	v_mov_b32_e32 v2, v122
	v_mov_b32_e32 v3, v123
	v_cmp_lt_i32_e32 vcc, 11, v36
	v_and_b32_e32 v110, 0xffff0000, v22
	v_add_f32_e32 v14, v14, v110
	v_lshlrev_b32_e32 v111, 16, v21
	v_and_b32_e32 v91, 0xffff0000, v21
	v_lshlrev_b32_e32 v109, 16, v22
	v_add_f32_e32 v18, v18, v111
	v_lshlrev_b32_e32 v107, 16, v23
	v_and_b32_e32 v108, 0xffff0000, v23
	v_add_f32_e32 v23, v90, v109
	v_add_f32_e32 v13, v13, v91
	v_lshlrev_b32_e32 v90, 16, v20
	v_add_f32_e32 v15, v89, v107
	v_add_f32_e32 v17, v17, v90
	v_and_b32_e32 v89, 0xffff0000, v20
	v_add_f32_e32 v12, v12, v89
	v_add_f32_e32 v19, v19, v108
	s_waitcnt vmcnt(0)
	v_cndmask_b32_e32 v31, 0, v0, vcc
	v_max_i32_e32 v0, 11, v36
	v_add3_u32 v0, s4, -11, v0
	v_cndmask_b32_e32 v30, 0, v1, vcc
	v_mad_i64_i32 v[0:1], s[0:1], v0, s27, v[34:35]
	v_cndmask_b32_e32 v28, 0, v3, vcc
	v_cndmask_b32_e32 v29, 0, v2, vcc
	v_mov_b32_e32 v0, v124
	v_mov_b32_e32 v1, v125
	v_mov_b32_e32 v2, v126
	v_mov_b32_e32 v3, v127
	v_cmp_lt_i32_e32 vcc, 10, v36
	v_and_b32_e32 v21, 0xffff0000, v30
	v_add_f32_e32 v14, v14, v21
	v_lshlrev_b32_e32 v21, 16, v29
	v_add_f32_e32 v18, v18, v21
	v_and_b32_e32 v21, 0xffff0000, v29
	v_add_f32_e32 v13, v13, v21
	v_lshlrev_b32_e32 v21, 16, v28
	v_lshlrev_b32_e32 v20, 16, v31
	v_add_f32_e32 v17, v17, v21
	v_and_b32_e32 v21, 0xffff0000, v28
	v_add_f32_e32 v15, v15, v20
	v_and_b32_e32 v20, 0xffff0000, v31
	v_add_f32_e32 v12, v12, v21
	v_add_f32_e32 v19, v19, v20
	v_lshlrev_b32_e32 v20, 16, v30
	v_add_f32_e32 v20, v23, v20
	s_waitcnt vmcnt(0)
	v_cndmask_b32_e32 v48, 0, v0, vcc
	v_max_i32_e32 v0, 10, v36
	v_add3_u32 v0, s4, -10, v0
	v_cndmask_b32_e32 v47, 0, v1, vcc
	v_mad_i64_i32 v[0:1], s[0:1], v0, s27, v[34:35]
	v_cndmask_b32_e32 v45, 0, v3, vcc
	v_cndmask_b32_e32 v46, 0, v2, vcc
	v_mov_b32_e32 v0, v128
	v_mov_b32_e32 v1, v129
	v_mov_b32_e32 v2, v130
	v_mov_b32_e32 v3, v131
	v_cmp_lt_i32_e32 vcc, 9, v36
	v_lshlrev_b32_e32 v21, 16, v48
	v_add_f32_e32 v15, v15, v21
	v_and_b32_e32 v21, 0xffff0000, v48
	v_add_f32_e32 v19, v19, v21
	v_lshlrev_b32_e32 v21, 16, v47
	v_add_f32_e32 v20, v20, v21
	v_and_b32_e32 v21, 0xffff0000, v47
	v_add_f32_e32 v14, v14, v21
	v_lshlrev_b32_e32 v21, 16, v46
	v_add_f32_e32 v18, v18, v21
	v_and_b32_e32 v21, 0xffff0000, v46
	v_add_f32_e32 v13, v13, v21
	v_lshlrev_b32_e32 v21, 16, v45
	v_add_f32_e32 v17, v17, v21
	v_and_b32_e32 v21, 0xffff0000, v45
	v_add_f32_e32 v12, v12, v21
	s_waitcnt vmcnt(0)
	v_cndmask_b32_e32 v52, 0, v0, vcc
	v_max_i32_e32 v0, 9, v36
	v_add3_u32 v0, s4, -9, v0
	v_cndmask_b32_e32 v51, 0, v1, vcc
	v_mad_i64_i32 v[0:1], s[0:1], v0, s27, v[34:35]
	v_cndmask_b32_e32 v49, 0, v3, vcc
	v_cndmask_b32_e32 v50, 0, v2, vcc
	v_mov_b32_e32 v0, v132
	v_mov_b32_e32 v1, v133
	v_mov_b32_e32 v2, v134
	v_mov_b32_e32 v3, v135
	v_cmp_lt_i32_e32 vcc, 8, v36
	v_lshlrev_b32_e32 v21, 16, v52
	v_add_f32_e32 v15, v15, v21
	v_and_b32_e32 v21, 0xffff0000, v52
	v_add_f32_e32 v19, v19, v21
	v_lshlrev_b32_e32 v21, 16, v51
	v_add_f32_e32 v20, v20, v21
	v_and_b32_e32 v21, 0xffff0000, v51
	v_add_f32_e32 v14, v14, v21
	v_lshlrev_b32_e32 v21, 16, v50
	v_add_f32_e32 v18, v18, v21
	v_and_b32_e32 v21, 0xffff0000, v50
	v_add_f32_e32 v13, v13, v21
	v_lshlrev_b32_e32 v21, 16, v49
	v_add_f32_e32 v17, v17, v21
	v_and_b32_e32 v21, 0xffff0000, v49
	v_add_f32_e32 v12, v12, v21
	s_waitcnt vmcnt(0)
	v_cndmask_b32_e32 v56, 0, v0, vcc
	v_max_i32_e32 v0, 8, v36
	v_add3_u32 v0, s4, -8, v0
	v_cndmask_b32_e32 v55, 0, v1, vcc
	v_mad_i64_i32 v[0:1], s[0:1], v0, s27, v[34:35]
	v_cndmask_b32_e32 v53, 0, v3, vcc
	v_cndmask_b32_e32 v54, 0, v2, vcc
	v_mov_b32_e32 v0, v136
	v_mov_b32_e32 v1, v137
	v_mov_b32_e32 v2, v138
	v_mov_b32_e32 v3, v139
	v_cmp_lt_i32_e32 vcc, 7, v36
	v_lshlrev_b32_e32 v21, 16, v56
	v_add_f32_e32 v15, v15, v21
	v_and_b32_e32 v21, 0xffff0000, v56
	v_add_f32_e32 v19, v19, v21
	v_lshlrev_b32_e32 v21, 16, v55
	v_add_f32_e32 v20, v20, v21
	v_and_b32_e32 v21, 0xffff0000, v55
	v_add_f32_e32 v14, v14, v21
	v_lshlrev_b32_e32 v21, 16, v54
	v_add_f32_e32 v18, v18, v21
	v_and_b32_e32 v21, 0xffff0000, v54
	v_add_f32_e32 v13, v13, v21
	v_lshlrev_b32_e32 v21, 16, v53
	v_add_f32_e32 v17, v17, v21
	v_and_b32_e32 v21, 0xffff0000, v53
	v_add_f32_e32 v12, v12, v21
	s_waitcnt vmcnt(0)
	v_cndmask_b32_e32 v60, 0, v0, vcc
	v_max_i32_e32 v0, 7, v36
	v_add3_u32 v0, s4, -7, v0
	v_cndmask_b32_e32 v59, 0, v1, vcc
	v_mad_i64_i32 v[0:1], s[0:1], v0, s27, v[34:35]
	v_cndmask_b32_e32 v57, 0, v3, vcc
	v_cndmask_b32_e32 v58, 0, v2, vcc
	v_mov_b32_e32 v0, v176
	v_mov_b32_e32 v1, v177
	v_mov_b32_e32 v2, v178
	v_mov_b32_e32 v3, v179
	v_cmp_lt_i32_e32 vcc, 6, v36
	v_lshlrev_b32_e32 v21, 16, v60
	v_add_f32_e32 v15, v15, v21
	v_and_b32_e32 v21, 0xffff0000, v60
	v_add_f32_e32 v19, v19, v21
	v_lshlrev_b32_e32 v21, 16, v59
	v_add_f32_e32 v20, v20, v21
	v_and_b32_e32 v21, 0xffff0000, v59
	v_add_f32_e32 v14, v14, v21
	v_lshlrev_b32_e32 v21, 16, v58
	v_add_f32_e32 v18, v18, v21
	v_and_b32_e32 v21, 0xffff0000, v58
	v_add_f32_e32 v13, v13, v21
	v_lshlrev_b32_e32 v21, 16, v57
	v_add_f32_e32 v17, v17, v21
	v_and_b32_e32 v21, 0xffff0000, v57
	v_add_f32_e32 v12, v12, v21
	s_waitcnt vmcnt(0)
	v_cndmask_b32_e32 v64, 0, v0, vcc
	v_max_i32_e32 v0, 6, v36
	v_add3_u32 v0, s4, -6, v0
	v_cndmask_b32_e32 v63, 0, v1, vcc
	v_mad_i64_i32 v[0:1], s[0:1], v0, s27, v[34:35]
	v_cndmask_b32_e32 v61, 0, v3, vcc
	v_cndmask_b32_e32 v62, 0, v2, vcc
	v_mov_b32_e32 v0, v180
	v_mov_b32_e32 v1, v181
	v_mov_b32_e32 v2, v182
	v_mov_b32_e32 v3, v183
	v_cmp_lt_i32_e32 vcc, 5, v36
	v_lshlrev_b32_e32 v21, 16, v64
	v_add_f32_e32 v15, v15, v21
	v_and_b32_e32 v21, 0xffff0000, v64
	v_add_f32_e32 v19, v19, v21
	v_lshlrev_b32_e32 v21, 16, v63
	v_add_f32_e32 v20, v20, v21
	v_and_b32_e32 v21, 0xffff0000, v63
	v_add_f32_e32 v14, v14, v21
	v_lshlrev_b32_e32 v21, 16, v62
	v_add_f32_e32 v18, v18, v21
	v_and_b32_e32 v21, 0xffff0000, v62
	v_add_f32_e32 v13, v13, v21
	v_lshlrev_b32_e32 v21, 16, v61
	v_add_f32_e32 v17, v17, v21
	v_and_b32_e32 v21, 0xffff0000, v61
	v_add_f32_e32 v12, v12, v21
	s_waitcnt vmcnt(0)
	v_cndmask_b32_e32 v68, 0, v0, vcc
	v_max_i32_e32 v0, 5, v36
	v_add3_u32 v0, s4, -5, v0
	v_cndmask_b32_e32 v67, 0, v1, vcc
	v_mad_i64_i32 v[0:1], s[0:1], v0, s27, v[34:35]
	v_cndmask_b32_e32 v65, 0, v3, vcc
	v_cndmask_b32_e32 v66, 0, v2, vcc
	v_mov_b32_e32 v0, v184
	v_mov_b32_e32 v1, v185
	v_mov_b32_e32 v2, v186
	v_mov_b32_e32 v3, v187
	v_cmp_lt_i32_e32 vcc, 4, v36
	v_lshlrev_b32_e32 v21, 16, v68
	v_add_f32_e32 v15, v15, v21
	v_and_b32_e32 v21, 0xffff0000, v68
	v_add_f32_e32 v19, v19, v21
	v_lshlrev_b32_e32 v21, 16, v67
	v_add_f32_e32 v20, v20, v21
	v_and_b32_e32 v21, 0xffff0000, v67
	v_add_f32_e32 v14, v14, v21
	v_lshlrev_b32_e32 v21, 16, v66
	v_add_f32_e32 v18, v18, v21
	v_and_b32_e32 v21, 0xffff0000, v66
	v_add_f32_e32 v13, v13, v21
	v_lshlrev_b32_e32 v21, 16, v65
	v_add_f32_e32 v17, v17, v21
	v_and_b32_e32 v21, 0xffff0000, v65
	v_add_f32_e32 v12, v12, v21
	s_waitcnt vmcnt(0)
	v_cndmask_b32_e32 v72, 0, v0, vcc
	v_max_i32_e32 v0, 4, v36
	v_add3_u32 v0, s4, -4, v0
	v_cndmask_b32_e32 v71, 0, v1, vcc
	v_mad_i64_i32 v[0:1], s[0:1], v0, s27, v[34:35]
	v_cndmask_b32_e32 v69, 0, v3, vcc
	v_cndmask_b32_e32 v70, 0, v2, vcc
	v_mov_b32_e32 v0, v188
	v_mov_b32_e32 v1, v189
	v_mov_b32_e32 v2, v190
	v_mov_b32_e32 v3, v191
	v_cmp_lt_i32_e32 vcc, 3, v36
	v_lshlrev_b32_e32 v21, 16, v72
	v_add_f32_e32 v15, v15, v21
	v_and_b32_e32 v21, 0xffff0000, v72
	v_add_f32_e32 v19, v19, v21
	v_lshlrev_b32_e32 v21, 16, v71
	v_add_f32_e32 v20, v20, v21
	v_and_b32_e32 v21, 0xffff0000, v71
	v_add_f32_e32 v14, v14, v21
	v_lshlrev_b32_e32 v21, 16, v70
	v_add_f32_e32 v18, v18, v21
	v_and_b32_e32 v21, 0xffff0000, v70
	v_add_f32_e32 v13, v13, v21
	v_lshlrev_b32_e32 v21, 16, v69
	v_add_f32_e32 v17, v17, v21
	v_and_b32_e32 v21, 0xffff0000, v69
	v_add_f32_e32 v12, v12, v21
	s_waitcnt vmcnt(0)
	v_cndmask_b32_e32 v76, 0, v0, vcc
	v_max_i32_e32 v0, 3, v36
	v_add3_u32 v0, s4, -3, v0
	v_cndmask_b32_e32 v75, 0, v1, vcc
	v_mad_i64_i32 v[0:1], s[0:1], v0, s27, v[34:35]
	v_cndmask_b32_e32 v73, 0, v3, vcc
	v_cndmask_b32_e32 v74, 0, v2, vcc
	v_mov_b32_e32 v0, v192
	v_mov_b32_e32 v1, v193
	v_mov_b32_e32 v2, v194
	v_mov_b32_e32 v3, v195
	v_cmp_lt_i32_e32 vcc, 2, v36
	v_lshlrev_b32_e32 v21, 16, v76
	v_add_f32_e32 v15, v15, v21
	v_and_b32_e32 v21, 0xffff0000, v76
	v_add_f32_e32 v19, v19, v21
	v_lshlrev_b32_e32 v21, 16, v75
	v_add_f32_e32 v20, v20, v21
	v_and_b32_e32 v21, 0xffff0000, v75
	v_add_f32_e32 v14, v14, v21
	v_lshlrev_b32_e32 v21, 16, v74
	v_add_f32_e32 v18, v18, v21
	v_and_b32_e32 v21, 0xffff0000, v74
	v_add_f32_e32 v13, v13, v21
	v_lshlrev_b32_e32 v21, 16, v73
	v_add_f32_e32 v17, v17, v21
	v_and_b32_e32 v21, 0xffff0000, v73
	v_add_f32_e32 v12, v12, v21
	s_waitcnt vmcnt(0)
	v_cndmask_b32_e32 v80, 0, v0, vcc
	v_max_i32_e32 v0, 2, v36
	v_add3_u32 v0, s4, -2, v0
	v_cndmask_b32_e32 v79, 0, v1, vcc
	v_mad_i64_i32 v[0:1], s[0:1], v0, s27, v[34:35]
	v_cndmask_b32_e32 v77, 0, v3, vcc
	v_cndmask_b32_e32 v78, 0, v2, vcc
	v_mov_b32_e32 v0, v196
	v_mov_b32_e32 v1, v197
	v_mov_b32_e32 v2, v198
	v_mov_b32_e32 v3, v199
	v_cmp_lt_i32_e32 vcc, 1, v36
	v_lshlrev_b32_e32 v21, 16, v80
	v_add_f32_e32 v15, v15, v21
	v_and_b32_e32 v21, 0xffff0000, v80
	v_add_f32_e32 v19, v19, v21
	v_lshlrev_b32_e32 v21, 16, v79
	v_add_f32_e32 v20, v20, v21
	v_and_b32_e32 v21, 0xffff0000, v79
	v_add_f32_e32 v14, v14, v21
	v_lshlrev_b32_e32 v21, 16, v78
	v_add_f32_e32 v18, v18, v21
	v_and_b32_e32 v21, 0xffff0000, v78
	v_add_f32_e32 v13, v13, v21
	v_lshlrev_b32_e32 v21, 16, v77
	v_add_f32_e32 v17, v17, v21
	v_and_b32_e32 v21, 0xffff0000, v77
	v_add_f32_e32 v12, v12, v21
	s_waitcnt vmcnt(0)
	v_cndmask_b32_e32 v83, 0, v1, vcc
	v_cndmask_b32_e32 v85, 0, v0, vcc
	v_mad_i64_i32 v[0:1], s[0:1], v44, s27, v[34:35]
	v_cndmask_b32_e32 v81, 0, v3, vcc
	v_cndmask_b32_e32 v82, 0, v2, vcc
	v_mov_b32_e32 v0, v200
	v_mov_b32_e32 v1, v201
	v_mov_b32_e32 v2, v202
	v_mov_b32_e32 v3, v203
	v_lshlrev_b32_e32 v21, 16, v85
	v_add_f32_e32 v15, v15, v21
	v_and_b32_e32 v21, 0xffff0000, v85
	v_add_f32_e32 v19, v19, v21
	v_lshlrev_b32_e32 v21, 16, v83
	v_add_f32_e32 v20, v20, v21
	v_and_b32_e32 v21, 0xffff0000, v83
	v_add_f32_e32 v14, v14, v21
	v_lshlrev_b32_e32 v21, 16, v82
	v_add_f32_e32 v18, v18, v21
	v_and_b32_e32 v21, 0xffff0000, v82
	v_add_f32_e32 v13, v13, v21
	v_lshlrev_b32_e32 v21, 16, v81
	v_add_f32_e32 v17, v17, v21
	v_and_b32_e32 v21, 0xffff0000, v81
	v_add_f32_e32 v12, v12, v21
	s_waitcnt vmcnt(0)
	v_cndmask_b32_e64 v87, 0, v1, s[22:23]
	v_cndmask_b32_e64 v88, 0, v0, s[22:23]
	v_mad_i64_i32 v[0:1], s[0:1], v43, s27, v[34:35]
	v_cndmask_b32_e64 v84, 0, v3, s[22:23]
	v_cndmask_b32_e64 v86, 0, v2, s[22:23]
	v_mov_b32_e32 v0, v218
	v_mov_b32_e32 v1, v219
	v_mov_b32_e32 v2, v220
	v_mov_b32_e32 v3, v221
	v_lshlrev_b32_e32 v21, 16, v88
	v_add_f32_e32 v15, v15, v21
	v_and_b32_e32 v21, 0xffff0000, v88
	v_add_f32_e32 v19, v19, v21
	v_lshlrev_b32_e32 v21, 16, v87
	v_add_f32_e32 v20, v20, v21
	v_and_b32_e32 v21, 0xffff0000, v87
	v_add_f32_e32 v14, v14, v21
	v_lshlrev_b32_e32 v21, 16, v86
	v_add_f32_e32 v18, v18, v21
	v_and_b32_e32 v21, 0xffff0000, v86
	v_add_f32_e32 v13, v13, v21
	v_lshlrev_b32_e32 v21, 16, v84
	v_add_f32_e32 v17, v17, v21
	v_and_b32_e32 v21, 0xffff0000, v84
	v_add_f32_e32 v12, v12, v21
	s_waitcnt vmcnt(0)
	v_cndmask_b32_e64 v3, 0, v3, s[20:21]
	v_and_b32_e32 v46, 0xffff0000, v3
	v_add_f32_e32 v47, v12, v46
	v_min_i32_e32 v12, 15, v36
	v_add_u32_e32 v12, 1, v12
	v_cvt_f32_i32_e32 v12, v12
	v_cndmask_b32_e64 v2, 0, v2, s[20:21]
	v_and_b32_e32 v30, 0xffff0000, v2
	v_add_f32_e32 v31, v13, v30
	v_div_scale_f32 v13, s[0:1], v12, v12, 1.0
	v_rcp_f32_e32 v48, v13
	v_cndmask_b32_e64 v0, 0, v0, s[20:21]
	v_lshlrev_b32_e32 v21, 16, v0
	v_cndmask_b32_e64 v1, 0, v1, s[20:21]
	v_fma_f32 v49, -v13, v48, 1.0
	v_fmac_f32_e32 v48, v49, v48
	v_div_scale_f32 v49, vcc, 1.0, v12, 1.0
	v_mul_f32_e32 v50, v49, v48
	v_fma_f32 v51, -v13, v50, v49
	v_fmac_f32_e32 v50, v51, v48
	v_fma_f32 v13, -v13, v50, v49
	v_div_fmas_f32 v13, v13, v48, v50
	v_add_f32_e32 v22, v15, v21
	v_and_b32_e32 v15, 0xffff0000, v0
	v_div_fixup_f32 v12, v13, v12, 1.0
	v_add_f32_e32 v19, v19, v15
	v_lshlrev_b32_e32 v23, 16, v1
	v_cndmask_b32_e64 v48, v12, v213, s[14:15]
	v_add_f32_e32 v20, v20, v23
	v_fma_f32 v12, v48, v22, -v21
	v_fma_f32 v13, v48, v19, -v15
	v_and_b32_e32 v28, 0xffff0000, v1
	v_cvt_pk_bf16_f32 v12, v12, v13
	v_fma_f32 v13, v48, v20, -v23
	v_and_b32_e32 v23, 0xffff0000, v4
	v_add_f32_e32 v29, v14, v28
	v_lshlrev_b32_e32 v14, 16, v2
	v_add_f32_e32 v19, v19, v23
	v_add_f32_e32 v18, v18, v14
	v_lshlrev_b32_e32 v45, 16, v3
	v_fma_f32 v15, v48, v29, -v28
	v_sub_f32_e32 v28, v19, v16
	v_lshlrev_b32_e32 v19, 16, v5
	v_add_f32_e32 v17, v17, v45
	v_cvt_pk_bf16_f32 v13, v13, v15
	v_fma_f32 v14, v48, v18, -v14
	v_fma_f32 v15, v48, v31, -v30
	v_add_f32_e32 v16, v20, v19
	v_and_b32_e32 v30, 0xffff0000, v5
	v_cvt_pk_bf16_f32 v14, v14, v15
	v_fma_f32 v15, v48, v17, -v45
	v_sub_f32_e32 v20, v16, v93
	v_add_f32_e32 v16, v29, v30
	v_lshlrev_b32_e32 v45, 16, v6
	v_sub_f32_e32 v29, v16, v94
	v_add_f32_e32 v16, v18, v45
	v_and_b32_e32 v18, 0xffff0000, v6
	v_fma_f32 v21, v48, v47, -v46
	v_sub_f32_e32 v46, v16, v95
	v_add_f32_e32 v16, v31, v18
	v_lshlrev_b32_e32 v48, 16, v7
	v_sub_f32_e32 v31, v16, v97
	v_add_f32_e32 v16, v17, v48
	v_and_b32_e32 v50, 0xffff0000, v7
	v_sub_f32_e32 v49, v16, v98
	v_add_f32_e32 v16, v47, v50
	v_sub_f32_e32 v47, v16, v100
	v_min_i32_e32 v16, 15, v39
	v_add_u32_e32 v16, 1, v16
	v_cvt_f32_i32_e32 v16, v16
	v_cvt_pk_bf16_f32 v15, v15, v21
	v_lshlrev_b32_e32 v21, 16, v4
	v_add_f32_e32 v22, v22, v21
	v_div_scale_f32 v17, s[0:1], v16, v16, 1.0
	v_rcp_f32_e32 v51, v17
	v_sub_f32_e32 v22, v22, v92
	v_fma_f32 v52, -v17, v51, 1.0
	v_fmac_f32_e32 v51, v52, v51
	v_div_scale_f32 v52, vcc, 1.0, v16, 1.0
	v_mul_f32_e32 v53, v52, v51
	v_fma_f32 v54, -v17, v53, v52
	v_fmac_f32_e32 v53, v54, v51
	v_fma_f32 v17, -v17, v53, v52
	v_div_fmas_f32 v17, v17, v51, v53
	v_div_fixup_f32 v16, v17, v16, 1.0
	v_cndmask_b32_e64 v51, v16, v213, s[14:15]
	v_fma_f32 v16, v51, v22, -v21
	v_fma_f32 v17, v51, v28, -v23
	v_cvt_pk_bf16_f32 v16, v16, v17
	v_fma_f32 v17, v51, v20, -v19
	v_fma_f32 v19, v51, v29, -v30
	v_cvt_pk_bf16_f32 v17, v17, v19
	v_fma_f32 v19, v51, v46, -v45
	v_fma_f32 v18, v51, v31, -v18
	v_cvt_pk_bf16_f32 v18, v19, v18
	v_fma_f32 v19, v51, v49, -v48
	v_fma_f32 v21, v51, v47, -v50
	v_cvt_pk_bf16_f32 v19, v19, v21
	v_lshlrev_b32_e32 v21, 16, v8
	v_add_f32_e32 v22, v22, v21
	v_sub_f32_e32 v30, v22, v101
	v_and_b32_e32 v22, 0xffff0000, v8
	v_add_f32_e32 v23, v28, v22
	v_sub_f32_e32 v28, v23, v102
	v_lshlrev_b32_e32 v23, 16, v9
	v_add_f32_e32 v20, v20, v23
	v_and_b32_e32 v48, 0xffff0000, v9
	v_sub_f32_e32 v45, v20, v103
	v_add_f32_e32 v20, v29, v48
	v_lshlrev_b32_e32 v50, 16, v10
	v_sub_f32_e32 v29, v20, v104
	v_add_f32_e32 v20, v46, v50
	v_and_b32_e32 v51, 0xffff0000, v10
	v_sub_f32_e32 v46, v20, v105
	v_add_f32_e32 v20, v31, v51
	v_lshlrev_b32_e32 v52, 16, v11
	v_sub_f32_e32 v31, v20, v96
	v_add_f32_e32 v20, v49, v52
	v_and_b32_e32 v53, 0xffff0000, v11
	v_sub_f32_e32 v49, v20, v106
	v_add_f32_e32 v20, v47, v53
	v_sub_f32_e32 v47, v20, v99
	v_min_i32_e32 v20, 15, v38
	v_add_u32_e32 v20, 1, v20
	v_cvt_f32_i32_e32 v20, v20
	v_div_scale_f32 v54, s[0:1], v20, v20, 1.0
	v_rcp_f32_e32 v55, v54
	s_nop 0
	v_fma_f32 v56, -v54, v55, 1.0
	v_fmac_f32_e32 v55, v56, v55
	v_div_scale_f32 v56, vcc, 1.0, v20, 1.0
	v_mul_f32_e32 v57, v56, v55
	v_fma_f32 v58, -v54, v57, v56
	v_fmac_f32_e32 v57, v58, v55
	v_fma_f32 v54, -v54, v57, v56
	v_div_fmas_f32 v54, v54, v55, v57
	v_min_i32_e32 v57, 15, v37
	v_add_u32_e32 v57, 1, v57
	v_cvt_f32_i32_e32 v57, v57
	v_div_fixup_f32 v20, v54, v20, 1.0
	v_cmp_lt_i32_e32 vcc, -4, v36
	v_cndmask_b32_e64 v54, v20, v213, s[14:15]
	v_div_scale_f32 v58, s[0:1], v57, v57, 1.0
	v_rcp_f32_e32 v59, v58
	v_cndmask_b32_e32 v27, 0, v27, vcc
	v_cndmask_b32_e32 v26, 0, v26, vcc
	v_cndmask_b32_e32 v25, 0, v25, vcc
	v_fma_f32 v60, -v58, v59, 1.0
	v_cndmask_b32_e32 v24, 0, v24, vcc
	v_fmac_f32_e32 v59, v60, v59
	v_div_scale_f32 v60, vcc, 1.0, v57, 1.0
	v_fma_f32 v20, v54, v30, -v21
	v_fma_f32 v21, v54, v28, -v22
	v_mul_f32_e32 v61, v60, v59
	v_cvt_pk_bf16_f32 v20, v20, v21
	v_fma_f32 v21, v54, v45, -v23
	v_fma_f32 v22, v54, v29, -v48
	v_fma_f32 v62, -v58, v61, v60
	v_cvt_pk_bf16_f32 v21, v21, v22
	v_fma_f32 v22, v54, v46, -v50
	v_fma_f32 v23, v54, v31, -v51
	v_fmac_f32_e32 v61, v62, v59
	v_cvt_pk_bf16_f32 v22, v22, v23
	v_fma_f32 v23, v54, v49, -v52
	v_fma_f32 v48, v54, v47, -v53
	v_fma_f32 v58, -v58, v61, v60
	v_cvt_pk_bf16_f32 v23, v23, v48
	v_lshlrev_b32_e32 v48, 16, v24
	v_and_b32_e32 v50, 0xffff0000, v24
	v_div_fmas_f32 v58, v58, v59, v61
	v_add_f32_e32 v30, v30, v48
	v_add_f32_e32 v28, v28, v50
	v_lshlrev_b32_e32 v51, 16, v25
	v_and_b32_e32 v52, 0xffff0000, v25
	v_div_fixup_f32 v57, v58, v57, 1.0
	v_sub_f32_e32 v30, v30, v107
	v_sub_f32_e32 v28, v28, v108
	v_add_f32_e32 v45, v45, v51
	v_add_f32_e32 v29, v29, v52
	v_lshlrev_b32_e32 v53, 16, v26
	v_and_b32_e32 v54, 0xffff0000, v26
	v_cndmask_b32_e64 v57, v57, v213, s[14:15]
	v_sub_f32_e32 v45, v45, v109
	v_sub_f32_e32 v29, v29, v110
	v_add_f32_e32 v46, v46, v53
	v_add_f32_e32 v31, v31, v54
	v_lshlrev_b32_e32 v55, 16, v27
	v_fma_f32 v30, v57, v30, -v48
	v_fma_f32 v28, v57, v28, -v50
	v_sub_f32_e32 v46, v46, v111
	v_sub_f32_e32 v31, v31, v91
	v_add_f32_e32 v49, v49, v55
	v_and_b32_e32 v56, 0xffff0000, v27
	v_cvt_pk_bf16_f32 v28, v30, v28
	v_fma_f32 v30, v57, v45, -v51
	v_fma_f32 v29, v57, v29, -v52
	v_sub_f32_e32 v49, v49, v90
	v_add_f32_e32 v47, v47, v56
	v_cvt_pk_bf16_f32 v29, v30, v29
	v_fma_f32 v30, v57, v46, -v53
	v_fma_f32 v31, v57, v31, -v54
	v_sub_f32_e32 v47, v47, v89
	v_cvt_pk_bf16_f32 v30, v30, v31
	v_fma_f32 v31, v57, v49, -v55
	v_fma_f32 v45, v57, v47, -v56
	v_cvt_pk_bf16_f32 v31, v31, v45
	s_mov_b64 s[0:1], 0

.LBB0_1675:
	s_and_b64 vcc, exec, s[8:9]
	s_cbranch_vccz .LBB0_1649
	s_mul_i32 s0, s0, 15
	s_ashr_i32 s1, s0, 31
	s_sub_i32 s4, s37, s38
	s_lshl_b64 s[0:1], s[0:1], 9
	s_add_u32 s10, s0, 0x1e000
	s_addc_u32 s11, s1, 0
	s_lshl_b32 s8, s6, 7
	s_cmp_eq_u32 s38, 0
	s_cselect_b64 s[0:1], -1, 0
	v_or_b32_e32 v32, s8, v207
	s_and_b64 s[12:13], s[20:21], s[0:1]
	v_add_u32_e32 v36, s38, v150
	s_mov_b64 s[0:1], -1
	s_andn2_b64 vcc, exec, s[12:13]
	v_ashrrev_i32_e32 v33, 31, v32
	s_cbranch_vccz .LBB0_1692
	v_lshl_add_u64 v[34:35], v[32:33], 1, s[52:53]
	s_mov_b64 s[14:15], -1
	s_mov_b64 s[0:1], 0
	s_cmp_lt_i32 s6, 1
	s_mov_b64 s[12:13], 0
	s_cbranch_scc1 .LBB0_1685
	s_cmp_gt_i32 s6, 1
	s_cbranch_scc0 .LBB0_1682
	s_cmp_eq_u32 s6, 2
	s_mov_b64 s[12:13], -1
	s_cbranch_scc0 .LBB0_1681
	v_max_i32_e32 v112, 6, v36
	v_add3_u32 v112, s4, -6, v112
	v_mad_i64_i32 v[112:113], s[12:13], v112, s31, v[34:35]
	global_load_dwordx4 v[112:115], v[112:113], off
	v_max_i32_e32 v116, 5, v36
	v_add3_u32 v116, s4, -5, v116
	v_mad_i64_i32 v[116:117], s[12:13], v116, s31, v[34:35]
	global_load_dwordx4 v[116:119], v[116:117], off
	v_max_i32_e32 v120, 4, v36
	v_add3_u32 v120, s4, -4, v120
	v_mad_i64_i32 v[120:121], s[12:13], v120, s31, v[34:35]
	global_load_dwordx4 v[120:123], v[120:121], off
	v_max_i32_e32 v124, 3, v36
	v_add3_u32 v124, s4, -3, v124
	v_mad_i64_i32 v[124:125], s[12:13], v124, s31, v[34:35]
	global_load_dwordx4 v[124:127], v[124:125], off
	v_max_i32_e32 v128, 2, v36
	v_add3_u32 v128, s4, -2, v128
	v_mad_i64_i32 v[128:129], s[12:13], v128, s31, v[34:35]
	global_load_dwordx4 v[128:131], v[128:129], off
	v_max_i32_e32 v132, 1, v36
	v_add3_u32 v132, s4, -1, v132
	v_mad_i64_i32 v[132:133], s[12:13], v132, s31, v[34:35]
	global_load_dwordx4 v[132:135], v[132:133], off
	v_max_i32_e32 v136, 0, v36
	v_add_u32_e32 v136, s4, v136
	v_mad_i64_i32 v[136:137], s[12:13], v136, s31, v[34:35]
	global_load_dwordx4 v[136:139], v[136:137], off
	v_max_i32_e32 v0, 7, v36
	v_add3_u32 v0, s4, -7, v0
	v_mad_i64_i32 v[0:1], s[12:13], v0, s31, v[34:35]
	global_load_dwordx4 v[0:3], v[0:1], off
	v_or_b32_e32 v52, 1, v36
	v_max_i32_e32 v4, 0, v52
	v_add_u32_e32 v4, s4, v4
	v_cmp_lt_i32_e32 vcc, 6, v36
	v_mad_i64_i32 v[4:5], s[12:13], v4, s31, v[34:35]
	global_load_dwordx4 v[4:7], v[4:5], off
	v_or_b32_e32 v20, 2, v36
	v_max_i32_e32 v8, 0, v20
	v_add_u32_e32 v8, s4, v8
	v_mad_i64_i32 v[8:9], s[12:13], v8, s31, v[34:35]
	v_or_b32_e32 v53, 3, v36
	v_max_i32_e32 v12, 0, v53
	v_add_u32_e32 v12, s4, v12
	v_mad_i64_i32 v[12:13], s[12:13], v12, s31, v[34:35]
	v_min_i32_e32 v20, 7, v20
	v_add_u32_e32 v20, 1, v20
	v_cvt_f32_i32_e32 v20, v20
	global_load_dwordx4 v[8:11], v[8:9], off
	s_waitcnt vmcnt(2)
	v_cndmask_b32_e32 v17, 0, v0, vcc
	v_max_i32_e32 v0, 6, v36
	v_add3_u32 v0, s4, -6, v0
	v_cndmask_b32_e32 v16, 0, v1, vcc
	v_mad_i64_i32 v[0:1], s[12:13], v0, s31, v[34:35]
	v_cndmask_b32_e32 v14, 0, v3, vcc
	v_cndmask_b32_e32 v15, 0, v2, vcc
	v_mov_b32_e32 v0, v112
	v_mov_b32_e32 v1, v113
	v_mov_b32_e32 v2, v114
	v_mov_b32_e32 v3, v115
	v_cmp_lt_i32_e32 vcc, 5, v36
	v_lshlrev_b32_e32 v54, 16, v17
	v_and_b32_e32 v17, 0xffff0000, v17
	v_lshlrev_b32_e32 v55, 16, v16
	v_and_b32_e32 v16, 0xffff0000, v16
	v_add_f32_e32 v56, 0, v55
	v_add_f32_e32 v57, 0, v16
	v_and_b32_e32 v60, 0xffff0000, v15
	v_lshlrev_b32_e32 v61, 16, v14
	v_lshlrev_b32_e32 v58, 16, v15
	v_add_f32_e32 v15, 0, v60
	v_add_f32_e32 v62, 0, v61
	v_and_b32_e32 v63, 0xffff0000, v14
	v_add_f32_e32 v14, 0, v63
	v_add_f32_e32 v59, 0, v58
	global_load_dwordx4 v[24:27], v[12:13], off
	v_add_f32_e32 v12, 0, v54
	v_add_f32_e32 v13, 0, v17
	s_waitcnt vmcnt(1)
	v_cndmask_b32_e32 v22, 0, v0, vcc
	v_max_i32_e32 v0, 5, v36
	v_add3_u32 v0, s4, -5, v0
	v_cndmask_b32_e32 v21, 0, v1, vcc
	v_mad_i64_i32 v[0:1], s[12:13], v0, s31, v[34:35]
	v_cndmask_b32_e32 v18, 0, v3, vcc
	v_cndmask_b32_e32 v19, 0, v2, vcc
	v_mov_b32_e32 v0, v116
	v_mov_b32_e32 v1, v117
	v_mov_b32_e32 v2, v118
	v_mov_b32_e32 v3, v119
	v_cmp_lt_i32_e32 vcc, 4, v36
	v_lshlrev_b32_e32 v64, 16, v22
	v_add_f32_e32 v12, v12, v64
	v_and_b32_e32 v22, 0xffff0000, v22
	v_add_f32_e32 v13, v13, v22
	v_lshlrev_b32_e32 v65, 16, v21
	v_and_b32_e32 v21, 0xffff0000, v21
	v_add_f32_e32 v56, v56, v65
	v_add_f32_e32 v57, v57, v21
	v_and_b32_e32 v67, 0xffff0000, v19
	v_lshlrev_b32_e32 v68, 16, v18
	v_lshlrev_b32_e32 v66, 16, v19
	v_add_f32_e32 v15, v15, v67
	v_add_f32_e32 v19, v62, v68
	v_and_b32_e32 v62, 0xffff0000, v18
	v_add_f32_e32 v14, v14, v62
	v_add_f32_e32 v59, v59, v66
	s_waitcnt vmcnt(0)
	v_cndmask_b32_e32 v30, 0, v0, vcc
	v_max_i32_e32 v0, 4, v36
	v_add3_u32 v0, s4, -4, v0
	v_cndmask_b32_e32 v29, 0, v1, vcc
	v_mad_i64_i32 v[0:1], s[12:13], v0, s31, v[34:35]
	v_cndmask_b32_e32 v23, 0, v3, vcc
	v_cndmask_b32_e32 v28, 0, v2, vcc
	v_mov_b32_e32 v0, v120
	v_mov_b32_e32 v1, v121
	v_mov_b32_e32 v2, v122
	v_mov_b32_e32 v3, v123
	v_cmp_lt_i32_e32 vcc, 3, v36
	v_lshlrev_b32_e32 v69, 16, v30
	v_add_f32_e32 v12, v12, v69
	v_and_b32_e32 v30, 0xffff0000, v30
	v_lshlrev_b32_e32 v71, 16, v23
	v_and_b32_e32 v72, 0xffff0000, v23
	v_add_f32_e32 v13, v13, v30
	v_lshlrev_b32_e32 v70, 16, v29
	v_and_b32_e32 v29, 0xffff0000, v29
	v_add_f32_e32 v18, v56, v70
	v_add_f32_e32 v56, v57, v29
	v_lshlrev_b32_e32 v57, 16, v28
	v_and_b32_e32 v28, 0xffff0000, v28
	v_add_f32_e32 v15, v15, v28
	v_add_f32_e32 v19, v19, v71
	v_add_f32_e32 v14, v14, v72
	v_add_f32_e32 v59, v59, v57
	s_waitcnt vmcnt(0)
	v_cndmask_b32_e32 v39, 0, v0, vcc
	v_max_i32_e32 v0, 3, v36
	v_add3_u32 v0, s4, -3, v0
	v_cndmask_b32_e32 v38, 0, v1, vcc
	v_mad_i64_i32 v[0:1], s[12:13], v0, s31, v[34:35]
	v_cndmask_b32_e32 v31, 0, v3, vcc
	v_cndmask_b32_e32 v37, 0, v2, vcc
	v_mov_b32_e32 v0, v124
	v_mov_b32_e32 v1, v125
	v_mov_b32_e32 v2, v126
	v_mov_b32_e32 v3, v127
	v_cmp_lt_i32_e32 vcc, 2, v36
	v_lshlrev_b32_e32 v23, 16, v39
	v_add_f32_e32 v12, v12, v23
	v_and_b32_e32 v23, 0xffff0000, v39
	v_add_f32_e32 v13, v13, v23
	v_lshlrev_b32_e32 v23, 16, v38
	v_add_f32_e32 v18, v18, v23
	v_and_b32_e32 v23, 0xffff0000, v38
	v_lshlrev_b32_e32 v38, 16, v37
	v_and_b32_e32 v37, 0xffff0000, v37
	v_add_f32_e32 v15, v15, v37
	v_lshlrev_b32_e32 v37, 16, v31
	v_add_f32_e32 v19, v19, v37
	v_and_b32_e32 v31, 0xffff0000, v31
	v_add_f32_e32 v14, v14, v31
	v_add_f32_e32 v23, v56, v23
	v_add_f32_e32 v38, v59, v38
	s_waitcnt vmcnt(0)
	v_cndmask_b32_e32 v43, 0, v0, vcc
	v_max_i32_e32 v0, 2, v36
	v_add3_u32 v0, s4, -2, v0
	v_cndmask_b32_e32 v42, 0, v1, vcc
	v_mad_i64_i32 v[0:1], s[12:13], v0, s31, v[34:35]
	v_cndmask_b32_e32 v40, 0, v3, vcc
	v_cndmask_b32_e32 v41, 0, v2, vcc
	v_mov_b32_e32 v0, v128
	v_mov_b32_e32 v1, v129
	v_mov_b32_e32 v2, v130
	v_mov_b32_e32 v3, v131
	v_cmp_lt_i32_e32 vcc, 1, v36
	v_and_b32_e32 v37, 0xffff0000, v41
	v_add_f32_e32 v15, v15, v37
	v_lshlrev_b32_e32 v37, 16, v40
	v_lshlrev_b32_e32 v31, 16, v43
	v_add_f32_e32 v19, v19, v37
	v_and_b32_e32 v37, 0xffff0000, v40
	v_add_f32_e32 v12, v12, v31
	v_and_b32_e32 v31, 0xffff0000, v43
	v_add_f32_e32 v14, v14, v37
	v_add_f32_e32 v13, v13, v31
	v_lshlrev_b32_e32 v31, 16, v42
	v_add_f32_e32 v18, v18, v31
	v_and_b32_e32 v31, 0xffff0000, v42
	v_add_f32_e32 v23, v23, v31
	v_lshlrev_b32_e32 v31, 16, v41
	v_add_f32_e32 v31, v38, v31
	s_waitcnt vmcnt(0)
	v_cndmask_b32_e32 v47, 0, v0, vcc
	v_max_i32_e32 v0, 1, v36
	v_add3_u32 v0, s4, -1, v0
	v_cndmask_b32_e32 v46, 0, v1, vcc
	v_mad_i64_i32 v[0:1], s[12:13], v0, s31, v[34:35]
	v_cndmask_b32_e32 v44, 0, v3, vcc
	v_cndmask_b32_e32 v45, 0, v2, vcc
	v_mov_b32_e32 v0, v132
	v_mov_b32_e32 v1, v133
	v_mov_b32_e32 v2, v134
	v_mov_b32_e32 v3, v135
	v_cmp_lt_i32_e32 vcc, 0, v36
	v_lshlrev_b32_e32 v37, 16, v47
	v_add_f32_e32 v12, v12, v37
	v_and_b32_e32 v37, 0xffff0000, v47
	v_add_f32_e32 v13, v13, v37
	v_lshlrev_b32_e32 v37, 16, v46
	v_add_f32_e32 v18, v18, v37
	v_and_b32_e32 v37, 0xffff0000, v46
	v_add_f32_e32 v23, v23, v37
	v_lshlrev_b32_e32 v37, 16, v45
	v_add_f32_e32 v31, v31, v37
	v_and_b32_e32 v37, 0xffff0000, v45
	v_add_f32_e32 v15, v15, v37
	v_lshlrev_b32_e32 v37, 16, v44
	v_add_f32_e32 v19, v19, v37
	v_and_b32_e32 v37, 0xffff0000, v44
	v_add_f32_e32 v14, v14, v37
	s_waitcnt vmcnt(0)
	v_cndmask_b32_e32 v51, 0, v0, vcc
	v_max_i32_e32 v0, 0, v36
	v_add_u32_e32 v0, s4, v0
	v_cndmask_b32_e32 v50, 0, v1, vcc
	v_mad_i64_i32 v[0:1], s[12:13], v0, s31, v[34:35]
	v_cndmask_b32_e32 v48, 0, v3, vcc
	v_cndmask_b32_e32 v49, 0, v2, vcc
	v_mov_b32_e32 v0, v136
	v_mov_b32_e32 v1, v137
	v_mov_b32_e32 v2, v138
	v_mov_b32_e32 v3, v139
	v_lshlrev_b32_e32 v37, 16, v51
	v_add_f32_e32 v12, v12, v37
	v_and_b32_e32 v37, 0xffff0000, v51
	v_add_f32_e32 v13, v13, v37
	v_lshlrev_b32_e32 v37, 16, v50
	v_add_f32_e32 v18, v18, v37
	v_and_b32_e32 v37, 0xffff0000, v50
	v_add_f32_e32 v23, v23, v37
	v_lshlrev_b32_e32 v37, 16, v49
	v_add_f32_e32 v31, v31, v37
	v_and_b32_e32 v37, 0xffff0000, v49
	v_cmp_lt_i32_e32 vcc, -1, v36
	v_add_f32_e32 v15, v15, v37
	v_lshlrev_b32_e32 v37, 16, v48
	v_add_f32_e32 v19, v19, v37
	v_and_b32_e32 v37, 0xffff0000, v48
	v_add_f32_e32 v14, v14, v37
	s_waitcnt vmcnt(0)
	v_cndmask_b32_e32 v3, 0, v3, vcc
	v_and_b32_e32 v44, 0xffff0000, v3
	v_add_f32_e32 v45, v14, v44
	v_min_i32_e32 v14, 7, v36
	v_add_u32_e32 v14, 1, v14
	v_cvt_f32_i32_e32 v14, v14
	v_cndmask_b32_e32 v2, 0, v2, vcc
	v_cndmask_b32_e32 v1, 0, v1, vcc
	v_cndmask_b32_e32 v0, 0, v0, vcc
	v_div_scale_f32 v46, s[12:13], v14, v14, 1.0
	v_rcp_f32_e32 v47, v46
	v_cmp_lt_i32_e32 vcc, -2, v36
	v_lshlrev_b32_e32 v37, 16, v0
	v_add_f32_e32 v38, v12, v37
	v_cndmask_b32_e32 v7, 0, v7, vcc
	v_cndmask_b32_e32 v6, 0, v6, vcc
	v_cndmask_b32_e32 v5, 0, v5, vcc
	v_cndmask_b32_e32 v4, 0, v4, vcc
	v_cmp_lt_i32_e32 vcc, -3, v36
	v_fma_f32 v48, -v46, v47, 1.0
	v_fmac_f32_e32 v47, v48, v47
	v_cndmask_b32_e32 v11, 0, v11, vcc
	v_cndmask_b32_e32 v10, 0, v10, vcc
	v_cndmask_b32_e32 v9, 0, v9, vcc
	v_cndmask_b32_e32 v8, 0, v8, vcc
	v_div_scale_f32 v48, vcc, 1.0, v14, 1.0
	v_mul_f32_e32 v49, v48, v47
	v_fma_f32 v50, -v46, v49, v48
	v_fmac_f32_e32 v49, v50, v47
	v_fma_f32 v46, -v46, v49, v48
	v_div_fmas_f32 v46, v46, v47, v49
	v_and_b32_e32 v12, 0xffff0000, v0
	v_div_fixup_f32 v14, v46, v14, 1.0
	v_add_f32_e32 v39, v13, v12
	v_and_b32_e32 v40, 0xffff0000, v1
	v_cndmask_b32_e64 v46, v14, v211, s[20:21]
	v_add_f32_e32 v23, v23, v40
	v_fma_f32 v14, v46, v38, -v37
	v_fma_f32 v12, v46, v39, -v12
	v_cvt_pk_bf16_f32 v12, v14, v12
	v_fma_f32 v14, v46, v23, -v40
	v_and_b32_e32 v40, 0xffff0000, v4
	v_lshlrev_b32_e32 v13, 16, v1
	v_add_f32_e32 v39, v39, v40
	v_add_f32_e32 v18, v18, v13
	v_lshlrev_b32_e32 v41, 16, v2
	v_sub_f32_e32 v39, v39, v17
	v_lshlrev_b32_e32 v17, 16, v5
	v_add_f32_e32 v31, v31, v41
	v_and_b32_e32 v42, 0xffff0000, v2
	v_fma_f32 v13, v46, v18, -v13
	v_add_f32_e32 v18, v18, v17
	v_add_f32_e32 v43, v15, v42
	v_cvt_pk_bf16_f32 v13, v13, v14
	v_fma_f32 v14, v46, v31, -v41
	v_sub_f32_e32 v41, v18, v55
	v_and_b32_e32 v18, 0xffff0000, v5
	v_lshlrev_b32_e32 v15, 16, v3
	v_fma_f32 v37, v46, v43, -v42
	v_add_f32_e32 v23, v23, v18
	v_lshlrev_b32_e32 v42, 16, v6
	v_add_f32_e32 v19, v19, v15
	v_cvt_pk_bf16_f32 v14, v14, v37
	v_fma_f32 v37, v46, v45, -v44
	v_sub_f32_e32 v23, v23, v16
	v_add_f32_e32 v16, v31, v42
	v_and_b32_e32 v44, 0xffff0000, v6
	v_fma_f32 v15, v46, v19, -v15
	v_sub_f32_e32 v31, v16, v58
	v_add_f32_e32 v16, v43, v44
	v_lshlrev_b32_e32 v46, 16, v7
	v_sub_f32_e32 v43, v16, v60
	v_add_f32_e32 v16, v19, v46
	v_and_b32_e32 v19, 0xffff0000, v7
	v_sub_f32_e32 v47, v16, v61
	v_add_f32_e32 v16, v45, v19
	v_sub_f32_e32 v45, v16, v63
	v_min_i32_e32 v16, 7, v52
	v_add_u32_e32 v16, 1, v16
	v_cvt_f32_i32_e32 v16, v16
	v_cvt_pk_bf16_f32 v15, v15, v37
	v_lshlrev_b32_e32 v37, 16, v4
	v_add_f32_e32 v38, v38, v37
	v_div_scale_f32 v48, s[12:13], v16, v16, 1.0
	v_rcp_f32_e32 v49, v48
	v_sub_f32_e32 v38, v38, v54
	v_fma_f32 v50, -v48, v49, 1.0
	v_fmac_f32_e32 v49, v50, v49
	v_div_scale_f32 v50, vcc, 1.0, v16, 1.0
	v_mul_f32_e32 v51, v50, v49
	v_fma_f32 v52, -v48, v51, v50
	v_fmac_f32_e32 v51, v52, v49
	v_fma_f32 v48, -v48, v51, v50
	v_div_fmas_f32 v48, v48, v49, v51
	v_div_fixup_f32 v16, v48, v16, 1.0
	v_cndmask_b32_e64 v48, v16, v211, s[20:21]
	v_fma_f32 v17, v48, v41, -v17
	v_fma_f32 v18, v48, v23, -v18
	v_cvt_pk_bf16_f32 v17, v17, v18
	v_fma_f32 v18, v48, v31, -v42
	v_and_b32_e32 v42, 0xffff0000, v9
	v_fma_f32 v16, v48, v38, -v37
	v_fma_f32 v37, v48, v39, -v40
	v_add_f32_e32 v23, v23, v42
	v_cvt_pk_bf16_f32 v16, v16, v37
	v_fma_f32 v37, v48, v43, -v44
	v_sub_f32_e32 v44, v23, v21
	v_lshlrev_b32_e32 v23, 16, v10
	v_cvt_pk_bf16_f32 v18, v18, v37
	v_fma_f32 v37, v48, v47, -v46
	v_add_f32_e32 v21, v31, v23
	v_and_b32_e32 v46, 0xffff0000, v10
	v_fma_f32 v19, v48, v45, -v19
	v_sub_f32_e32 v31, v21, v66
	v_add_f32_e32 v21, v43, v46
	v_lshlrev_b32_e32 v48, 16, v11
	v_sub_f32_e32 v43, v21, v67
	v_add_f32_e32 v21, v47, v48
	v_and_b32_e32 v49, 0xffff0000, v11
	v_sub_f32_e32 v47, v21, v68
	v_add_f32_e32 v21, v45, v49
	v_sub_f32_e32 v45, v21, v62
	v_div_scale_f32 v21, s[12:13], v20, v20, 1.0
	v_rcp_f32_e32 v50, v21
	v_and_b32_e32 v40, 0xffff0000, v8
	v_cvt_pk_bf16_f32 v19, v37, v19
	v_lshlrev_b32_e32 v37, 16, v8
	v_fma_f32 v51, -v21, v50, 1.0
	v_fmac_f32_e32 v50, v51, v50
	v_div_scale_f32 v51, vcc, 1.0, v20, 1.0
	v_mul_f32_e32 v52, v51, v50
	v_fma_f32 v54, -v21, v52, v51
	v_fmac_f32_e32 v52, v54, v50
	v_fma_f32 v21, -v21, v52, v51
	v_add_f32_e32 v39, v39, v40
	v_div_fmas_f32 v21, v21, v50, v52
	v_add_f32_e32 v38, v38, v37
	v_sub_f32_e32 v39, v39, v22
	v_lshlrev_b32_e32 v22, 16, v9
	v_div_fixup_f32 v20, v21, v20, 1.0
	v_sub_f32_e32 v38, v38, v64
	v_add_f32_e32 v41, v41, v22
	v_cndmask_b32_e64 v50, v20, v211, s[20:21]
	v_sub_f32_e32 v41, v41, v65
	v_fma_f32 v20, v50, v38, -v37
	v_fma_f32 v21, v50, v39, -v40
	v_cmp_lt_i32_e32 vcc, -4, v36
	v_cvt_pk_bf16_f32 v20, v20, v21
	v_fma_f32 v21, v50, v41, -v22
	v_fma_f32 v22, v50, v44, -v42
	v_cndmask_b32_e32 v26, 0, v26, vcc
	v_cvt_pk_bf16_f32 v21, v21, v22
	v_fma_f32 v22, v50, v31, -v23
	v_fma_f32 v23, v50, v43, -v46
	v_cndmask_b32_e32 v27, 0, v27, vcc
	v_and_b32_e32 v46, 0xffff0000, v26
	v_cvt_pk_bf16_f32 v22, v22, v23
	v_fma_f32 v23, v50, v47, -v48
	v_add_f32_e32 v43, v43, v46
	v_lshlrev_b32_e32 v48, 16, v27
	v_fma_f32 v37, v50, v45, -v49
	v_sub_f32_e32 v43, v43, v28
	v_add_f32_e32 v28, v47, v48
	v_and_b32_e32 v49, 0xffff0000, v27
	v_sub_f32_e32 v47, v28, v71
	v_add_f32_e32 v28, v45, v49
	v_sub_f32_e32 v45, v28, v72
	v_min_i32_e32 v28, 7, v53
	v_add_u32_e32 v28, 1, v28
	v_cvt_f32_i32_e32 v28, v28
	v_cndmask_b32_e32 v25, 0, v25, vcc
	v_cndmask_b32_e32 v24, 0, v24, vcc
	v_and_b32_e32 v40, 0xffff0000, v24
	v_div_scale_f32 v50, s[12:13], v28, v28, 1.0
	v_rcp_f32_e32 v51, v50
	v_cvt_pk_bf16_f32 v23, v23, v37
	v_lshlrev_b32_e32 v37, 16, v24
	v_add_f32_e32 v39, v39, v40
	v_fma_f32 v52, -v50, v51, 1.0
	v_fmac_f32_e32 v51, v52, v51
	v_div_scale_f32 v52, vcc, 1.0, v28, 1.0
	v_mul_f32_e32 v53, v52, v51
	v_fma_f32 v54, -v50, v53, v52
	v_fmac_f32_e32 v53, v54, v51
	v_fma_f32 v50, -v50, v53, v52
	v_and_b32_e32 v42, 0xffff0000, v25
	v_div_fmas_f32 v50, v50, v51, v53
	v_add_f32_e32 v38, v38, v37
	v_sub_f32_e32 v30, v39, v30
	v_lshlrev_b32_e32 v39, 16, v25
	v_add_f32_e32 v44, v44, v42
	v_div_fixup_f32 v28, v50, v28, 1.0
	v_sub_f32_e32 v38, v38, v69
	v_add_f32_e32 v41, v41, v39
	v_sub_f32_e32 v29, v44, v29
	v_lshlrev_b32_e32 v44, 16, v26
	v_cndmask_b32_e64 v50, v28, v211, s[20:21]
	v_sub_f32_e32 v41, v41, v70
	v_add_f32_e32 v31, v31, v44
	v_fma_f32 v28, v50, v38, -v37
	v_fma_f32 v30, v50, v30, -v40
	v_sub_f32_e32 v31, v31, v57
	v_cvt_pk_bf16_f32 v28, v28, v30
	v_fma_f32 v30, v50, v41, -v39
	v_fma_f32 v29, v50, v29, -v42
	v_cvt_pk_bf16_f32 v29, v30, v29
	v_fma_f32 v30, v50, v31, -v44
	v_fma_f32 v31, v50, v43, -v46
	v_cvt_pk_bf16_f32 v30, v30, v31
	v_fma_f32 v31, v50, v47, -v48
	v_fma_f32 v37, v50, v45, -v49
	v_cvt_pk_bf16_f32 v31, v31, v37
	s_mov_b64 s[12:13], 0

.LBB0_1687:
	v_max_i32_e32 v40, 1, v36
	v_max_i32_e32 v41, 0, v36
	v_or_b32_e32 v39, 1, v36
	v_or_b32_e32 v38, 2, v36
	v_or_b32_e32 v37, 3, v36
	s_andn2_b64 vcc, exec, s[12:13]
	v_cmp_lt_i32_e64 s[28:29], 0, v36
	v_cmp_lt_i32_e64 s[26:27], -1, v36
	v_cmp_lt_i32_e64 s[24:25], -2, v36
	v_cmp_lt_i32_e64 s[22:23], -3, v36
	v_add3_u32 v44, s4, -1, v40
	v_add_u32_e32 v43, s4, v41
	v_max_i32_e32 v42, 0, v39
	v_max_i32_e32 v41, 0, v38
	v_max_i32_e32 v40, 0, v37
	s_cbranch_vccnz .LBB0_1689
	v_max_i32_e32 v112, 14, v36
	v_add3_u32 v112, s4, -14, v112
	v_mad_i64_i32 v[112:113], s[0:1], v112, s31, v[34:35]
	global_load_dwordx4 v[112:115], v[112:113], off
	v_max_i32_e32 v116, 13, v36
	v_add3_u32 v116, s4, -13, v116
	v_mad_i64_i32 v[116:117], s[0:1], v116, s31, v[34:35]
	global_load_dwordx4 v[116:119], v[116:117], off
	v_max_i32_e32 v120, 12, v36
	v_add3_u32 v120, s4, -12, v120
	v_mad_i64_i32 v[120:121], s[0:1], v120, s31, v[34:35]
	global_load_dwordx4 v[120:123], v[120:121], off
	v_max_i32_e32 v124, 11, v36
	v_add3_u32 v124, s4, -11, v124
	v_mad_i64_i32 v[124:125], s[0:1], v124, s31, v[34:35]
	global_load_dwordx4 v[124:127], v[124:125], off
	v_max_i32_e32 v128, 10, v36
	v_add3_u32 v128, s4, -10, v128
	v_mad_i64_i32 v[128:129], s[0:1], v128, s31, v[34:35]
	global_load_dwordx4 v[128:131], v[128:129], off
	v_max_i32_e32 v132, 9, v36
	v_add3_u32 v132, s4, -9, v132
	v_mad_i64_i32 v[132:133], s[0:1], v132, s31, v[34:35]
	global_load_dwordx4 v[132:135], v[132:133], off
	v_max_i32_e32 v136, 8, v36
	v_add3_u32 v136, s4, -8, v136
	v_mad_i64_i32 v[136:137], s[0:1], v136, s31, v[34:35]
	global_load_dwordx4 v[136:139], v[136:137], off
	v_max_i32_e32 v176, 7, v36
	v_add3_u32 v176, s4, -7, v176
	v_mad_i64_i32 v[176:177], s[0:1], v176, s31, v[34:35]
	global_load_dwordx4 v[176:179], v[176:177], off
	v_max_i32_e32 v180, 6, v36
	v_add3_u32 v180, s4, -6, v180
	v_mad_i64_i32 v[180:181], s[0:1], v180, s31, v[34:35]
	global_load_dwordx4 v[180:183], v[180:181], off
	v_max_i32_e32 v184, 5, v36
	v_add3_u32 v184, s4, -5, v184
	v_mad_i64_i32 v[184:185], s[0:1], v184, s31, v[34:35]
	global_load_dwordx4 v[184:187], v[184:185], off
	v_max_i32_e32 v188, 4, v36
	v_add3_u32 v188, s4, -4, v188
	v_mad_i64_i32 v[188:189], s[0:1], v188, s31, v[34:35]
	global_load_dwordx4 v[188:191], v[188:189], off
	v_max_i32_e32 v192, 3, v36
	v_add3_u32 v192, s4, -3, v192
	v_mad_i64_i32 v[192:193], s[0:1], v192, s31, v[34:35]
	global_load_dwordx4 v[192:195], v[192:193], off
	v_max_i32_e32 v196, 2, v36
	v_add3_u32 v196, s4, -2, v196
	v_mad_i64_i32 v[196:197], s[0:1], v196, s31, v[34:35]
	global_load_dwordx4 v[196:199], v[196:197], off
	v_mad_i64_i32 v[200:201], s[0:1], v44, s31, v[34:35]
	global_load_dwordx4 v[200:203], v[200:201], off
	v_mad_i64_i32 v[218:219], s[0:1], v43, s31, v[34:35]
	global_load_dwordx4 v[218:221], v[218:219], off
	v_max_i32_e32 v0, 15, v36
	v_add3_u32 v0, s4, -15, v0
	v_mad_i64_i32 v[0:1], s[0:1], v0, s31, v[34:35]
	global_load_dwordx4 v[0:3], v[0:1], off
	v_add_u32_e32 v4, s4, v42
	v_cmp_lt_i32_e32 vcc, 14, v36
	v_mad_i64_i32 v[4:5], s[0:1], v4, s31, v[34:35]
	global_load_dwordx4 v[4:7], v[4:5], off
	v_add_u32_e32 v8, s4, v41
	v_mad_i64_i32 v[8:9], s[0:1], v8, s31, v[34:35]
	v_add_u32_e32 v24, s4, v40
	v_mad_i64_i32 v[24:25], s[0:1], v24, s31, v[34:35]
	global_load_dwordx4 v[8:11], v[8:9], off
	s_waitcnt vmcnt(2)
	v_cndmask_b32_e32 v16, 0, v0, vcc
	v_max_i32_e32 v0, 14, v36
	v_add3_u32 v0, s4, -14, v0
	v_cndmask_b32_e32 v14, 0, v1, vcc
	v_mad_i64_i32 v[0:1], s[0:1], v0, s31, v[34:35]
	v_cndmask_b32_e32 v12, 0, v3, vcc
	v_cndmask_b32_e32 v13, 0, v2, vcc
	v_mov_b32_e32 v0, v112
	v_mov_b32_e32 v1, v113
	v_mov_b32_e32 v2, v114
	v_mov_b32_e32 v3, v115
	v_cmp_lt_i32_e32 vcc, 13, v36
	v_and_b32_e32 v94, 0xffff0000, v14
	v_lshlrev_b32_e32 v92, 16, v16
	v_and_b32_e32 v16, 0xffff0000, v16
	v_lshlrev_b32_e32 v93, 16, v14
	v_add_f32_e32 v14, 0, v94
	v_lshlrev_b32_e32 v95, 16, v13
	v_add_f32_e32 v90, 0, v16
	v_add_f32_e32 v91, 0, v93
	v_add_f32_e32 v96, 0, v95
	v_and_b32_e32 v97, 0xffff0000, v13
	v_add_f32_e32 v13, 0, v97
	v_lshlrev_b32_e32 v98, 16, v12
	v_add_f32_e32 v89, 0, v92
	v_add_f32_e32 v99, 0, v98
	v_and_b32_e32 v100, 0xffff0000, v12
	v_add_f32_e32 v12, 0, v100
	s_waitcnt vmcnt(1)
	v_cndmask_b32_e64 v4, 0, v4, s[24:25]
	v_cndmask_b32_e64 v5, 0, v5, s[24:25]
	v_cndmask_b32_e64 v6, 0, v6, s[24:25]
	v_cndmask_b32_e64 v7, 0, v7, s[24:25]
	s_waitcnt vmcnt(0)
	v_cndmask_b32_e64 v8, 0, v8, s[22:23]
	v_cndmask_b32_e64 v9, 0, v9, s[22:23]
	v_cndmask_b32_e64 v10, 0, v10, s[22:23]
	v_cndmask_b32_e64 v11, 0, v11, s[22:23]
	global_load_dwordx4 v[24:27], v[24:25], off
	s_waitcnt vmcnt(1)
	v_cndmask_b32_e32 v19, 0, v0, vcc
	v_max_i32_e32 v0, 13, v36
	v_add3_u32 v0, s4, -13, v0
	v_cndmask_b32_e32 v18, 0, v1, vcc
	v_mad_i64_i32 v[0:1], s[0:1], v0, s31, v[34:35]
	v_cndmask_b32_e32 v15, 0, v3, vcc
	v_cndmask_b32_e32 v17, 0, v2, vcc
	v_mov_b32_e32 v0, v116
	v_mov_b32_e32 v1, v117
	v_mov_b32_e32 v2, v118
	v_mov_b32_e32 v3, v119
	v_cmp_lt_i32_e32 vcc, 12, v36
	v_and_b32_e32 v104, 0xffff0000, v18
	v_and_b32_e32 v102, 0xffff0000, v19
	v_lshlrev_b32_e32 v103, 16, v18
	v_add_f32_e32 v14, v14, v104
	v_lshlrev_b32_e32 v105, 16, v17
	v_lshlrev_b32_e32 v101, 16, v19
	v_add_f32_e32 v19, v90, v102
	v_add_f32_e32 v90, v91, v103
	v_add_f32_e32 v18, v96, v105
	v_and_b32_e32 v96, 0xffff0000, v17
	v_add_f32_e32 v13, v13, v96
	v_lshlrev_b32_e32 v106, 16, v15
	v_add_f32_e32 v89, v89, v101
	v_add_f32_e32 v17, v99, v106
	v_and_b32_e32 v99, 0xffff0000, v15
	v_add_f32_e32 v12, v12, v99
	s_waitcnt vmcnt(0)
	v_cndmask_b32_e32 v23, 0, v0, vcc
	v_max_i32_e32 v0, 12, v36
	v_add3_u32 v0, s4, -12, v0
	v_cndmask_b32_e32 v22, 0, v1, vcc
	v_mad_i64_i32 v[0:1], s[0:1], v0, s31, v[34:35]
	v_cndmask_b32_e32 v20, 0, v3, vcc
	v_cndmask_b32_e32 v21, 0, v2, vcc
	v_mov_b32_e32 v0, v120
	v_mov_b32_e32 v1, v121
	v_mov_b32_e32 v2, v122
	v_mov_b32_e32 v3, v123
	v_cmp_lt_i32_e32 vcc, 11, v36
	v_and_b32_e32 v110, 0xffff0000, v22
	v_add_f32_e32 v14, v14, v110
	v_lshlrev_b32_e32 v111, 16, v21
	v_and_b32_e32 v91, 0xffff0000, v21
	v_lshlrev_b32_e32 v109, 16, v22
	v_add_f32_e32 v18, v18, v111
	v_lshlrev_b32_e32 v107, 16, v23
	v_and_b32_e32 v108, 0xffff0000, v23
	v_add_f32_e32 v23, v90, v109
	v_add_f32_e32 v13, v13, v91
	v_lshlrev_b32_e32 v90, 16, v20
	v_add_f32_e32 v15, v89, v107
	v_add_f32_e32 v17, v17, v90
	v_and_b32_e32 v89, 0xffff0000, v20
	v_add_f32_e32 v12, v12, v89
	v_add_f32_e32 v19, v19, v108
	s_waitcnt vmcnt(0)
	v_cndmask_b32_e32 v31, 0, v0, vcc
	v_max_i32_e32 v0, 11, v36
	v_add3_u32 v0, s4, -11, v0
	v_cndmask_b32_e32 v30, 0, v1, vcc
	v_mad_i64_i32 v[0:1], s[0:1], v0, s31, v[34:35]
	v_cndmask_b32_e32 v28, 0, v3, vcc
	v_cndmask_b32_e32 v29, 0, v2, vcc
	v_mov_b32_e32 v0, v124
	v_mov_b32_e32 v1, v125
	v_mov_b32_e32 v2, v126
	v_mov_b32_e32 v3, v127
	v_cmp_lt_i32_e32 vcc, 10, v36
	v_and_b32_e32 v21, 0xffff0000, v30
	v_add_f32_e32 v14, v14, v21
	v_lshlrev_b32_e32 v21, 16, v29
	v_add_f32_e32 v18, v18, v21
	v_and_b32_e32 v21, 0xffff0000, v29
	v_add_f32_e32 v13, v13, v21
	v_lshlrev_b32_e32 v21, 16, v28
	v_lshlrev_b32_e32 v20, 16, v31
	v_add_f32_e32 v17, v17, v21
	v_and_b32_e32 v21, 0xffff0000, v28
	v_add_f32_e32 v15, v15, v20
	v_and_b32_e32 v20, 0xffff0000, v31
	v_add_f32_e32 v12, v12, v21
	v_add_f32_e32 v19, v19, v20
	v_lshlrev_b32_e32 v20, 16, v30
	v_add_f32_e32 v20, v23, v20
	s_waitcnt vmcnt(0)
	v_cndmask_b32_e32 v48, 0, v0, vcc
	v_max_i32_e32 v0, 10, v36
	v_add3_u32 v0, s4, -10, v0
	v_cndmask_b32_e32 v47, 0, v1, vcc
	v_mad_i64_i32 v[0:1], s[0:1], v0, s31, v[34:35]
	v_cndmask_b32_e32 v45, 0, v3, vcc
	v_cndmask_b32_e32 v46, 0, v2, vcc
	v_mov_b32_e32 v0, v128
	v_mov_b32_e32 v1, v129
	v_mov_b32_e32 v2, v130
	v_mov_b32_e32 v3, v131
	v_cmp_lt_i32_e32 vcc, 9, v36
	v_lshlrev_b32_e32 v21, 16, v48
	v_add_f32_e32 v15, v15, v21
	v_and_b32_e32 v21, 0xffff0000, v48
	v_add_f32_e32 v19, v19, v21
	v_lshlrev_b32_e32 v21, 16, v47
	v_add_f32_e32 v20, v20, v21
	v_and_b32_e32 v21, 0xffff0000, v47
	v_add_f32_e32 v14, v14, v21
	v_lshlrev_b32_e32 v21, 16, v46
	v_add_f32_e32 v18, v18, v21
	v_and_b32_e32 v21, 0xffff0000, v46
	v_add_f32_e32 v13, v13, v21
	v_lshlrev_b32_e32 v21, 16, v45
	v_add_f32_e32 v17, v17, v21
	v_and_b32_e32 v21, 0xffff0000, v45
	v_add_f32_e32 v12, v12, v21
	s_waitcnt vmcnt(0)
	v_cndmask_b32_e32 v52, 0, v0, vcc
	v_max_i32_e32 v0, 9, v36
	v_add3_u32 v0, s4, -9, v0
	v_cndmask_b32_e32 v51, 0, v1, vcc
	v_mad_i64_i32 v[0:1], s[0:1], v0, s31, v[34:35]
	v_cndmask_b32_e32 v49, 0, v3, vcc
	v_cndmask_b32_e32 v50, 0, v2, vcc
	v_mov_b32_e32 v0, v132
	v_mov_b32_e32 v1, v133
	v_mov_b32_e32 v2, v134
	v_mov_b32_e32 v3, v135
	v_cmp_lt_i32_e32 vcc, 8, v36
	v_lshlrev_b32_e32 v21, 16, v52
	v_add_f32_e32 v15, v15, v21
	v_and_b32_e32 v21, 0xffff0000, v52
	v_add_f32_e32 v19, v19, v21
	v_lshlrev_b32_e32 v21, 16, v51
	v_add_f32_e32 v20, v20, v21
	v_and_b32_e32 v21, 0xffff0000, v51
	v_add_f32_e32 v14, v14, v21
	v_lshlrev_b32_e32 v21, 16, v50
	v_add_f32_e32 v18, v18, v21
	v_and_b32_e32 v21, 0xffff0000, v50
	v_add_f32_e32 v13, v13, v21
	v_lshlrev_b32_e32 v21, 16, v49
	v_add_f32_e32 v17, v17, v21
	v_and_b32_e32 v21, 0xffff0000, v49
	v_add_f32_e32 v12, v12, v21
	s_waitcnt vmcnt(0)
	v_cndmask_b32_e32 v56, 0, v0, vcc
	v_max_i32_e32 v0, 8, v36
	v_add3_u32 v0, s4, -8, v0
	v_cndmask_b32_e32 v55, 0, v1, vcc
	v_mad_i64_i32 v[0:1], s[0:1], v0, s31, v[34:35]
	v_cndmask_b32_e32 v53, 0, v3, vcc
	v_cndmask_b32_e32 v54, 0, v2, vcc
	v_mov_b32_e32 v0, v136
	v_mov_b32_e32 v1, v137
	v_mov_b32_e32 v2, v138
	v_mov_b32_e32 v3, v139
	v_cmp_lt_i32_e32 vcc, 7, v36
	v_lshlrev_b32_e32 v21, 16, v56
	v_add_f32_e32 v15, v15, v21
	v_and_b32_e32 v21, 0xffff0000, v56
	v_add_f32_e32 v19, v19, v21
	v_lshlrev_b32_e32 v21, 16, v55
	v_add_f32_e32 v20, v20, v21
	v_and_b32_e32 v21, 0xffff0000, v55
	v_add_f32_e32 v14, v14, v21
	v_lshlrev_b32_e32 v21, 16, v54
	v_add_f32_e32 v18, v18, v21
	v_and_b32_e32 v21, 0xffff0000, v54
	v_add_f32_e32 v13, v13, v21
	v_lshlrev_b32_e32 v21, 16, v53
	v_add_f32_e32 v17, v17, v21
	v_and_b32_e32 v21, 0xffff0000, v53
	v_add_f32_e32 v12, v12, v21
	s_waitcnt vmcnt(0)
	v_cndmask_b32_e32 v60, 0, v0, vcc
	v_max_i32_e32 v0, 7, v36
	v_add3_u32 v0, s4, -7, v0
	v_cndmask_b32_e32 v59, 0, v1, vcc
	v_mad_i64_i32 v[0:1], s[0:1], v0, s31, v[34:35]
	v_cndmask_b32_e32 v57, 0, v3, vcc
	v_cndmask_b32_e32 v58, 0, v2, vcc
	v_mov_b32_e32 v0, v176
	v_mov_b32_e32 v1, v177
	v_mov_b32_e32 v2, v178
	v_mov_b32_e32 v3, v179
	v_cmp_lt_i32_e32 vcc, 6, v36
	v_lshlrev_b32_e32 v21, 16, v60
	v_add_f32_e32 v15, v15, v21
	v_and_b32_e32 v21, 0xffff0000, v60
	v_add_f32_e32 v19, v19, v21
	v_lshlrev_b32_e32 v21, 16, v59
	v_add_f32_e32 v20, v20, v21
	v_and_b32_e32 v21, 0xffff0000, v59
	v_add_f32_e32 v14, v14, v21
	v_lshlrev_b32_e32 v21, 16, v58
	v_add_f32_e32 v18, v18, v21
	v_and_b32_e32 v21, 0xffff0000, v58
	v_add_f32_e32 v13, v13, v21
	v_lshlrev_b32_e32 v21, 16, v57
	v_add_f32_e32 v17, v17, v21
	v_and_b32_e32 v21, 0xffff0000, v57
	v_add_f32_e32 v12, v12, v21
	s_waitcnt vmcnt(0)
	v_cndmask_b32_e32 v64, 0, v0, vcc
	v_max_i32_e32 v0, 6, v36
	v_add3_u32 v0, s4, -6, v0
	v_cndmask_b32_e32 v63, 0, v1, vcc
	v_mad_i64_i32 v[0:1], s[0:1], v0, s31, v[34:35]
	v_cndmask_b32_e32 v61, 0, v3, vcc
	v_cndmask_b32_e32 v62, 0, v2, vcc
	v_mov_b32_e32 v0, v180
	v_mov_b32_e32 v1, v181
	v_mov_b32_e32 v2, v182
	v_mov_b32_e32 v3, v183
	v_cmp_lt_i32_e32 vcc, 5, v36
	v_lshlrev_b32_e32 v21, 16, v64
	v_add_f32_e32 v15, v15, v21
	v_and_b32_e32 v21, 0xffff0000, v64
	v_add_f32_e32 v19, v19, v21
	v_lshlrev_b32_e32 v21, 16, v63
	v_add_f32_e32 v20, v20, v21
	v_and_b32_e32 v21, 0xffff0000, v63
	v_add_f32_e32 v14, v14, v21
	v_lshlrev_b32_e32 v21, 16, v62
	v_add_f32_e32 v18, v18, v21
	v_and_b32_e32 v21, 0xffff0000, v62
	v_add_f32_e32 v13, v13, v21
	v_lshlrev_b32_e32 v21, 16, v61
	v_add_f32_e32 v17, v17, v21
	v_and_b32_e32 v21, 0xffff0000, v61
	v_add_f32_e32 v12, v12, v21
	s_waitcnt vmcnt(0)
	v_cndmask_b32_e32 v68, 0, v0, vcc
	v_max_i32_e32 v0, 5, v36
	v_add3_u32 v0, s4, -5, v0
	v_cndmask_b32_e32 v67, 0, v1, vcc
	v_mad_i64_i32 v[0:1], s[0:1], v0, s31, v[34:35]
	v_cndmask_b32_e32 v65, 0, v3, vcc
	v_cndmask_b32_e32 v66, 0, v2, vcc
	v_mov_b32_e32 v0, v184
	v_mov_b32_e32 v1, v185
	v_mov_b32_e32 v2, v186
	v_mov_b32_e32 v3, v187
	v_cmp_lt_i32_e32 vcc, 4, v36
	v_lshlrev_b32_e32 v21, 16, v68
	v_add_f32_e32 v15, v15, v21
	v_and_b32_e32 v21, 0xffff0000, v68
	v_add_f32_e32 v19, v19, v21
	v_lshlrev_b32_e32 v21, 16, v67
	v_add_f32_e32 v20, v20, v21
	v_and_b32_e32 v21, 0xffff0000, v67
	v_add_f32_e32 v14, v14, v21
	v_lshlrev_b32_e32 v21, 16, v66
	v_add_f32_e32 v18, v18, v21
	v_and_b32_e32 v21, 0xffff0000, v66
	v_add_f32_e32 v13, v13, v21
	v_lshlrev_b32_e32 v21, 16, v65
	v_add_f32_e32 v17, v17, v21
	v_and_b32_e32 v21, 0xffff0000, v65
	v_add_f32_e32 v12, v12, v21
	s_waitcnt vmcnt(0)
	v_cndmask_b32_e32 v72, 0, v0, vcc
	v_max_i32_e32 v0, 4, v36
	v_add3_u32 v0, s4, -4, v0
	v_cndmask_b32_e32 v71, 0, v1, vcc
	v_mad_i64_i32 v[0:1], s[0:1], v0, s31, v[34:35]
	v_cndmask_b32_e32 v69, 0, v3, vcc
	v_cndmask_b32_e32 v70, 0, v2, vcc
	v_mov_b32_e32 v0, v188
	v_mov_b32_e32 v1, v189
	v_mov_b32_e32 v2, v190
	v_mov_b32_e32 v3, v191
	v_cmp_lt_i32_e32 vcc, 3, v36
	v_lshlrev_b32_e32 v21, 16, v72
	v_add_f32_e32 v15, v15, v21
	v_and_b32_e32 v21, 0xffff0000, v72
	v_add_f32_e32 v19, v19, v21
	v_lshlrev_b32_e32 v21, 16, v71
	v_add_f32_e32 v20, v20, v21
	v_and_b32_e32 v21, 0xffff0000, v71
	v_add_f32_e32 v14, v14, v21
	v_lshlrev_b32_e32 v21, 16, v70
	v_add_f32_e32 v18, v18, v21
	v_and_b32_e32 v21, 0xffff0000, v70
	v_add_f32_e32 v13, v13, v21
	v_lshlrev_b32_e32 v21, 16, v69
	v_add_f32_e32 v17, v17, v21
	v_and_b32_e32 v21, 0xffff0000, v69
	v_add_f32_e32 v12, v12, v21
	s_waitcnt vmcnt(0)
	v_cndmask_b32_e32 v76, 0, v0, vcc
	v_max_i32_e32 v0, 3, v36
	v_add3_u32 v0, s4, -3, v0
	v_cndmask_b32_e32 v75, 0, v1, vcc
	v_mad_i64_i32 v[0:1], s[0:1], v0, s31, v[34:35]
	v_cndmask_b32_e32 v73, 0, v3, vcc
	v_cndmask_b32_e32 v74, 0, v2, vcc
	v_mov_b32_e32 v0, v192
	v_mov_b32_e32 v1, v193
	v_mov_b32_e32 v2, v194
	v_mov_b32_e32 v3, v195
	v_cmp_lt_i32_e32 vcc, 2, v36
	v_lshlrev_b32_e32 v21, 16, v76
	v_add_f32_e32 v15, v15, v21
	v_and_b32_e32 v21, 0xffff0000, v76
	v_add_f32_e32 v19, v19, v21
	v_lshlrev_b32_e32 v21, 16, v75
	v_add_f32_e32 v20, v20, v21
	v_and_b32_e32 v21, 0xffff0000, v75
	v_add_f32_e32 v14, v14, v21
	v_lshlrev_b32_e32 v21, 16, v74
	v_add_f32_e32 v18, v18, v21
	v_and_b32_e32 v21, 0xffff0000, v74
	v_add_f32_e32 v13, v13, v21
	v_lshlrev_b32_e32 v21, 16, v73
	v_add_f32_e32 v17, v17, v21
	v_and_b32_e32 v21, 0xffff0000, v73
	v_add_f32_e32 v12, v12, v21
	s_waitcnt vmcnt(0)
	v_cndmask_b32_e32 v80, 0, v0, vcc
	v_max_i32_e32 v0, 2, v36
	v_add3_u32 v0, s4, -2, v0
	v_cndmask_b32_e32 v79, 0, v1, vcc
	v_mad_i64_i32 v[0:1], s[0:1], v0, s31, v[34:35]
	v_cndmask_b32_e32 v77, 0, v3, vcc
	v_cndmask_b32_e32 v78, 0, v2, vcc
	v_mov_b32_e32 v0, v196
	v_mov_b32_e32 v1, v197
	v_mov_b32_e32 v2, v198
	v_mov_b32_e32 v3, v199
	v_cmp_lt_i32_e32 vcc, 1, v36
	v_lshlrev_b32_e32 v21, 16, v80
	v_add_f32_e32 v15, v15, v21
	v_and_b32_e32 v21, 0xffff0000, v80
	v_add_f32_e32 v19, v19, v21
	v_lshlrev_b32_e32 v21, 16, v79
	v_add_f32_e32 v20, v20, v21
	v_and_b32_e32 v21, 0xffff0000, v79
	v_add_f32_e32 v14, v14, v21
	v_lshlrev_b32_e32 v21, 16, v78
	v_add_f32_e32 v18, v18, v21
	v_and_b32_e32 v21, 0xffff0000, v78
	v_add_f32_e32 v13, v13, v21
	v_lshlrev_b32_e32 v21, 16, v77
	v_add_f32_e32 v17, v17, v21
	v_and_b32_e32 v21, 0xffff0000, v77
	v_add_f32_e32 v12, v12, v21
	s_waitcnt vmcnt(0)
	v_cndmask_b32_e32 v83, 0, v1, vcc
	v_cndmask_b32_e32 v85, 0, v0, vcc
	v_mad_i64_i32 v[0:1], s[0:1], v44, s31, v[34:35]
	v_cndmask_b32_e32 v81, 0, v3, vcc
	v_cndmask_b32_e32 v82, 0, v2, vcc
	v_mov_b32_e32 v0, v200
	v_mov_b32_e32 v1, v201
	v_mov_b32_e32 v2, v202
	v_mov_b32_e32 v3, v203
	v_lshlrev_b32_e32 v21, 16, v85
	v_add_f32_e32 v15, v15, v21
	v_and_b32_e32 v21, 0xffff0000, v85
	v_add_f32_e32 v19, v19, v21
	v_lshlrev_b32_e32 v21, 16, v83
	v_add_f32_e32 v20, v20, v21
	v_and_b32_e32 v21, 0xffff0000, v83
	v_add_f32_e32 v14, v14, v21
	v_lshlrev_b32_e32 v21, 16, v82
	v_add_f32_e32 v18, v18, v21
	v_and_b32_e32 v21, 0xffff0000, v82
	v_add_f32_e32 v13, v13, v21
	v_lshlrev_b32_e32 v21, 16, v81
	v_add_f32_e32 v17, v17, v21
	v_and_b32_e32 v21, 0xffff0000, v81
	v_add_f32_e32 v12, v12, v21
	s_waitcnt vmcnt(0)
	v_cndmask_b32_e64 v87, 0, v1, s[28:29]
	v_cndmask_b32_e64 v88, 0, v0, s[28:29]
	v_mad_i64_i32 v[0:1], s[0:1], v43, s31, v[34:35]
	v_cndmask_b32_e64 v84, 0, v3, s[28:29]
	v_cndmask_b32_e64 v86, 0, v2, s[28:29]
	v_mov_b32_e32 v0, v218
	v_mov_b32_e32 v1, v219
	v_mov_b32_e32 v2, v220
	v_mov_b32_e32 v3, v221
	v_lshlrev_b32_e32 v21, 16, v88
	v_add_f32_e32 v15, v15, v21
	v_and_b32_e32 v21, 0xffff0000, v88
	v_add_f32_e32 v19, v19, v21
	v_lshlrev_b32_e32 v21, 16, v87
	v_add_f32_e32 v20, v20, v21
	v_and_b32_e32 v21, 0xffff0000, v87
	v_add_f32_e32 v14, v14, v21
	v_lshlrev_b32_e32 v21, 16, v86
	v_add_f32_e32 v18, v18, v21
	v_and_b32_e32 v21, 0xffff0000, v86
	v_add_f32_e32 v13, v13, v21
	v_lshlrev_b32_e32 v21, 16, v84
	v_add_f32_e32 v17, v17, v21
	v_and_b32_e32 v21, 0xffff0000, v84
	v_add_f32_e32 v12, v12, v21
	s_waitcnt vmcnt(0)
	v_cndmask_b32_e64 v3, 0, v3, s[26:27]
	v_and_b32_e32 v46, 0xffff0000, v3
	v_add_f32_e32 v47, v12, v46
	v_min_i32_e32 v12, 15, v36
	v_add_u32_e32 v12, 1, v12
	v_cvt_f32_i32_e32 v12, v12
	v_cndmask_b32_e64 v2, 0, v2, s[26:27]
	v_and_b32_e32 v30, 0xffff0000, v2
	v_add_f32_e32 v31, v13, v30
	v_div_scale_f32 v13, s[0:1], v12, v12, 1.0
	v_rcp_f32_e32 v48, v13
	v_cndmask_b32_e64 v0, 0, v0, s[26:27]
	v_lshlrev_b32_e32 v21, 16, v0
	v_cndmask_b32_e64 v1, 0, v1, s[26:27]
	v_fma_f32 v49, -v13, v48, 1.0
	v_fmac_f32_e32 v48, v49, v48
	v_div_scale_f32 v49, vcc, 1.0, v12, 1.0
	v_mul_f32_e32 v50, v49, v48
	v_fma_f32 v51, -v13, v50, v49
	v_fmac_f32_e32 v50, v51, v48
	v_fma_f32 v13, -v13, v50, v49
	v_div_fmas_f32 v13, v13, v48, v50
	v_add_f32_e32 v22, v15, v21
	v_and_b32_e32 v15, 0xffff0000, v0
	v_div_fixup_f32 v12, v13, v12, 1.0
	v_add_f32_e32 v19, v19, v15
	v_lshlrev_b32_e32 v23, 16, v1
	v_cndmask_b32_e64 v48, v12, v213, s[20:21]
	v_add_f32_e32 v20, v20, v23
	v_fma_f32 v12, v48, v22, -v21
	v_fma_f32 v13, v48, v19, -v15
	v_and_b32_e32 v28, 0xffff0000, v1
	v_cvt_pk_bf16_f32 v12, v12, v13
	v_fma_f32 v13, v48, v20, -v23
	v_and_b32_e32 v23, 0xffff0000, v4
	v_add_f32_e32 v29, v14, v28
	v_lshlrev_b32_e32 v14, 16, v2
	v_add_f32_e32 v19, v19, v23
	v_add_f32_e32 v18, v18, v14
	v_lshlrev_b32_e32 v45, 16, v3
	v_fma_f32 v15, v48, v29, -v28
	v_sub_f32_e32 v28, v19, v16
	v_lshlrev_b32_e32 v19, 16, v5
	v_add_f32_e32 v17, v17, v45
	v_cvt_pk_bf16_f32 v13, v13, v15
	v_fma_f32 v14, v48, v18, -v14
	v_fma_f32 v15, v48, v31, -v30
	v_add_f32_e32 v16, v20, v19
	v_and_b32_e32 v30, 0xffff0000, v5
	v_cvt_pk_bf16_f32 v14, v14, v15
	v_fma_f32 v15, v48, v17, -v45
	v_sub_f32_e32 v20, v16, v93
	v_add_f32_e32 v16, v29, v30
	v_lshlrev_b32_e32 v45, 16, v6
	v_sub_f32_e32 v29, v16, v94
	v_add_f32_e32 v16, v18, v45
	v_and_b32_e32 v18, 0xffff0000, v6
	v_fma_f32 v21, v48, v47, -v46
	v_sub_f32_e32 v46, v16, v95
	v_add_f32_e32 v16, v31, v18
	v_lshlrev_b32_e32 v48, 16, v7
	v_sub_f32_e32 v31, v16, v97
	v_add_f32_e32 v16, v17, v48
	v_and_b32_e32 v50, 0xffff0000, v7
	v_sub_f32_e32 v49, v16, v98
	v_add_f32_e32 v16, v47, v50
	v_sub_f32_e32 v47, v16, v100
	v_min_i32_e32 v16, 15, v39
	v_add_u32_e32 v16, 1, v16
	v_cvt_f32_i32_e32 v16, v16
	v_cvt_pk_bf16_f32 v15, v15, v21
	v_lshlrev_b32_e32 v21, 16, v4
	v_add_f32_e32 v22, v22, v21
	v_div_scale_f32 v17, s[0:1], v16, v16, 1.0
	v_rcp_f32_e32 v51, v17
	v_sub_f32_e32 v22, v22, v92
	v_fma_f32 v52, -v17, v51, 1.0
	v_fmac_f32_e32 v51, v52, v51
	v_div_scale_f32 v52, vcc, 1.0, v16, 1.0
	v_mul_f32_e32 v53, v52, v51
	v_fma_f32 v54, -v17, v53, v52
	v_fmac_f32_e32 v53, v54, v51
	v_fma_f32 v17, -v17, v53, v52
	v_div_fmas_f32 v17, v17, v51, v53
	v_div_fixup_f32 v16, v17, v16, 1.0
	v_cndmask_b32_e64 v51, v16, v213, s[20:21]
	v_fma_f32 v16, v51, v22, -v21
	v_fma_f32 v17, v51, v28, -v23
	v_cvt_pk_bf16_f32 v16, v16, v17
	v_fma_f32 v17, v51, v20, -v19
	v_fma_f32 v19, v51, v29, -v30
	v_cvt_pk_bf16_f32 v17, v17, v19
	v_fma_f32 v19, v51, v46, -v45
	v_fma_f32 v18, v51, v31, -v18
	v_cvt_pk_bf16_f32 v18, v19, v18
	v_fma_f32 v19, v51, v49, -v48
	v_fma_f32 v21, v51, v47, -v50
	v_cvt_pk_bf16_f32 v19, v19, v21
	v_lshlrev_b32_e32 v21, 16, v8
	v_add_f32_e32 v22, v22, v21
	v_sub_f32_e32 v30, v22, v101
	v_and_b32_e32 v22, 0xffff0000, v8
	v_add_f32_e32 v23, v28, v22
	v_sub_f32_e32 v28, v23, v102
	v_lshlrev_b32_e32 v23, 16, v9
	v_add_f32_e32 v20, v20, v23
	v_and_b32_e32 v48, 0xffff0000, v9
	v_sub_f32_e32 v45, v20, v103
	v_add_f32_e32 v20, v29, v48
	v_lshlrev_b32_e32 v50, 16, v10
	v_sub_f32_e32 v29, v20, v104
	v_add_f32_e32 v20, v46, v50
	v_and_b32_e32 v51, 0xffff0000, v10
	v_sub_f32_e32 v46, v20, v105
	v_add_f32_e32 v20, v31, v51
	v_lshlrev_b32_e32 v52, 16, v11
	v_sub_f32_e32 v31, v20, v96
	v_add_f32_e32 v20, v49, v52
	v_and_b32_e32 v53, 0xffff0000, v11
	v_sub_f32_e32 v49, v20, v106
	v_add_f32_e32 v20, v47, v53
	v_sub_f32_e32 v47, v20, v99
	v_min_i32_e32 v20, 15, v38
	v_add_u32_e32 v20, 1, v20
	v_cvt_f32_i32_e32 v20, v20
	v_div_scale_f32 v54, s[0:1], v20, v20, 1.0
	v_rcp_f32_e32 v55, v54
	s_nop 0
	v_fma_f32 v56, -v54, v55, 1.0
	v_fmac_f32_e32 v55, v56, v55
	v_div_scale_f32 v56, vcc, 1.0, v20, 1.0
	v_mul_f32_e32 v57, v56, v55
	v_fma_f32 v58, -v54, v57, v56
	v_fmac_f32_e32 v57, v58, v55
	v_fma_f32 v54, -v54, v57, v56
	v_div_fmas_f32 v54, v54, v55, v57
	v_min_i32_e32 v57, 15, v37
	v_add_u32_e32 v57, 1, v57
	v_cvt_f32_i32_e32 v57, v57
	v_div_fixup_f32 v20, v54, v20, 1.0
	v_cmp_lt_i32_e32 vcc, -4, v36
	v_cndmask_b32_e64 v54, v20, v213, s[20:21]
	v_div_scale_f32 v58, s[0:1], v57, v57, 1.0
	v_rcp_f32_e32 v59, v58
	v_cndmask_b32_e32 v27, 0, v27, vcc
	v_cndmask_b32_e32 v26, 0, v26, vcc
	v_cndmask_b32_e32 v25, 0, v25, vcc
	v_fma_f32 v60, -v58, v59, 1.0
	v_cndmask_b32_e32 v24, 0, v24, vcc
	v_fmac_f32_e32 v59, v60, v59
	v_div_scale_f32 v60, vcc, 1.0, v57, 1.0
	v_fma_f32 v20, v54, v30, -v21
	v_fma_f32 v21, v54, v28, -v22
	v_mul_f32_e32 v61, v60, v59
	v_cvt_pk_bf16_f32 v20, v20, v21
	v_fma_f32 v21, v54, v45, -v23
	v_fma_f32 v22, v54, v29, -v48
	v_fma_f32 v62, -v58, v61, v60
	v_cvt_pk_bf16_f32 v21, v21, v22
	v_fma_f32 v22, v54, v46, -v50
	v_fma_f32 v23, v54, v31, -v51
	v_fmac_f32_e32 v61, v62, v59
	v_cvt_pk_bf16_f32 v22, v22, v23
	v_fma_f32 v23, v54, v49, -v52
	v_fma_f32 v48, v54, v47, -v53
	v_fma_f32 v58, -v58, v61, v60
	v_cvt_pk_bf16_f32 v23, v23, v48
	v_lshlrev_b32_e32 v48, 16, v24
	v_and_b32_e32 v50, 0xffff0000, v24
	v_div_fmas_f32 v58, v58, v59, v61
	v_add_f32_e32 v30, v30, v48
	v_add_f32_e32 v28, v28, v50
	v_lshlrev_b32_e32 v51, 16, v25
	v_and_b32_e32 v52, 0xffff0000, v25
	v_div_fixup_f32 v57, v58, v57, 1.0
	v_sub_f32_e32 v30, v30, v107
	v_sub_f32_e32 v28, v28, v108
	v_add_f32_e32 v45, v45, v51
	v_add_f32_e32 v29, v29, v52
	v_lshlrev_b32_e32 v53, 16, v26
	v_and_b32_e32 v54, 0xffff0000, v26
	v_cndmask_b32_e64 v57, v57, v213, s[20:21]
	v_sub_f32_e32 v45, v45, v109
	v_sub_f32_e32 v29, v29, v110
	v_add_f32_e32 v46, v46, v53
	v_add_f32_e32 v31, v31, v54
	v_lshlrev_b32_e32 v55, 16, v27
	v_fma_f32 v30, v57, v30, -v48
	v_fma_f32 v28, v57, v28, -v50
	v_sub_f32_e32 v46, v46, v111
	v_sub_f32_e32 v31, v31, v91
	v_add_f32_e32 v49, v49, v55
	v_and_b32_e32 v56, 0xffff0000, v27
	v_cvt_pk_bf16_f32 v28, v30, v28
	v_fma_f32 v30, v57, v45, -v51
	v_fma_f32 v29, v57, v29, -v52
	v_sub_f32_e32 v49, v49, v90
	v_add_f32_e32 v47, v47, v56
	v_cvt_pk_bf16_f32 v29, v30, v29
	v_fma_f32 v30, v57, v46, -v53
	v_fma_f32 v31, v57, v31, -v54
	v_sub_f32_e32 v47, v47, v89
	v_cvt_pk_bf16_f32 v30, v30, v31
	v_fma_f32 v31, v57, v49, -v55
	v_fma_f32 v45, v57, v47, -v56
	v_cvt_pk_bf16_f32 v31, v31, v45
	s_mov_b64 s[0:1], 0

.LBB0_2396:
	v_max_i32_e32 v40, 1, v36
	v_max_i32_e32 v41, 0, v36
	v_or_b32_e32 v39, 1, v36
	v_or_b32_e32 v38, 2, v36
	v_or_b32_e32 v37, 3, v36
	s_andn2_b64 vcc, exec, s[12:13]
	v_cmp_lt_i32_e64 s[22:23], 0, v36
	v_cmp_lt_i32_e64 s[20:21], -1, v36
	v_cmp_lt_i32_e64 s[18:19], -2, v36
	v_cmp_lt_i32_e64 s[16:17], -3, v36
	v_add3_u32 v44, s11, -1, v40
	v_add_u32_e32 v43, s11, v41
	v_max_i32_e32 v42, 0, v39
	v_max_i32_e32 v41, 0, v38
	v_max_i32_e32 v40, 0, v37
	s_cbranch_vccnz .LBB0_2398
	v_max_i32_e32 v112, 14, v36
	v_add3_u32 v112, s11, -14, v112
	v_mad_i64_i32 v[112:113], s[0:1], v112, s31, v[34:35]
	global_load_dwordx4 v[112:115], v[112:113], off
	v_max_i32_e32 v116, 13, v36
	v_add3_u32 v116, s11, -13, v116
	v_mad_i64_i32 v[116:117], s[0:1], v116, s31, v[34:35]
	global_load_dwordx4 v[116:119], v[116:117], off
	v_max_i32_e32 v120, 12, v36
	v_add3_u32 v120, s11, -12, v120
	v_mad_i64_i32 v[120:121], s[0:1], v120, s31, v[34:35]
	global_load_dwordx4 v[120:123], v[120:121], off
	v_max_i32_e32 v124, 11, v36
	v_add3_u32 v124, s11, -11, v124
	v_mad_i64_i32 v[124:125], s[0:1], v124, s31, v[34:35]
	global_load_dwordx4 v[124:127], v[124:125], off
	v_max_i32_e32 v128, 10, v36
	v_add3_u32 v128, s11, -10, v128
	v_mad_i64_i32 v[128:129], s[0:1], v128, s31, v[34:35]
	global_load_dwordx4 v[128:131], v[128:129], off
	v_max_i32_e32 v132, 9, v36
	v_add3_u32 v132, s11, -9, v132
	v_mad_i64_i32 v[132:133], s[0:1], v132, s31, v[34:35]
	global_load_dwordx4 v[132:135], v[132:133], off
	v_max_i32_e32 v136, 8, v36
	v_add3_u32 v136, s11, -8, v136
	v_mad_i64_i32 v[136:137], s[0:1], v136, s31, v[34:35]
	global_load_dwordx4 v[136:139], v[136:137], off
	v_max_i32_e32 v176, 7, v36
	v_add3_u32 v176, s11, -7, v176
	v_mad_i64_i32 v[176:177], s[0:1], v176, s31, v[34:35]
	global_load_dwordx4 v[176:179], v[176:177], off
	v_max_i32_e32 v180, 6, v36
	v_add3_u32 v180, s11, -6, v180
	v_mad_i64_i32 v[180:181], s[0:1], v180, s31, v[34:35]
	global_load_dwordx4 v[180:183], v[180:181], off
	v_max_i32_e32 v184, 5, v36
	v_add3_u32 v184, s11, -5, v184
	v_mad_i64_i32 v[184:185], s[0:1], v184, s31, v[34:35]
	global_load_dwordx4 v[184:187], v[184:185], off
	v_max_i32_e32 v188, 4, v36
	v_add3_u32 v188, s11, -4, v188
	v_mad_i64_i32 v[188:189], s[0:1], v188, s31, v[34:35]
	global_load_dwordx4 v[188:191], v[188:189], off
	v_max_i32_e32 v192, 3, v36
	v_add3_u32 v192, s11, -3, v192
	v_mad_i64_i32 v[192:193], s[0:1], v192, s31, v[34:35]
	global_load_dwordx4 v[192:195], v[192:193], off
	v_max_i32_e32 v196, 2, v36
	v_add3_u32 v196, s11, -2, v196
	v_mad_i64_i32 v[196:197], s[0:1], v196, s31, v[34:35]
	global_load_dwordx4 v[196:199], v[196:197], off
	v_mad_i64_i32 v[200:201], s[0:1], v44, s31, v[34:35]
	global_load_dwordx4 v[200:203], v[200:201], off
	v_mad_i64_i32 v[218:219], s[0:1], v43, s31, v[34:35]
	global_load_dwordx4 v[218:221], v[218:219], off
	v_max_i32_e32 v0, 15, v36
	v_add3_u32 v0, s11, -15, v0
	v_mad_i64_i32 v[0:1], s[0:1], v0, s31, v[34:35]
	global_load_dwordx4 v[0:3], v[0:1], off
	v_add_u32_e32 v4, s11, v42
	v_cmp_lt_i32_e32 vcc, 14, v36
	v_mad_i64_i32 v[4:5], s[0:1], v4, s31, v[34:35]
	global_load_dwordx4 v[4:7], v[4:5], off
	v_add_u32_e32 v8, s11, v41
	v_mad_i64_i32 v[8:9], s[0:1], v8, s31, v[34:35]
	v_add_u32_e32 v24, s11, v40
	v_mad_i64_i32 v[24:25], s[0:1], v24, s31, v[34:35]
	global_load_dwordx4 v[8:11], v[8:9], off
	s_waitcnt vmcnt(2)
	v_cndmask_b32_e32 v16, 0, v0, vcc
	v_max_i32_e32 v0, 14, v36
	v_add3_u32 v0, s11, -14, v0
	v_cndmask_b32_e32 v14, 0, v1, vcc
	v_mad_i64_i32 v[0:1], s[0:1], v0, s31, v[34:35]
	v_cndmask_b32_e32 v12, 0, v3, vcc
	v_cndmask_b32_e32 v13, 0, v2, vcc
	v_mov_b32_e32 v0, v112
	v_mov_b32_e32 v1, v113
	v_mov_b32_e32 v2, v114
	v_mov_b32_e32 v3, v115
	v_cmp_lt_i32_e32 vcc, 13, v36
	v_and_b32_e32 v94, 0xffff0000, v14
	v_lshlrev_b32_e32 v92, 16, v16
	v_and_b32_e32 v16, 0xffff0000, v16
	v_lshlrev_b32_e32 v93, 16, v14
	v_add_f32_e32 v14, 0, v94
	v_lshlrev_b32_e32 v95, 16, v13
	v_add_f32_e32 v90, 0, v16
	v_add_f32_e32 v91, 0, v93
	v_add_f32_e32 v96, 0, v95
	v_and_b32_e32 v97, 0xffff0000, v13
	v_add_f32_e32 v13, 0, v97
	v_lshlrev_b32_e32 v98, 16, v12
	v_add_f32_e32 v89, 0, v92
	v_add_f32_e32 v99, 0, v98
	v_and_b32_e32 v100, 0xffff0000, v12
	v_add_f32_e32 v12, 0, v100
	s_waitcnt vmcnt(1)
	v_cndmask_b32_e64 v4, 0, v4, s[18:19]
	v_cndmask_b32_e64 v5, 0, v5, s[18:19]
	v_cndmask_b32_e64 v6, 0, v6, s[18:19]
	v_cndmask_b32_e64 v7, 0, v7, s[18:19]
	s_waitcnt vmcnt(0)
	v_cndmask_b32_e64 v8, 0, v8, s[16:17]
	v_cndmask_b32_e64 v9, 0, v9, s[16:17]
	v_cndmask_b32_e64 v10, 0, v10, s[16:17]
	v_cndmask_b32_e64 v11, 0, v11, s[16:17]
	global_load_dwordx4 v[24:27], v[24:25], off
	s_waitcnt vmcnt(1)
	v_cndmask_b32_e32 v19, 0, v0, vcc
	v_max_i32_e32 v0, 13, v36
	v_add3_u32 v0, s11, -13, v0
	v_cndmask_b32_e32 v18, 0, v1, vcc
	v_mad_i64_i32 v[0:1], s[0:1], v0, s31, v[34:35]
	v_cndmask_b32_e32 v15, 0, v3, vcc
	v_cndmask_b32_e32 v17, 0, v2, vcc
	v_mov_b32_e32 v0, v116
	v_mov_b32_e32 v1, v117
	v_mov_b32_e32 v2, v118
	v_mov_b32_e32 v3, v119
	v_cmp_lt_i32_e32 vcc, 12, v36
	v_and_b32_e32 v104, 0xffff0000, v18
	v_and_b32_e32 v102, 0xffff0000, v19
	v_lshlrev_b32_e32 v103, 16, v18
	v_add_f32_e32 v14, v14, v104
	v_lshlrev_b32_e32 v105, 16, v17
	v_lshlrev_b32_e32 v101, 16, v19
	v_add_f32_e32 v19, v90, v102
	v_add_f32_e32 v90, v91, v103
	v_add_f32_e32 v18, v96, v105
	v_and_b32_e32 v96, 0xffff0000, v17
	v_add_f32_e32 v13, v13, v96
	v_lshlrev_b32_e32 v106, 16, v15
	v_add_f32_e32 v89, v89, v101
	v_add_f32_e32 v17, v99, v106
	v_and_b32_e32 v99, 0xffff0000, v15
	v_add_f32_e32 v12, v12, v99
	s_waitcnt vmcnt(0)
	v_cndmask_b32_e32 v23, 0, v0, vcc
	v_max_i32_e32 v0, 12, v36
	v_add3_u32 v0, s11, -12, v0
	v_cndmask_b32_e32 v22, 0, v1, vcc
	v_mad_i64_i32 v[0:1], s[0:1], v0, s31, v[34:35]
	v_cndmask_b32_e32 v20, 0, v3, vcc
	v_cndmask_b32_e32 v21, 0, v2, vcc
	v_mov_b32_e32 v0, v120
	v_mov_b32_e32 v1, v121
	v_mov_b32_e32 v2, v122
	v_mov_b32_e32 v3, v123
	v_cmp_lt_i32_e32 vcc, 11, v36
	v_and_b32_e32 v110, 0xffff0000, v22
	v_add_f32_e32 v14, v14, v110
	v_lshlrev_b32_e32 v111, 16, v21
	v_and_b32_e32 v91, 0xffff0000, v21
	v_lshlrev_b32_e32 v109, 16, v22
	v_add_f32_e32 v18, v18, v111
	v_lshlrev_b32_e32 v107, 16, v23
	v_and_b32_e32 v108, 0xffff0000, v23
	v_add_f32_e32 v23, v90, v109
	v_add_f32_e32 v13, v13, v91
	v_lshlrev_b32_e32 v90, 16, v20
	v_add_f32_e32 v15, v89, v107
	v_add_f32_e32 v17, v17, v90
	v_and_b32_e32 v89, 0xffff0000, v20
	v_add_f32_e32 v12, v12, v89
	v_add_f32_e32 v19, v19, v108
	s_waitcnt vmcnt(0)
	v_cndmask_b32_e32 v31, 0, v0, vcc
	v_max_i32_e32 v0, 11, v36
	v_add3_u32 v0, s11, -11, v0
	v_cndmask_b32_e32 v30, 0, v1, vcc
	v_mad_i64_i32 v[0:1], s[0:1], v0, s31, v[34:35]
	v_cndmask_b32_e32 v28, 0, v3, vcc
	v_cndmask_b32_e32 v29, 0, v2, vcc
	v_mov_b32_e32 v0, v124
	v_mov_b32_e32 v1, v125
	v_mov_b32_e32 v2, v126
	v_mov_b32_e32 v3, v127
	v_cmp_lt_i32_e32 vcc, 10, v36
	v_and_b32_e32 v21, 0xffff0000, v30
	v_add_f32_e32 v14, v14, v21
	v_lshlrev_b32_e32 v21, 16, v29
	v_add_f32_e32 v18, v18, v21
	v_and_b32_e32 v21, 0xffff0000, v29
	v_add_f32_e32 v13, v13, v21
	v_lshlrev_b32_e32 v21, 16, v28
	v_lshlrev_b32_e32 v20, 16, v31
	v_add_f32_e32 v17, v17, v21
	v_and_b32_e32 v21, 0xffff0000, v28
	v_add_f32_e32 v15, v15, v20
	v_and_b32_e32 v20, 0xffff0000, v31
	v_add_f32_e32 v12, v12, v21
	v_add_f32_e32 v19, v19, v20
	v_lshlrev_b32_e32 v20, 16, v30
	v_add_f32_e32 v20, v23, v20
	s_waitcnt vmcnt(0)
	v_cndmask_b32_e32 v48, 0, v0, vcc
	v_max_i32_e32 v0, 10, v36
	v_add3_u32 v0, s11, -10, v0
	v_cndmask_b32_e32 v47, 0, v1, vcc
	v_mad_i64_i32 v[0:1], s[0:1], v0, s31, v[34:35]
	v_cndmask_b32_e32 v45, 0, v3, vcc
	v_cndmask_b32_e32 v46, 0, v2, vcc
	v_mov_b32_e32 v0, v128
	v_mov_b32_e32 v1, v129
	v_mov_b32_e32 v2, v130
	v_mov_b32_e32 v3, v131
	v_cmp_lt_i32_e32 vcc, 9, v36
	v_lshlrev_b32_e32 v21, 16, v48
	v_add_f32_e32 v15, v15, v21
	v_and_b32_e32 v21, 0xffff0000, v48
	v_add_f32_e32 v19, v19, v21
	v_lshlrev_b32_e32 v21, 16, v47
	v_add_f32_e32 v20, v20, v21
	v_and_b32_e32 v21, 0xffff0000, v47
	v_add_f32_e32 v14, v14, v21
	v_lshlrev_b32_e32 v21, 16, v46
	v_add_f32_e32 v18, v18, v21
	v_and_b32_e32 v21, 0xffff0000, v46
	v_add_f32_e32 v13, v13, v21
	v_lshlrev_b32_e32 v21, 16, v45
	v_add_f32_e32 v17, v17, v21
	v_and_b32_e32 v21, 0xffff0000, v45
	v_add_f32_e32 v12, v12, v21
	s_waitcnt vmcnt(0)
	v_cndmask_b32_e32 v52, 0, v0, vcc
	v_max_i32_e32 v0, 9, v36
	v_add3_u32 v0, s11, -9, v0
	v_cndmask_b32_e32 v51, 0, v1, vcc
	v_mad_i64_i32 v[0:1], s[0:1], v0, s31, v[34:35]
	v_cndmask_b32_e32 v49, 0, v3, vcc
	v_cndmask_b32_e32 v50, 0, v2, vcc
	v_mov_b32_e32 v0, v132
	v_mov_b32_e32 v1, v133
	v_mov_b32_e32 v2, v134
	v_mov_b32_e32 v3, v135
	v_cmp_lt_i32_e32 vcc, 8, v36
	v_lshlrev_b32_e32 v21, 16, v52
	v_add_f32_e32 v15, v15, v21
	v_and_b32_e32 v21, 0xffff0000, v52
	v_add_f32_e32 v19, v19, v21
	v_lshlrev_b32_e32 v21, 16, v51
	v_add_f32_e32 v20, v20, v21
	v_and_b32_e32 v21, 0xffff0000, v51
	v_add_f32_e32 v14, v14, v21
	v_lshlrev_b32_e32 v21, 16, v50
	v_add_f32_e32 v18, v18, v21
	v_and_b32_e32 v21, 0xffff0000, v50
	v_add_f32_e32 v13, v13, v21
	v_lshlrev_b32_e32 v21, 16, v49
	v_add_f32_e32 v17, v17, v21
	v_and_b32_e32 v21, 0xffff0000, v49
	v_add_f32_e32 v12, v12, v21
	s_waitcnt vmcnt(0)
	v_cndmask_b32_e32 v56, 0, v0, vcc
	v_max_i32_e32 v0, 8, v36
	v_add3_u32 v0, s11, -8, v0
	v_cndmask_b32_e32 v55, 0, v1, vcc
	v_mad_i64_i32 v[0:1], s[0:1], v0, s31, v[34:35]
	v_cndmask_b32_e32 v53, 0, v3, vcc
	v_cndmask_b32_e32 v54, 0, v2, vcc
	v_mov_b32_e32 v0, v136
	v_mov_b32_e32 v1, v137
	v_mov_b32_e32 v2, v138
	v_mov_b32_e32 v3, v139
	v_cmp_lt_i32_e32 vcc, 7, v36
	v_lshlrev_b32_e32 v21, 16, v56
	v_add_f32_e32 v15, v15, v21
	v_and_b32_e32 v21, 0xffff0000, v56
	v_add_f32_e32 v19, v19, v21
	v_lshlrev_b32_e32 v21, 16, v55
	v_add_f32_e32 v20, v20, v21
	v_and_b32_e32 v21, 0xffff0000, v55
	v_add_f32_e32 v14, v14, v21
	v_lshlrev_b32_e32 v21, 16, v54
	v_add_f32_e32 v18, v18, v21
	v_and_b32_e32 v21, 0xffff0000, v54
	v_add_f32_e32 v13, v13, v21
	v_lshlrev_b32_e32 v21, 16, v53
	v_add_f32_e32 v17, v17, v21
	v_and_b32_e32 v21, 0xffff0000, v53
	v_add_f32_e32 v12, v12, v21
	s_waitcnt vmcnt(0)
	v_cndmask_b32_e32 v60, 0, v0, vcc
	v_max_i32_e32 v0, 7, v36
	v_add3_u32 v0, s11, -7, v0
	v_cndmask_b32_e32 v59, 0, v1, vcc
	v_mad_i64_i32 v[0:1], s[0:1], v0, s31, v[34:35]
	v_cndmask_b32_e32 v57, 0, v3, vcc
	v_cndmask_b32_e32 v58, 0, v2, vcc
	v_mov_b32_e32 v0, v176
	v_mov_b32_e32 v1, v177
	v_mov_b32_e32 v2, v178
	v_mov_b32_e32 v3, v179
	v_cmp_lt_i32_e32 vcc, 6, v36
	v_lshlrev_b32_e32 v21, 16, v60
	v_add_f32_e32 v15, v15, v21
	v_and_b32_e32 v21, 0xffff0000, v60
	v_add_f32_e32 v19, v19, v21
	v_lshlrev_b32_e32 v21, 16, v59
	v_add_f32_e32 v20, v20, v21
	v_and_b32_e32 v21, 0xffff0000, v59
	v_add_f32_e32 v14, v14, v21
	v_lshlrev_b32_e32 v21, 16, v58
	v_add_f32_e32 v18, v18, v21
	v_and_b32_e32 v21, 0xffff0000, v58
	v_add_f32_e32 v13, v13, v21
	v_lshlrev_b32_e32 v21, 16, v57
	v_add_f32_e32 v17, v17, v21
	v_and_b32_e32 v21, 0xffff0000, v57
	v_add_f32_e32 v12, v12, v21
	s_waitcnt vmcnt(0)
	v_cndmask_b32_e32 v64, 0, v0, vcc
	v_max_i32_e32 v0, 6, v36
	v_add3_u32 v0, s11, -6, v0
	v_cndmask_b32_e32 v63, 0, v1, vcc
	v_mad_i64_i32 v[0:1], s[0:1], v0, s31, v[34:35]
	v_cndmask_b32_e32 v61, 0, v3, vcc
	v_cndmask_b32_e32 v62, 0, v2, vcc
	v_mov_b32_e32 v0, v180
	v_mov_b32_e32 v1, v181
	v_mov_b32_e32 v2, v182
	v_mov_b32_e32 v3, v183
	v_cmp_lt_i32_e32 vcc, 5, v36
	v_lshlrev_b32_e32 v21, 16, v64
	v_add_f32_e32 v15, v15, v21
	v_and_b32_e32 v21, 0xffff0000, v64
	v_add_f32_e32 v19, v19, v21
	v_lshlrev_b32_e32 v21, 16, v63
	v_add_f32_e32 v20, v20, v21
	v_and_b32_e32 v21, 0xffff0000, v63
	v_add_f32_e32 v14, v14, v21
	v_lshlrev_b32_e32 v21, 16, v62
	v_add_f32_e32 v18, v18, v21
	v_and_b32_e32 v21, 0xffff0000, v62
	v_add_f32_e32 v13, v13, v21
	v_lshlrev_b32_e32 v21, 16, v61
	v_add_f32_e32 v17, v17, v21
	v_and_b32_e32 v21, 0xffff0000, v61
	v_add_f32_e32 v12, v12, v21
	s_waitcnt vmcnt(0)
	v_cndmask_b32_e32 v68, 0, v0, vcc
	v_max_i32_e32 v0, 5, v36
	v_add3_u32 v0, s11, -5, v0
	v_cndmask_b32_e32 v67, 0, v1, vcc
	v_mad_i64_i32 v[0:1], s[0:1], v0, s31, v[34:35]
	v_cndmask_b32_e32 v65, 0, v3, vcc
	v_cndmask_b32_e32 v66, 0, v2, vcc
	v_mov_b32_e32 v0, v184
	v_mov_b32_e32 v1, v185
	v_mov_b32_e32 v2, v186
	v_mov_b32_e32 v3, v187
	v_cmp_lt_i32_e32 vcc, 4, v36
	v_lshlrev_b32_e32 v21, 16, v68
	v_add_f32_e32 v15, v15, v21
	v_and_b32_e32 v21, 0xffff0000, v68
	v_add_f32_e32 v19, v19, v21
	v_lshlrev_b32_e32 v21, 16, v67
	v_add_f32_e32 v20, v20, v21
	v_and_b32_e32 v21, 0xffff0000, v67
	v_add_f32_e32 v14, v14, v21
	v_lshlrev_b32_e32 v21, 16, v66
	v_add_f32_e32 v18, v18, v21
	v_and_b32_e32 v21, 0xffff0000, v66
	v_add_f32_e32 v13, v13, v21
	v_lshlrev_b32_e32 v21, 16, v65
	v_add_f32_e32 v17, v17, v21
	v_and_b32_e32 v21, 0xffff0000, v65
	v_add_f32_e32 v12, v12, v21
	s_waitcnt vmcnt(0)
	v_cndmask_b32_e32 v72, 0, v0, vcc
	v_max_i32_e32 v0, 4, v36
	v_add3_u32 v0, s11, -4, v0
	v_cndmask_b32_e32 v71, 0, v1, vcc
	v_mad_i64_i32 v[0:1], s[0:1], v0, s31, v[34:35]
	v_cndmask_b32_e32 v69, 0, v3, vcc
	v_cndmask_b32_e32 v70, 0, v2, vcc
	v_mov_b32_e32 v0, v188
	v_mov_b32_e32 v1, v189
	v_mov_b32_e32 v2, v190
	v_mov_b32_e32 v3, v191
	v_cmp_lt_i32_e32 vcc, 3, v36
	v_lshlrev_b32_e32 v21, 16, v72
	v_add_f32_e32 v15, v15, v21
	v_and_b32_e32 v21, 0xffff0000, v72
	v_add_f32_e32 v19, v19, v21
	v_lshlrev_b32_e32 v21, 16, v71
	v_add_f32_e32 v20, v20, v21
	v_and_b32_e32 v21, 0xffff0000, v71
	v_add_f32_e32 v14, v14, v21
	v_lshlrev_b32_e32 v21, 16, v70
	v_add_f32_e32 v18, v18, v21
	v_and_b32_e32 v21, 0xffff0000, v70
	v_add_f32_e32 v13, v13, v21
	v_lshlrev_b32_e32 v21, 16, v69
	v_add_f32_e32 v17, v17, v21
	v_and_b32_e32 v21, 0xffff0000, v69
	v_add_f32_e32 v12, v12, v21
	s_waitcnt vmcnt(0)
	v_cndmask_b32_e32 v76, 0, v0, vcc
	v_max_i32_e32 v0, 3, v36
	v_add3_u32 v0, s11, -3, v0
	v_cndmask_b32_e32 v75, 0, v1, vcc
	v_mad_i64_i32 v[0:1], s[0:1], v0, s31, v[34:35]
	v_cndmask_b32_e32 v73, 0, v3, vcc
	v_cndmask_b32_e32 v74, 0, v2, vcc
	v_mov_b32_e32 v0, v192
	v_mov_b32_e32 v1, v193
	v_mov_b32_e32 v2, v194
	v_mov_b32_e32 v3, v195
	v_cmp_lt_i32_e32 vcc, 2, v36
	v_lshlrev_b32_e32 v21, 16, v76
	v_add_f32_e32 v15, v15, v21
	v_and_b32_e32 v21, 0xffff0000, v76
	v_add_f32_e32 v19, v19, v21
	v_lshlrev_b32_e32 v21, 16, v75
	v_add_f32_e32 v20, v20, v21
	v_and_b32_e32 v21, 0xffff0000, v75
	v_add_f32_e32 v14, v14, v21
	v_lshlrev_b32_e32 v21, 16, v74
	v_add_f32_e32 v18, v18, v21
	v_and_b32_e32 v21, 0xffff0000, v74
	v_add_f32_e32 v13, v13, v21
	v_lshlrev_b32_e32 v21, 16, v73
	v_add_f32_e32 v17, v17, v21
	v_and_b32_e32 v21, 0xffff0000, v73
	v_add_f32_e32 v12, v12, v21
	s_waitcnt vmcnt(0)
	v_cndmask_b32_e32 v80, 0, v0, vcc
	v_max_i32_e32 v0, 2, v36
	v_add3_u32 v0, s11, -2, v0
	v_cndmask_b32_e32 v79, 0, v1, vcc
	v_mad_i64_i32 v[0:1], s[0:1], v0, s31, v[34:35]
	v_cndmask_b32_e32 v77, 0, v3, vcc
	v_cndmask_b32_e32 v78, 0, v2, vcc
	v_mov_b32_e32 v0, v196
	v_mov_b32_e32 v1, v197
	v_mov_b32_e32 v2, v198
	v_mov_b32_e32 v3, v199
	v_cmp_lt_i32_e32 vcc, 1, v36
	v_lshlrev_b32_e32 v21, 16, v80
	v_add_f32_e32 v15, v15, v21
	v_and_b32_e32 v21, 0xffff0000, v80
	v_add_f32_e32 v19, v19, v21
	v_lshlrev_b32_e32 v21, 16, v79
	v_add_f32_e32 v20, v20, v21
	v_and_b32_e32 v21, 0xffff0000, v79
	v_add_f32_e32 v14, v14, v21
	v_lshlrev_b32_e32 v21, 16, v78
	v_add_f32_e32 v18, v18, v21
	v_and_b32_e32 v21, 0xffff0000, v78
	v_add_f32_e32 v13, v13, v21
	v_lshlrev_b32_e32 v21, 16, v77
	v_add_f32_e32 v17, v17, v21
	v_and_b32_e32 v21, 0xffff0000, v77
	v_add_f32_e32 v12, v12, v21
	s_waitcnt vmcnt(0)
	v_cndmask_b32_e32 v83, 0, v1, vcc
	v_cndmask_b32_e32 v85, 0, v0, vcc
	v_mad_i64_i32 v[0:1], s[0:1], v44, s31, v[34:35]
	v_cndmask_b32_e32 v81, 0, v3, vcc
	v_cndmask_b32_e32 v82, 0, v2, vcc
	v_mov_b32_e32 v0, v200
	v_mov_b32_e32 v1, v201
	v_mov_b32_e32 v2, v202
	v_mov_b32_e32 v3, v203
	v_lshlrev_b32_e32 v21, 16, v85
	v_add_f32_e32 v15, v15, v21
	v_and_b32_e32 v21, 0xffff0000, v85
	v_add_f32_e32 v19, v19, v21
	v_lshlrev_b32_e32 v21, 16, v83
	v_add_f32_e32 v20, v20, v21
	v_and_b32_e32 v21, 0xffff0000, v83
	v_add_f32_e32 v14, v14, v21
	v_lshlrev_b32_e32 v21, 16, v82
	v_add_f32_e32 v18, v18, v21
	v_and_b32_e32 v21, 0xffff0000, v82
	v_add_f32_e32 v13, v13, v21
	v_lshlrev_b32_e32 v21, 16, v81
	v_add_f32_e32 v17, v17, v21
	v_and_b32_e32 v21, 0xffff0000, v81
	v_add_f32_e32 v12, v12, v21
	s_waitcnt vmcnt(0)
	v_cndmask_b32_e64 v87, 0, v1, s[22:23]
	v_cndmask_b32_e64 v88, 0, v0, s[22:23]
	v_mad_i64_i32 v[0:1], s[0:1], v43, s31, v[34:35]
	v_cndmask_b32_e64 v84, 0, v3, s[22:23]
	v_cndmask_b32_e64 v86, 0, v2, s[22:23]
	v_mov_b32_e32 v0, v218
	v_mov_b32_e32 v1, v219
	v_mov_b32_e32 v2, v220
	v_mov_b32_e32 v3, v221
	v_lshlrev_b32_e32 v21, 16, v88
	v_add_f32_e32 v15, v15, v21
	v_and_b32_e32 v21, 0xffff0000, v88
	v_add_f32_e32 v19, v19, v21
	v_lshlrev_b32_e32 v21, 16, v87
	v_add_f32_e32 v20, v20, v21
	v_and_b32_e32 v21, 0xffff0000, v87
	v_add_f32_e32 v14, v14, v21
	v_lshlrev_b32_e32 v21, 16, v86
	v_add_f32_e32 v18, v18, v21
	v_and_b32_e32 v21, 0xffff0000, v86
	v_add_f32_e32 v13, v13, v21
	v_lshlrev_b32_e32 v21, 16, v84
	v_add_f32_e32 v17, v17, v21
	v_and_b32_e32 v21, 0xffff0000, v84
	v_add_f32_e32 v12, v12, v21
	s_waitcnt vmcnt(0)
	v_cndmask_b32_e64 v3, 0, v3, s[20:21]
	v_and_b32_e32 v46, 0xffff0000, v3
	v_add_f32_e32 v47, v12, v46
	v_min_i32_e32 v12, 15, v36
	v_add_u32_e32 v12, 1, v12
	v_cvt_f32_i32_e32 v12, v12
	v_cndmask_b32_e64 v2, 0, v2, s[20:21]
	v_and_b32_e32 v30, 0xffff0000, v2
	v_add_f32_e32 v31, v13, v30
	v_div_scale_f32 v13, s[0:1], v12, v12, 1.0
	v_rcp_f32_e32 v48, v13
	v_cndmask_b32_e64 v0, 0, v0, s[20:21]
	v_lshlrev_b32_e32 v21, 16, v0
	v_cndmask_b32_e64 v1, 0, v1, s[20:21]
	v_fma_f32 v49, -v13, v48, 1.0
	v_fmac_f32_e32 v48, v49, v48
	v_div_scale_f32 v49, vcc, 1.0, v12, 1.0
	v_mul_f32_e32 v50, v49, v48
	v_fma_f32 v51, -v13, v50, v49
	v_fmac_f32_e32 v50, v51, v48
	v_fma_f32 v13, -v13, v50, v49
	v_div_fmas_f32 v13, v13, v48, v50
	v_add_f32_e32 v22, v15, v21
	v_and_b32_e32 v15, 0xffff0000, v0
	v_div_fixup_f32 v12, v13, v12, 1.0
	v_add_f32_e32 v19, v19, v15
	v_lshlrev_b32_e32 v23, 16, v1
	v_cndmask_b32_e64 v48, v12, v213, s[8:9]
	v_add_f32_e32 v20, v20, v23
	v_fma_f32 v12, v48, v22, -v21
	v_fma_f32 v13, v48, v19, -v15
	v_and_b32_e32 v28, 0xffff0000, v1
	v_cvt_pk_bf16_f32 v12, v12, v13
	v_fma_f32 v13, v48, v20, -v23
	v_and_b32_e32 v23, 0xffff0000, v4
	v_add_f32_e32 v29, v14, v28
	v_lshlrev_b32_e32 v14, 16, v2
	v_add_f32_e32 v19, v19, v23
	v_add_f32_e32 v18, v18, v14
	v_lshlrev_b32_e32 v45, 16, v3
	v_fma_f32 v15, v48, v29, -v28
	v_sub_f32_e32 v28, v19, v16
	v_lshlrev_b32_e32 v19, 16, v5
	v_add_f32_e32 v17, v17, v45
	v_cvt_pk_bf16_f32 v13, v13, v15
	v_fma_f32 v14, v48, v18, -v14
	v_fma_f32 v15, v48, v31, -v30
	v_add_f32_e32 v16, v20, v19
	v_and_b32_e32 v30, 0xffff0000, v5
	v_cvt_pk_bf16_f32 v14, v14, v15
	v_fma_f32 v15, v48, v17, -v45
	v_sub_f32_e32 v20, v16, v93
	v_add_f32_e32 v16, v29, v30
	v_lshlrev_b32_e32 v45, 16, v6
	v_sub_f32_e32 v29, v16, v94
	v_add_f32_e32 v16, v18, v45
	v_and_b32_e32 v18, 0xffff0000, v6
	v_fma_f32 v21, v48, v47, -v46
	v_sub_f32_e32 v46, v16, v95
	v_add_f32_e32 v16, v31, v18
	v_lshlrev_b32_e32 v48, 16, v7
	v_sub_f32_e32 v31, v16, v97
	v_add_f32_e32 v16, v17, v48
	v_and_b32_e32 v50, 0xffff0000, v7
	v_sub_f32_e32 v49, v16, v98
	v_add_f32_e32 v16, v47, v50
	v_sub_f32_e32 v47, v16, v100
	v_min_i32_e32 v16, 15, v39
	v_add_u32_e32 v16, 1, v16
	v_cvt_f32_i32_e32 v16, v16
	v_cvt_pk_bf16_f32 v15, v15, v21
	v_lshlrev_b32_e32 v21, 16, v4
	v_add_f32_e32 v22, v22, v21
	v_div_scale_f32 v17, s[0:1], v16, v16, 1.0
	v_rcp_f32_e32 v51, v17
	v_sub_f32_e32 v22, v22, v92
	v_fma_f32 v52, -v17, v51, 1.0
	v_fmac_f32_e32 v51, v52, v51
	v_div_scale_f32 v52, vcc, 1.0, v16, 1.0
	v_mul_f32_e32 v53, v52, v51
	v_fma_f32 v54, -v17, v53, v52
	v_fmac_f32_e32 v53, v54, v51
	v_fma_f32 v17, -v17, v53, v52
	v_div_fmas_f32 v17, v17, v51, v53
	v_div_fixup_f32 v16, v17, v16, 1.0
	v_cndmask_b32_e64 v51, v16, v213, s[8:9]
	v_fma_f32 v16, v51, v22, -v21
	v_fma_f32 v17, v51, v28, -v23
	v_cvt_pk_bf16_f32 v16, v16, v17
	v_fma_f32 v17, v51, v20, -v19
	v_fma_f32 v19, v51, v29, -v30
	v_cvt_pk_bf16_f32 v17, v17, v19
	v_fma_f32 v19, v51, v46, -v45
	v_fma_f32 v18, v51, v31, -v18
	v_cvt_pk_bf16_f32 v18, v19, v18
	v_fma_f32 v19, v51, v49, -v48
	v_fma_f32 v21, v51, v47, -v50
	v_cvt_pk_bf16_f32 v19, v19, v21
	v_lshlrev_b32_e32 v21, 16, v8
	v_add_f32_e32 v22, v22, v21
	v_sub_f32_e32 v30, v22, v101
	v_and_b32_e32 v22, 0xffff0000, v8
	v_add_f32_e32 v23, v28, v22
	v_sub_f32_e32 v28, v23, v102
	v_lshlrev_b32_e32 v23, 16, v9
	v_add_f32_e32 v20, v20, v23
	v_and_b32_e32 v48, 0xffff0000, v9
	v_sub_f32_e32 v45, v20, v103
	v_add_f32_e32 v20, v29, v48
	v_lshlrev_b32_e32 v50, 16, v10
	v_sub_f32_e32 v29, v20, v104
	v_add_f32_e32 v20, v46, v50
	v_and_b32_e32 v51, 0xffff0000, v10
	v_sub_f32_e32 v46, v20, v105
	v_add_f32_e32 v20, v31, v51
	v_lshlrev_b32_e32 v52, 16, v11
	v_sub_f32_e32 v31, v20, v96
	v_add_f32_e32 v20, v49, v52
	v_and_b32_e32 v53, 0xffff0000, v11
	v_sub_f32_e32 v49, v20, v106
	v_add_f32_e32 v20, v47, v53
	v_sub_f32_e32 v47, v20, v99
	v_min_i32_e32 v20, 15, v38
	v_add_u32_e32 v20, 1, v20
	v_cvt_f32_i32_e32 v20, v20
	v_div_scale_f32 v54, s[0:1], v20, v20, 1.0
	v_rcp_f32_e32 v55, v54
	s_nop 0
	v_fma_f32 v56, -v54, v55, 1.0
	v_fmac_f32_e32 v55, v56, v55
	v_div_scale_f32 v56, vcc, 1.0, v20, 1.0
	v_mul_f32_e32 v57, v56, v55
	v_fma_f32 v58, -v54, v57, v56
	v_fmac_f32_e32 v57, v58, v55
	v_fma_f32 v54, -v54, v57, v56
	v_div_fmas_f32 v54, v54, v55, v57
	v_min_i32_e32 v57, 15, v37
	v_add_u32_e32 v57, 1, v57
	v_cvt_f32_i32_e32 v57, v57
	v_div_fixup_f32 v20, v54, v20, 1.0
	v_cmp_lt_i32_e32 vcc, -4, v36
	v_cndmask_b32_e64 v54, v20, v213, s[8:9]
	v_div_scale_f32 v58, s[0:1], v57, v57, 1.0
	v_rcp_f32_e32 v59, v58
	v_cndmask_b32_e32 v27, 0, v27, vcc
	v_cndmask_b32_e32 v26, 0, v26, vcc
	v_cndmask_b32_e32 v25, 0, v25, vcc
	v_fma_f32 v60, -v58, v59, 1.0
	v_cndmask_b32_e32 v24, 0, v24, vcc
	v_fmac_f32_e32 v59, v60, v59
	v_div_scale_f32 v60, vcc, 1.0, v57, 1.0
	v_fma_f32 v20, v54, v30, -v21
	v_fma_f32 v21, v54, v28, -v22
	v_mul_f32_e32 v61, v60, v59
	v_cvt_pk_bf16_f32 v20, v20, v21
	v_fma_f32 v21, v54, v45, -v23
	v_fma_f32 v22, v54, v29, -v48
	v_fma_f32 v62, -v58, v61, v60
	v_cvt_pk_bf16_f32 v21, v21, v22
	v_fma_f32 v22, v54, v46, -v50
	v_fma_f32 v23, v54, v31, -v51
	v_fmac_f32_e32 v61, v62, v59
	v_cvt_pk_bf16_f32 v22, v22, v23
	v_fma_f32 v23, v54, v49, -v52
	v_fma_f32 v48, v54, v47, -v53
	v_fma_f32 v58, -v58, v61, v60
	v_cvt_pk_bf16_f32 v23, v23, v48
	v_lshlrev_b32_e32 v48, 16, v24
	v_and_b32_e32 v50, 0xffff0000, v24
	v_div_fmas_f32 v58, v58, v59, v61
	v_add_f32_e32 v30, v30, v48
	v_add_f32_e32 v28, v28, v50
	v_lshlrev_b32_e32 v51, 16, v25
	v_and_b32_e32 v52, 0xffff0000, v25
	v_div_fixup_f32 v57, v58, v57, 1.0
	v_sub_f32_e32 v30, v30, v107
	v_sub_f32_e32 v28, v28, v108
	v_add_f32_e32 v45, v45, v51
	v_add_f32_e32 v29, v29, v52
	v_lshlrev_b32_e32 v53, 16, v26
	v_and_b32_e32 v54, 0xffff0000, v26
	v_cndmask_b32_e64 v57, v57, v213, s[8:9]
	v_sub_f32_e32 v45, v45, v109
	v_sub_f32_e32 v29, v29, v110
	v_add_f32_e32 v46, v46, v53
	v_add_f32_e32 v31, v31, v54
	v_lshlrev_b32_e32 v55, 16, v27
	v_fma_f32 v30, v57, v30, -v48
	v_fma_f32 v28, v57, v28, -v50
	v_sub_f32_e32 v46, v46, v111
	v_sub_f32_e32 v31, v31, v91
	v_add_f32_e32 v49, v49, v55
	v_and_b32_e32 v56, 0xffff0000, v27
	v_cvt_pk_bf16_f32 v28, v30, v28
	v_fma_f32 v30, v57, v45, -v51
	v_fma_f32 v29, v57, v29, -v52
	v_sub_f32_e32 v49, v49, v90
	v_add_f32_e32 v47, v47, v56
	v_cvt_pk_bf16_f32 v29, v30, v29
	v_fma_f32 v30, v57, v46, -v53
	v_fma_f32 v31, v57, v31, -v54
	v_sub_f32_e32 v47, v47, v89
	v_cvt_pk_bf16_f32 v30, v30, v31
	v_fma_f32 v31, v57, v49, -v55
	v_fma_f32 v45, v57, v47, -v56
	v_cvt_pk_bf16_f32 v31, v31, v45
	s_mov_b64 s[0:1], 0
